# GEMM loops: duplicate lgkmcnt(0) removed; LDS-DMA addresses via SGPR base + 32-bit VGPR offset (all v_lshl_add_u64 address math replaced by scalar adds)
# speedup vs baseline: 1.0117x; 1.0097x over previous
.LBB0_242:
	s_ashr_i32 s11, s10, 31
	s_xor_b64 s[14:15], s[28:29], -1
	s_lshl_b64 s[12:13], s[10:11], 20
	s_add_u32 s12, s34, s12
	s_addc_u32 s13, s35, s13
	s_and_b64 s[16:17], s[28:29], exec
	s_cselect_b32 s11, s13, s19
	s_cselect_b32 s67, s12, s18
	s_ashr_i32 s9, s8, 31
	s_lshl_b64 s[16:17], s[8:9], 20
	s_add_u32 s16, s22, s16
	s_addc_u32 s17, s23, s17
	s_and_b64 s[28:29], s[28:29], exec
	s_cselect_b32 s9, s17, s37
	s_cselect_b32 s28, s16, s36
	s_add_u32 s18, s18, 0x80080
	s_addc_u32 s19, s19, 0
	s_add_u32 s29, s36, 0x100
	s_addc_u32 s72, s37, 0
	s_mov_b32 s73, -2
	ds_read_b128 v[150:153], v146
	ds_read_b128 v[154:157], v146 offset:1024
	ds_read_b128 v[158:161], v146 offset:2048
	ds_read_b128 v[162:165], v146 offset:3072
	s_add_u32 s36, s18, 0xfff80080
	s_addc_u32 s37, s19, -1
	s_cmp_eq_u32 s73, 28
	s_cselect_b32 s55, s11, s37
	s_cselect_b32 s54, s67, s36
	s_cselect_b32 s37, s9, s72
	s_cselect_b32 s36, s28, s29
	s_add_i32 m0, s56, 0xc000
	ds_read_b128 v[166:169], v147
	ds_read_b128 v[170:173], v147 offset:1024
	ds_read_b128 v[174:177], v147 offset:2048
	ds_read_b128 v[178:181], v147 offset:3072
	ds_read_b128 v[182:185], v147 offset:4096
	ds_read_b128 v[186:189], v147 offset:5120
	ds_read_b128 v[190:193], v147 offset:6144
	ds_read_b128 v[194:197], v147 offset:7168
	global_load_lds_dwordx4 v138, s[18:19]
	s_add_i32 m0, s56, 0xe000
	s_nop 0
	global_load_lds_dwordx4 v140, s[18:19]
	s_waitcnt lgkmcnt(8)
	s_barrier
	s_waitcnt lgkmcnt(0)
	v_mfma_f32_16x16x32_bf16 v[124:127], v[150:153], v[166:169], 0
	v_mfma_f32_16x16x32_bf16 v[120:123], v[158:161], v[166:169], 0
	v_mfma_f32_16x16x32_bf16 v[116:119], v[150:153], v[174:177], 0
	v_mfma_f32_16x16x32_bf16 v[108:111], v[158:161], v[174:177], 0
	v_mfma_f32_16x16x32_bf16 v[100:103], v[150:153], v[182:185], 0
	v_mfma_f32_16x16x32_bf16 v[96:99], v[158:161], v[182:185], 0
	v_mfma_f32_16x16x32_bf16 v[84:87], v[150:153], v[190:193], 0
	v_mfma_f32_16x16x32_bf16 v[80:83], v[158:161], v[190:193], 0
	v_mfma_f32_16x16x32_bf16 v[124:127], v[154:157], v[170:173], v[124:127]
	v_mfma_f32_16x16x32_bf16 v[120:123], v[162:165], v[170:173], v[120:123]
	v_mfma_f32_16x16x32_bf16 v[116:119], v[154:157], v[178:181], v[116:119]
	v_mfma_f32_16x16x32_bf16 v[108:111], v[162:165], v[178:181], v[108:111]
	v_mfma_f32_16x16x32_bf16 v[100:103], v[154:157], v[186:189], v[100:103]
	v_mfma_f32_16x16x32_bf16 v[96:99], v[162:165], v[186:189], v[96:99]
	v_mfma_f32_16x16x32_bf16 v[84:87], v[154:157], v[194:197], v[84:87]
	v_mfma_f32_16x16x32_bf16 v[80:83], v[162:165], v[194:197], v[80:83]
	s_barrier
	s_add_i32 s74, s63, s33
	s_add_u32 s98, s36, s6
	s_addc_u32 s99, s37, s7
	s_mov_b32 m0, s74
	ds_read_b128 v[198:201], v148
	ds_read_b128 v[202:205], v148 offset:1024
	ds_read_b128 v[206:209], v148 offset:2048
	ds_read_b128 v[210:213], v148 offset:3072
	global_load_lds_dwordx4 v130, s[36:37]
	s_add_i32 m0, s74, 0x2000
	s_nop 0
	global_load_lds_dwordx4 v134, s[36:37]
	s_barrier
	s_waitcnt lgkmcnt(0)
	v_mfma_f32_16x16x32_bf16 v[112:115], v[198:201], v[166:169], 0
	v_mfma_f32_16x16x32_bf16 v[104:107], v[206:209], v[166:169], 0
	v_mfma_f32_16x16x32_bf16 v[92:95], v[198:201], v[174:177], 0
	v_mfma_f32_16x16x32_bf16 v[88:91], v[206:209], v[174:177], 0
	v_mfma_f32_16x16x32_bf16 v[76:79], v[198:201], v[182:185], 0
	v_mfma_f32_16x16x32_bf16 v[72:75], v[206:209], v[182:185], 0
	v_mfma_f32_16x16x32_bf16 v[68:71], v[198:201], v[190:193], 0
	v_mfma_f32_16x16x32_bf16 v[64:67], v[206:209], v[190:193], 0
	v_mfma_f32_16x16x32_bf16 v[112:115], v[202:205], v[170:173], v[112:115]
	v_mfma_f32_16x16x32_bf16 v[104:107], v[210:213], v[170:173], v[104:107]
	v_mfma_f32_16x16x32_bf16 v[92:95], v[202:205], v[178:181], v[92:95]
	v_mfma_f32_16x16x32_bf16 v[88:91], v[210:213], v[178:181], v[88:91]
	v_mfma_f32_16x16x32_bf16 v[76:79], v[202:205], v[186:189], v[76:79]
	v_mfma_f32_16x16x32_bf16 v[72:75], v[210:213], v[186:189], v[72:75]
	v_mfma_f32_16x16x32_bf16 v[68:71], v[202:205], v[194:197], v[68:71]
	v_mfma_f32_16x16x32_bf16 v[64:67], v[210:213], v[194:197], v[64:67]
	s_mov_b32 m0, s56
	s_add_u32 s100, s54, s6
	s_addc_u32 s101, s55, s7
	s_barrier
	ds_read_b128 v[166:169], v147 offset:16384
	ds_read_b128 v[170:173], v147 offset:17408
	ds_read_b128 v[174:177], v147 offset:18432
	ds_read_b128 v[178:181], v147 offset:19456
	ds_read_b128 v[182:185], v147 offset:20480
	ds_read_b128 v[186:189], v147 offset:21504
	ds_read_b128 v[190:193], v147 offset:22528
	ds_read_b128 v[194:197], v147 offset:23552
	global_load_lds_dwordx4 v128, s[54:55]
	s_mov_b32 m0, s57
	s_nop 0
	global_load_lds_dwordx4 v132, s[54:55]
	s_barrier
	s_waitcnt lgkmcnt(0)
	v_mfma_f32_16x16x32_bf16 v[60:63], v[150:153], v[166:169], 0
	v_mfma_f32_16x16x32_bf16 v[56:59], v[158:161], v[166:169], 0
	v_mfma_f32_16x16x32_bf16 v[52:55], v[150:153], v[174:177], 0
	v_mfma_f32_16x16x32_bf16 v[48:51], v[158:161], v[174:177], 0
	v_mfma_f32_16x16x32_bf16 v[36:39], v[150:153], v[182:185], 0
	v_mfma_f32_16x16x32_bf16 v[32:35], v[158:161], v[182:185], 0
	v_mfma_f32_16x16x32_bf16 v[20:23], v[150:153], v[190:193], 0
	v_mfma_f32_16x16x32_bf16 v[16:19], v[158:161], v[190:193], 0
	v_mfma_f32_16x16x32_bf16 v[60:63], v[154:157], v[170:173], v[60:63]
	v_mfma_f32_16x16x32_bf16 v[56:59], v[162:165], v[170:173], v[56:59]
	v_mfma_f32_16x16x32_bf16 v[52:55], v[154:157], v[178:181], v[52:55]
	v_mfma_f32_16x16x32_bf16 v[48:51], v[162:165], v[178:181], v[48:51]
	v_mfma_f32_16x16x32_bf16 v[36:39], v[154:157], v[186:189], v[36:39]
	v_mfma_f32_16x16x32_bf16 v[32:35], v[162:165], v[186:189], v[32:35]
	v_mfma_f32_16x16x32_bf16 v[20:23], v[154:157], v[194:197], v[20:23]
	v_mfma_f32_16x16x32_bf16 v[16:19], v[162:165], v[194:197], v[16:19]
	s_barrier
	s_add_u32 s74, s36, 0x80000
	s_addc_u32 s75, s37, 0
	s_add_i32 s76, s64, s33
	s_mov_b32 m0, s76
	s_nop 0
	global_load_lds_dwordx4 v130, s[74:75]
	s_add_i32 m0, s76, 0x2000
	s_nop 0
	global_load_lds_dwordx4 v134, s[74:75]
	s_waitcnt vmcnt(6)
	s_barrier
	v_mfma_f32_16x16x32_bf16 v[44:47], v[198:201], v[166:169], 0
	v_mfma_f32_16x16x32_bf16 v[40:43], v[206:209], v[166:169], 0
	v_mfma_f32_16x16x32_bf16 v[28:31], v[198:201], v[174:177], 0
	v_mfma_f32_16x16x32_bf16 v[24:27], v[206:209], v[174:177], 0
	v_mfma_f32_16x16x32_bf16 v[12:15], v[198:201], v[182:185], 0
	v_mfma_f32_16x16x32_bf16 v[8:11], v[206:209], v[182:185], 0
	v_mfma_f32_16x16x32_bf16 v[4:7], v[198:201], v[190:193], 0
	v_mfma_f32_16x16x32_bf16 v[0:3], v[206:209], v[190:193], 0
	v_mfma_f32_16x16x32_bf16 v[44:47], v[202:205], v[170:173], v[44:47]
	v_mfma_f32_16x16x32_bf16 v[40:43], v[210:213], v[170:173], v[40:43]
	v_mfma_f32_16x16x32_bf16 v[28:31], v[202:205], v[178:181], v[28:31]
	v_mfma_f32_16x16x32_bf16 v[24:27], v[210:213], v[178:181], v[24:27]
	v_mfma_f32_16x16x32_bf16 v[12:15], v[202:205], v[186:189], v[12:15]
	v_mfma_f32_16x16x32_bf16 v[8:11], v[210:213], v[186:189], v[8:11]
	v_mfma_f32_16x16x32_bf16 v[4:7], v[202:205], v[194:197], v[4:7]
	v_mfma_f32_16x16x32_bf16 v[0:3], v[210:213], v[194:197], v[0:3]
	s_add_i32 s74, 0, 0x18000
	v_add_u32_e32 v149, s74, v143
	s_barrier
	ds_read_b128 v[150:153], v149
	ds_read_b128 v[154:157], v149 offset:1024
	ds_read_b128 v[158:161], v149 offset:2048
	ds_read_b128 v[162:165], v149 offset:3072
	s_add_u32 s54, s54, 0x80000
	s_addc_u32 s55, s55, 0
	s_mov_b32 m0, s58
	ds_read_b128 v[166:169], v147 offset:32768
	ds_read_b128 v[170:173], v147 offset:33792
	ds_read_b128 v[174:177], v147 offset:34816
	ds_read_b128 v[178:181], v147 offset:35840
	ds_read_b128 v[182:185], v147 offset:36864
	ds_read_b128 v[186:189], v147 offset:37888
	ds_read_b128 v[190:193], v147 offset:38912
	ds_read_b128 v[194:197], v147 offset:39936
	global_load_lds_dwordx4 v128, s[54:55]
	s_mov_b32 m0, s59
	s_nop 0
	global_load_lds_dwordx4 v132, s[54:55]
	s_waitcnt lgkmcnt(8)
	s_barrier
	s_waitcnt lgkmcnt(0)
	v_mfma_f32_16x16x32_bf16 v[124:127], v[150:153], v[166:169], v[124:127]
	v_mfma_f32_16x16x32_bf16 v[120:123], v[158:161], v[166:169], v[120:123]
	v_mfma_f32_16x16x32_bf16 v[116:119], v[150:153], v[174:177], v[116:119]
	v_mfma_f32_16x16x32_bf16 v[108:111], v[158:161], v[174:177], v[108:111]
	v_mfma_f32_16x16x32_bf16 v[100:103], v[150:153], v[182:185], v[100:103]
	v_mfma_f32_16x16x32_bf16 v[96:99], v[158:161], v[182:185], v[96:99]
	v_mfma_f32_16x16x32_bf16 v[84:87], v[150:153], v[190:193], v[84:87]
	v_mfma_f32_16x16x32_bf16 v[80:83], v[158:161], v[190:193], v[80:83]
	v_mfma_f32_16x16x32_bf16 v[124:127], v[154:157], v[170:173], v[124:127]
	v_mfma_f32_16x16x32_bf16 v[120:123], v[162:165], v[170:173], v[120:123]
	v_mfma_f32_16x16x32_bf16 v[116:119], v[154:157], v[178:181], v[116:119]
	v_mfma_f32_16x16x32_bf16 v[108:111], v[162:165], v[178:181], v[108:111]
	v_mfma_f32_16x16x32_bf16 v[100:103], v[154:157], v[186:189], v[100:103]
	v_mfma_f32_16x16x32_bf16 v[96:99], v[162:165], v[186:189], v[96:99]
	v_mfma_f32_16x16x32_bf16 v[84:87], v[154:157], v[194:197], v[84:87]
	v_mfma_f32_16x16x32_bf16 v[80:83], v[162:165], v[194:197], v[80:83]
	s_barrier
	s_add_i32 s54, 0, 0x1c000
	s_add_i32 s55, s74, s33
	v_add_u32_e32 v149, s54, v143
	s_mov_b32 m0, s55
	ds_read_b128 v[198:201], v149
	ds_read_b128 v[202:205], v149 offset:1024
	ds_read_b128 v[206:209], v149 offset:2048
	ds_read_b128 v[210:213], v149 offset:3072
	global_load_lds_dwordx4 v130, s[98:99]
	s_add_i32 m0, s55, 0x2000
	s_nop 0
	global_load_lds_dwordx4 v134, s[98:99]
	s_barrier
	s_waitcnt lgkmcnt(0)
	v_mfma_f32_16x16x32_bf16 v[112:115], v[198:201], v[166:169], v[112:115]
	v_mfma_f32_16x16x32_bf16 v[104:107], v[206:209], v[166:169], v[104:107]
	v_mfma_f32_16x16x32_bf16 v[92:95], v[198:201], v[174:177], v[92:95]
	v_mfma_f32_16x16x32_bf16 v[88:91], v[206:209], v[174:177], v[88:91]
	v_mfma_f32_16x16x32_bf16 v[76:79], v[198:201], v[182:185], v[76:79]
	v_mfma_f32_16x16x32_bf16 v[72:75], v[206:209], v[182:185], v[72:75]
	v_mfma_f32_16x16x32_bf16 v[68:71], v[198:201], v[190:193], v[68:71]
	v_mfma_f32_16x16x32_bf16 v[64:67], v[206:209], v[190:193], v[64:67]
	v_mfma_f32_16x16x32_bf16 v[112:115], v[202:205], v[170:173], v[112:115]
	v_mfma_f32_16x16x32_bf16 v[104:107], v[210:213], v[170:173], v[104:107]
	v_mfma_f32_16x16x32_bf16 v[92:95], v[202:205], v[178:181], v[92:95]
	v_mfma_f32_16x16x32_bf16 v[88:91], v[210:213], v[178:181], v[88:91]
	v_mfma_f32_16x16x32_bf16 v[76:79], v[202:205], v[186:189], v[76:79]
	v_mfma_f32_16x16x32_bf16 v[72:75], v[210:213], v[186:189], v[72:75]
	v_mfma_f32_16x16x32_bf16 v[68:71], v[202:205], v[194:197], v[68:71]
	v_mfma_f32_16x16x32_bf16 v[64:67], v[210:213], v[194:197], v[64:67]
	s_mov_b32 m0, s60
	s_barrier
	ds_read_b128 v[166:169], v147 offset:49152
	ds_read_b128 v[170:173], v147 offset:50176
	ds_read_b128 v[174:177], v147 offset:51200
	ds_read_b128 v[178:181], v147 offset:52224
	ds_read_b128 v[182:185], v147 offset:53248
	ds_read_b128 v[186:189], v147 offset:54272
	ds_read_b128 v[190:193], v147 offset:55296
	ds_read_b128 v[194:197], v147 offset:56320
	global_load_lds_dwordx4 v128, s[100:101]
	s_mov_b32 m0, s61
	s_nop 0
	global_load_lds_dwordx4 v132, s[100:101]
	s_barrier
	s_waitcnt lgkmcnt(0)
	v_mfma_f32_16x16x32_bf16 v[60:63], v[150:153], v[166:169], v[60:63]
	v_mfma_f32_16x16x32_bf16 v[56:59], v[158:161], v[166:169], v[56:59]
	v_mfma_f32_16x16x32_bf16 v[52:55], v[150:153], v[174:177], v[52:55]
	v_mfma_f32_16x16x32_bf16 v[48:51], v[158:161], v[174:177], v[48:51]
	v_mfma_f32_16x16x32_bf16 v[36:39], v[150:153], v[182:185], v[36:39]
	v_mfma_f32_16x16x32_bf16 v[32:35], v[158:161], v[182:185], v[32:35]
	v_mfma_f32_16x16x32_bf16 v[20:23], v[150:153], v[190:193], v[20:23]
	v_mfma_f32_16x16x32_bf16 v[16:19], v[158:161], v[190:193], v[16:19]
	v_mfma_f32_16x16x32_bf16 v[60:63], v[154:157], v[170:173], v[60:63]
	v_mfma_f32_16x16x32_bf16 v[56:59], v[162:165], v[170:173], v[56:59]
	v_mfma_f32_16x16x32_bf16 v[52:55], v[154:157], v[178:181], v[52:55]
	v_mfma_f32_16x16x32_bf16 v[48:51], v[162:165], v[178:181], v[48:51]
	v_mfma_f32_16x16x32_bf16 v[36:39], v[154:157], v[186:189], v[36:39]
	v_mfma_f32_16x16x32_bf16 v[32:35], v[162:165], v[186:189], v[32:35]
	v_mfma_f32_16x16x32_bf16 v[20:23], v[154:157], v[194:197], v[20:23]
	v_mfma_f32_16x16x32_bf16 v[16:19], v[162:165], v[194:197], v[16:19]
	s_barrier
	s_add_u32 s36, s36, 0x80080
	s_addc_u32 s37, s37, 0
	s_add_i32 s54, s54, s33
	s_mov_b32 m0, s54
	s_nop 0
	global_load_lds_dwordx4 v130, s[36:37]
	s_add_i32 m0, s54, 0x2000
	s_nop 0
	global_load_lds_dwordx4 v134, s[36:37]
	s_waitcnt vmcnt(6)
	s_barrier
	v_mfma_f32_16x16x32_bf16 v[44:47], v[198:201], v[166:169], v[44:47]
	v_mfma_f32_16x16x32_bf16 v[40:43], v[206:209], v[166:169], v[40:43]
	v_mfma_f32_16x16x32_bf16 v[28:31], v[198:201], v[174:177], v[28:31]
	v_mfma_f32_16x16x32_bf16 v[24:27], v[206:209], v[174:177], v[24:27]
	v_mfma_f32_16x16x32_bf16 v[12:15], v[198:201], v[182:185], v[12:15]
	v_mfma_f32_16x16x32_bf16 v[8:11], v[206:209], v[182:185], v[8:11]
	v_mfma_f32_16x16x32_bf16 v[4:7], v[198:201], v[190:193], v[4:7]
	v_mfma_f32_16x16x32_bf16 v[0:3], v[206:209], v[190:193], v[0:3]
	v_mfma_f32_16x16x32_bf16 v[44:47], v[202:205], v[170:173], v[44:47]
	v_mfma_f32_16x16x32_bf16 v[40:43], v[210:213], v[170:173], v[40:43]
	v_mfma_f32_16x16x32_bf16 v[28:31], v[202:205], v[178:181], v[28:31]
	v_mfma_f32_16x16x32_bf16 v[24:27], v[210:213], v[178:181], v[24:27]
	v_mfma_f32_16x16x32_bf16 v[12:15], v[202:205], v[186:189], v[12:15]
	v_mfma_f32_16x16x32_bf16 v[8:11], v[210:213], v[186:189], v[8:11]
	v_mfma_f32_16x16x32_bf16 v[4:7], v[202:205], v[194:197], v[4:7]
	v_mfma_f32_16x16x32_bf16 v[0:3], v[210:213], v[194:197], v[0:3]
	s_add_i32 s73, s73, 2
	s_add_u32 s18, s18, 0x100
	s_addc_u32 s19, s19, 0
	s_add_u32 s29, s29, 0x100
	s_addc_u32 s72, s72, 0
	s_cmp_gt_u32 s73, 29
	s_barrier
	s_cbranch_scc0 .LBB0_243
.LBB0_243:
	ds_read_b128 v[150:153], v146
	ds_read_b128 v[154:157], v146 offset:1024
	ds_read_b128 v[158:161], v146 offset:2048
	ds_read_b128 v[162:165], v146 offset:3072
	s_add_u32 s36, s18, 0xfff80080
	s_addc_u32 s37, s19, -1
	s_cmp_eq_u32 s73, 28
	s_cselect_b32 s55, s11, s37
	s_cselect_b32 s54, s67, s36
	s_cselect_b32 s37, s9, s72
	s_cselect_b32 s36, s28, s29
	s_add_i32 m0, s56, 0xc000
	ds_read_b128 v[166:169], v147
	ds_read_b128 v[170:173], v147 offset:1024
	ds_read_b128 v[174:177], v147 offset:2048
	ds_read_b128 v[178:181], v147 offset:3072
	ds_read_b128 v[182:185], v147 offset:4096
	ds_read_b128 v[186:189], v147 offset:5120
	ds_read_b128 v[190:193], v147 offset:6144
	ds_read_b128 v[194:197], v147 offset:7168
	global_load_lds_dwordx4 v138, s[18:19]
	s_add_i32 m0, s56, 0xe000
	s_nop 0
	global_load_lds_dwordx4 v140, s[18:19]
	s_waitcnt lgkmcnt(8)
	s_barrier
	s_waitcnt lgkmcnt(0)
	v_mfma_f32_16x16x32_bf16 v[124:127], v[150:153], v[166:169], v[124:127]
	v_mfma_f32_16x16x32_bf16 v[120:123], v[158:161], v[166:169], v[120:123]
	v_mfma_f32_16x16x32_bf16 v[116:119], v[150:153], v[174:177], v[116:119]
	v_mfma_f32_16x16x32_bf16 v[108:111], v[158:161], v[174:177], v[108:111]
	v_mfma_f32_16x16x32_bf16 v[100:103], v[150:153], v[182:185], v[100:103]
	v_mfma_f32_16x16x32_bf16 v[96:99], v[158:161], v[182:185], v[96:99]
	v_mfma_f32_16x16x32_bf16 v[84:87], v[150:153], v[190:193], v[84:87]
	v_mfma_f32_16x16x32_bf16 v[80:83], v[158:161], v[190:193], v[80:83]
	v_mfma_f32_16x16x32_bf16 v[124:127], v[154:157], v[170:173], v[124:127]
	v_mfma_f32_16x16x32_bf16 v[120:123], v[162:165], v[170:173], v[120:123]
	v_mfma_f32_16x16x32_bf16 v[116:119], v[154:157], v[178:181], v[116:119]
	v_mfma_f32_16x16x32_bf16 v[108:111], v[162:165], v[178:181], v[108:111]
	v_mfma_f32_16x16x32_bf16 v[100:103], v[154:157], v[186:189], v[100:103]
	v_mfma_f32_16x16x32_bf16 v[96:99], v[162:165], v[186:189], v[96:99]
	v_mfma_f32_16x16x32_bf16 v[84:87], v[154:157], v[194:197], v[84:87]
	v_mfma_f32_16x16x32_bf16 v[80:83], v[162:165], v[194:197], v[80:83]
	s_barrier
	s_add_i32 s74, s63, s33
	s_add_u32 s98, s36, s6
	s_addc_u32 s99, s37, s7
	s_mov_b32 m0, s74
	ds_read_b128 v[198:201], v148
	ds_read_b128 v[202:205], v148 offset:1024
	ds_read_b128 v[206:209], v148 offset:2048
	ds_read_b128 v[210:213], v148 offset:3072
	global_load_lds_dwordx4 v130, s[36:37]
	s_add_i32 m0, s74, 0x2000
	s_nop 0
	global_load_lds_dwordx4 v134, s[36:37]
	s_barrier
	s_waitcnt lgkmcnt(0)
	v_mfma_f32_16x16x32_bf16 v[112:115], v[198:201], v[166:169], v[112:115]
	v_mfma_f32_16x16x32_bf16 v[104:107], v[206:209], v[166:169], v[104:107]
	v_mfma_f32_16x16x32_bf16 v[92:95], v[198:201], v[174:177], v[92:95]
	v_mfma_f32_16x16x32_bf16 v[88:91], v[206:209], v[174:177], v[88:91]
	v_mfma_f32_16x16x32_bf16 v[76:79], v[198:201], v[182:185], v[76:79]
	v_mfma_f32_16x16x32_bf16 v[72:75], v[206:209], v[182:185], v[72:75]
	v_mfma_f32_16x16x32_bf16 v[68:71], v[198:201], v[190:193], v[68:71]
	v_mfma_f32_16x16x32_bf16 v[64:67], v[206:209], v[190:193], v[64:67]
	v_mfma_f32_16x16x32_bf16 v[112:115], v[202:205], v[170:173], v[112:115]
	v_mfma_f32_16x16x32_bf16 v[104:107], v[210:213], v[170:173], v[104:107]
	v_mfma_f32_16x16x32_bf16 v[92:95], v[202:205], v[178:181], v[92:95]
	v_mfma_f32_16x16x32_bf16 v[88:91], v[210:213], v[178:181], v[88:91]
	v_mfma_f32_16x16x32_bf16 v[76:79], v[202:205], v[186:189], v[76:79]
	v_mfma_f32_16x16x32_bf16 v[72:75], v[210:213], v[186:189], v[72:75]
	v_mfma_f32_16x16x32_bf16 v[68:71], v[202:205], v[194:197], v[68:71]
	v_mfma_f32_16x16x32_bf16 v[64:67], v[210:213], v[194:197], v[64:67]
	s_mov_b32 m0, s56
	s_add_u32 s100, s54, s6
	s_addc_u32 s101, s55, s7
	s_barrier
	ds_read_b128 v[166:169], v147 offset:16384
	ds_read_b128 v[170:173], v147 offset:17408
	ds_read_b128 v[174:177], v147 offset:18432
	ds_read_b128 v[178:181], v147 offset:19456
	ds_read_b128 v[182:185], v147 offset:20480
	ds_read_b128 v[186:189], v147 offset:21504
	ds_read_b128 v[190:193], v147 offset:22528
	ds_read_b128 v[194:197], v147 offset:23552
	global_load_lds_dwordx4 v128, s[54:55]
	s_mov_b32 m0, s57
	s_nop 0
	global_load_lds_dwordx4 v132, s[54:55]
	s_barrier
	s_waitcnt lgkmcnt(0)
	v_mfma_f32_16x16x32_bf16 v[60:63], v[150:153], v[166:169], v[60:63]
	v_mfma_f32_16x16x32_bf16 v[56:59], v[158:161], v[166:169], v[56:59]
	v_mfma_f32_16x16x32_bf16 v[52:55], v[150:153], v[174:177], v[52:55]
	v_mfma_f32_16x16x32_bf16 v[48:51], v[158:161], v[174:177], v[48:51]
	v_mfma_f32_16x16x32_bf16 v[36:39], v[150:153], v[182:185], v[36:39]
	v_mfma_f32_16x16x32_bf16 v[32:35], v[158:161], v[182:185], v[32:35]
	v_mfma_f32_16x16x32_bf16 v[20:23], v[150:153], v[190:193], v[20:23]
	v_mfma_f32_16x16x32_bf16 v[16:19], v[158:161], v[190:193], v[16:19]
	v_mfma_f32_16x16x32_bf16 v[60:63], v[154:157], v[170:173], v[60:63]
	v_mfma_f32_16x16x32_bf16 v[56:59], v[162:165], v[170:173], v[56:59]
	v_mfma_f32_16x16x32_bf16 v[52:55], v[154:157], v[178:181], v[52:55]
	v_mfma_f32_16x16x32_bf16 v[48:51], v[162:165], v[178:181], v[48:51]
	v_mfma_f32_16x16x32_bf16 v[36:39], v[154:157], v[186:189], v[36:39]
	v_mfma_f32_16x16x32_bf16 v[32:35], v[162:165], v[186:189], v[32:35]
	v_mfma_f32_16x16x32_bf16 v[20:23], v[154:157], v[194:197], v[20:23]
	v_mfma_f32_16x16x32_bf16 v[16:19], v[162:165], v[194:197], v[16:19]
	s_barrier
	s_add_u32 s74, s36, 0x80000
	s_addc_u32 s75, s37, 0
	s_add_i32 s76, s64, s33
	s_mov_b32 m0, s76
	s_nop 0
	global_load_lds_dwordx4 v130, s[74:75]
	s_add_i32 m0, s76, 0x2000
	s_nop 0
	global_load_lds_dwordx4 v134, s[74:75]
	s_waitcnt vmcnt(6)
	s_barrier
	v_mfma_f32_16x16x32_bf16 v[44:47], v[198:201], v[166:169], v[44:47]
	v_mfma_f32_16x16x32_bf16 v[40:43], v[206:209], v[166:169], v[40:43]
	v_mfma_f32_16x16x32_bf16 v[28:31], v[198:201], v[174:177], v[28:31]
	v_mfma_f32_16x16x32_bf16 v[24:27], v[206:209], v[174:177], v[24:27]
	v_mfma_f32_16x16x32_bf16 v[12:15], v[198:201], v[182:185], v[12:15]
	v_mfma_f32_16x16x32_bf16 v[8:11], v[206:209], v[182:185], v[8:11]
	v_mfma_f32_16x16x32_bf16 v[4:7], v[198:201], v[190:193], v[4:7]
	v_mfma_f32_16x16x32_bf16 v[0:3], v[206:209], v[190:193], v[0:3]
	v_mfma_f32_16x16x32_bf16 v[44:47], v[202:205], v[170:173], v[44:47]
	v_mfma_f32_16x16x32_bf16 v[40:43], v[210:213], v[170:173], v[40:43]
	v_mfma_f32_16x16x32_bf16 v[28:31], v[202:205], v[178:181], v[28:31]
	v_mfma_f32_16x16x32_bf16 v[24:27], v[210:213], v[178:181], v[24:27]
	v_mfma_f32_16x16x32_bf16 v[12:15], v[202:205], v[186:189], v[12:15]
	v_mfma_f32_16x16x32_bf16 v[8:11], v[210:213], v[186:189], v[8:11]
	v_mfma_f32_16x16x32_bf16 v[4:7], v[202:205], v[194:197], v[4:7]
	v_mfma_f32_16x16x32_bf16 v[0:3], v[210:213], v[194:197], v[0:3]
	s_add_i32 s74, 0, 0x18000
	v_add_u32_e32 v149, s74, v143
	s_barrier
	ds_read_b128 v[150:153], v149
	ds_read_b128 v[154:157], v149 offset:1024
	ds_read_b128 v[158:161], v149 offset:2048
	ds_read_b128 v[162:165], v149 offset:3072
	s_add_u32 s54, s54, 0x80000
	s_addc_u32 s55, s55, 0
	s_mov_b32 m0, s58
	ds_read_b128 v[166:169], v147 offset:32768
	ds_read_b128 v[170:173], v147 offset:33792
	ds_read_b128 v[174:177], v147 offset:34816
	ds_read_b128 v[178:181], v147 offset:35840
	ds_read_b128 v[182:185], v147 offset:36864
	ds_read_b128 v[186:189], v147 offset:37888
	ds_read_b128 v[190:193], v147 offset:38912
	ds_read_b128 v[194:197], v147 offset:39936
	global_load_lds_dwordx4 v128, s[54:55]
	s_mov_b32 m0, s59
	s_nop 0
	global_load_lds_dwordx4 v132, s[54:55]
	s_waitcnt lgkmcnt(8)
	s_barrier
	s_waitcnt lgkmcnt(0)
	v_mfma_f32_16x16x32_bf16 v[124:127], v[150:153], v[166:169], v[124:127]
	v_mfma_f32_16x16x32_bf16 v[120:123], v[158:161], v[166:169], v[120:123]
	v_mfma_f32_16x16x32_bf16 v[116:119], v[150:153], v[174:177], v[116:119]
	v_mfma_f32_16x16x32_bf16 v[108:111], v[158:161], v[174:177], v[108:111]
	v_mfma_f32_16x16x32_bf16 v[100:103], v[150:153], v[182:185], v[100:103]
	v_mfma_f32_16x16x32_bf16 v[96:99], v[158:161], v[182:185], v[96:99]
	v_mfma_f32_16x16x32_bf16 v[84:87], v[150:153], v[190:193], v[84:87]
	v_mfma_f32_16x16x32_bf16 v[80:83], v[158:161], v[190:193], v[80:83]
	v_mfma_f32_16x16x32_bf16 v[124:127], v[154:157], v[170:173], v[124:127]
	v_mfma_f32_16x16x32_bf16 v[120:123], v[162:165], v[170:173], v[120:123]
	v_mfma_f32_16x16x32_bf16 v[116:119], v[154:157], v[178:181], v[116:119]
	v_mfma_f32_16x16x32_bf16 v[108:111], v[162:165], v[178:181], v[108:111]
	v_mfma_f32_16x16x32_bf16 v[100:103], v[154:157], v[186:189], v[100:103]
	v_mfma_f32_16x16x32_bf16 v[96:99], v[162:165], v[186:189], v[96:99]
	v_mfma_f32_16x16x32_bf16 v[84:87], v[154:157], v[194:197], v[84:87]
	v_mfma_f32_16x16x32_bf16 v[80:83], v[162:165], v[194:197], v[80:83]
	s_barrier
	s_add_i32 s54, 0, 0x1c000
	s_add_i32 s55, s74, s33
	v_add_u32_e32 v149, s54, v143
	s_mov_b32 m0, s55
	ds_read_b128 v[198:201], v149
	ds_read_b128 v[202:205], v149 offset:1024
	ds_read_b128 v[206:209], v149 offset:2048
	ds_read_b128 v[210:213], v149 offset:3072
	global_load_lds_dwordx4 v130, s[98:99]
	s_add_i32 m0, s55, 0x2000
	s_nop 0
	global_load_lds_dwordx4 v134, s[98:99]
	s_barrier
	s_waitcnt lgkmcnt(0)
	v_mfma_f32_16x16x32_bf16 v[112:115], v[198:201], v[166:169], v[112:115]
	v_mfma_f32_16x16x32_bf16 v[104:107], v[206:209], v[166:169], v[104:107]
	v_mfma_f32_16x16x32_bf16 v[92:95], v[198:201], v[174:177], v[92:95]
	v_mfma_f32_16x16x32_bf16 v[88:91], v[206:209], v[174:177], v[88:91]
	v_mfma_f32_16x16x32_bf16 v[76:79], v[198:201], v[182:185], v[76:79]
	v_mfma_f32_16x16x32_bf16 v[72:75], v[206:209], v[182:185], v[72:75]
	v_mfma_f32_16x16x32_bf16 v[68:71], v[198:201], v[190:193], v[68:71]
	v_mfma_f32_16x16x32_bf16 v[64:67], v[206:209], v[190:193], v[64:67]
	v_mfma_f32_16x16x32_bf16 v[112:115], v[202:205], v[170:173], v[112:115]
	v_mfma_f32_16x16x32_bf16 v[104:107], v[210:213], v[170:173], v[104:107]
	v_mfma_f32_16x16x32_bf16 v[92:95], v[202:205], v[178:181], v[92:95]
	v_mfma_f32_16x16x32_bf16 v[88:91], v[210:213], v[178:181], v[88:91]
	v_mfma_f32_16x16x32_bf16 v[76:79], v[202:205], v[186:189], v[76:79]
	v_mfma_f32_16x16x32_bf16 v[72:75], v[210:213], v[186:189], v[72:75]
	v_mfma_f32_16x16x32_bf16 v[68:71], v[202:205], v[194:197], v[68:71]
	v_mfma_f32_16x16x32_bf16 v[64:67], v[210:213], v[194:197], v[64:67]
	s_mov_b32 m0, s60
	s_barrier
	ds_read_b128 v[166:169], v147 offset:49152
	ds_read_b128 v[170:173], v147 offset:50176
	ds_read_b128 v[174:177], v147 offset:51200
	ds_read_b128 v[178:181], v147 offset:52224
	ds_read_b128 v[182:185], v147 offset:53248
	ds_read_b128 v[186:189], v147 offset:54272
	ds_read_b128 v[190:193], v147 offset:55296
	ds_read_b128 v[194:197], v147 offset:56320
	global_load_lds_dwordx4 v128, s[100:101]
	s_mov_b32 m0, s61
	s_nop 0
	global_load_lds_dwordx4 v132, s[100:101]
	s_barrier
	s_waitcnt lgkmcnt(0)
	v_mfma_f32_16x16x32_bf16 v[60:63], v[150:153], v[166:169], v[60:63]
	v_mfma_f32_16x16x32_bf16 v[56:59], v[158:161], v[166:169], v[56:59]
	v_mfma_f32_16x16x32_bf16 v[52:55], v[150:153], v[174:177], v[52:55]
	v_mfma_f32_16x16x32_bf16 v[48:51], v[158:161], v[174:177], v[48:51]
	v_mfma_f32_16x16x32_bf16 v[36:39], v[150:153], v[182:185], v[36:39]
	v_mfma_f32_16x16x32_bf16 v[32:35], v[158:161], v[182:185], v[32:35]
	v_mfma_f32_16x16x32_bf16 v[20:23], v[150:153], v[190:193], v[20:23]
	v_mfma_f32_16x16x32_bf16 v[16:19], v[158:161], v[190:193], v[16:19]
	v_mfma_f32_16x16x32_bf16 v[60:63], v[154:157], v[170:173], v[60:63]
	v_mfma_f32_16x16x32_bf16 v[56:59], v[162:165], v[170:173], v[56:59]
	v_mfma_f32_16x16x32_bf16 v[52:55], v[154:157], v[178:181], v[52:55]
	v_mfma_f32_16x16x32_bf16 v[48:51], v[162:165], v[178:181], v[48:51]
	v_mfma_f32_16x16x32_bf16 v[36:39], v[154:157], v[186:189], v[36:39]
	v_mfma_f32_16x16x32_bf16 v[32:35], v[162:165], v[186:189], v[32:35]
	v_mfma_f32_16x16x32_bf16 v[20:23], v[154:157], v[194:197], v[20:23]
	v_mfma_f32_16x16x32_bf16 v[16:19], v[162:165], v[194:197], v[16:19]
	s_barrier
	s_add_u32 s36, s36, 0x80080
	s_addc_u32 s37, s37, 0
	s_add_i32 s54, s54, s33
	s_mov_b32 m0, s54
	s_nop 0
	global_load_lds_dwordx4 v130, s[36:37]
	s_add_i32 m0, s54, 0x2000
	s_nop 0
	global_load_lds_dwordx4 v134, s[36:37]
	s_waitcnt vmcnt(6)
	s_barrier
	v_mfma_f32_16x16x32_bf16 v[44:47], v[198:201], v[166:169], v[44:47]
	v_mfma_f32_16x16x32_bf16 v[40:43], v[206:209], v[166:169], v[40:43]
	v_mfma_f32_16x16x32_bf16 v[28:31], v[198:201], v[174:177], v[28:31]
	v_mfma_f32_16x16x32_bf16 v[24:27], v[206:209], v[174:177], v[24:27]
	v_mfma_f32_16x16x32_bf16 v[12:15], v[198:201], v[182:185], v[12:15]
	v_mfma_f32_16x16x32_bf16 v[8:11], v[206:209], v[182:185], v[8:11]
	v_mfma_f32_16x16x32_bf16 v[4:7], v[198:201], v[190:193], v[4:7]
	v_mfma_f32_16x16x32_bf16 v[0:3], v[206:209], v[190:193], v[0:3]
	v_mfma_f32_16x16x32_bf16 v[44:47], v[202:205], v[170:173], v[44:47]
	v_mfma_f32_16x16x32_bf16 v[40:43], v[210:213], v[170:173], v[40:43]
	v_mfma_f32_16x16x32_bf16 v[28:31], v[202:205], v[178:181], v[28:31]
	v_mfma_f32_16x16x32_bf16 v[24:27], v[210:213], v[178:181], v[24:27]
	v_mfma_f32_16x16x32_bf16 v[12:15], v[202:205], v[186:189], v[12:15]
	v_mfma_f32_16x16x32_bf16 v[8:11], v[210:213], v[186:189], v[8:11]
	v_mfma_f32_16x16x32_bf16 v[4:7], v[202:205], v[194:197], v[4:7]
	v_mfma_f32_16x16x32_bf16 v[0:3], v[210:213], v[194:197], v[0:3]
	s_add_i32 s73, s73, 2
	s_add_u32 s18, s18, 0x100
	s_addc_u32 s19, s19, 0
	s_add_u32 s29, s29, 0x100
	s_addc_u32 s72, s72, 0
	s_cmp_gt_u32 s73, 29
	s_barrier
	s_cbranch_scc0 .LBB0_243
	v_lshl_add_u32 v150, s66, 8, v142
	v_lshl_or_b32 v149, s0, 8, v145
	v_ashrrev_i32_e32 v151, 31, v150
	v_cvt_pk_bf16_f32 v124, v124, v125
	v_cvt_pk_bf16_f32 v125, v126, v127
	v_cvt_pk_bf16_f32 v127, v122, v123
	v_ashrrev_i32_e32 v122, 4, v149
	v_cvt_pk_bf16_f32 v126, v120, v121
	v_mad_i64_i32 v[120:121], s[18:19], v122, s65, v[150:151]
	v_lshlrev_b64 v[120:121], 5, v[120:121]
	v_lshl_add_u64 v[120:121], v[136:137], 0, v[120:121]
	global_store_dwordx4 v[120:121], v[124:127], off
	v_or_b32_e32 v120, 8, v122
	v_cvt_pk_bf16_f32 v112, v112, v113
	v_cvt_pk_bf16_f32 v113, v114, v115
	v_cvt_pk_bf16_f32 v114, v104, v105
	v_mad_i64_i32 v[104:105], s[18:19], v120, s65, v[150:151]
	v_lshlrev_b64 v[104:105], 5, v[104:105]
	v_cvt_pk_bf16_f32 v115, v106, v107
	v_lshl_add_u64 v[104:105], v[136:137], 0, v[104:105]
	global_store_dwordx4 v[104:105], v[112:115], off
	v_cvt_pk_bf16_f32 v92, v92, v93
	v_cvt_pk_bf16_f32 v93, v94, v95
	v_or_b32_e32 v112, 16, v150
	v_ashrrev_i32_e32 v113, 31, v112
	v_cvt_pk_bf16_f32 v94, v88, v89
	v_mad_i64_i32 v[88:89], s[18:19], v120, s65, v[112:113]
	v_lshlrev_b64 v[88:89], 5, v[88:89]
	v_cvt_pk_bf16_f32 v95, v90, v91
	v_lshl_add_u64 v[88:89], v[136:137], 0, v[88:89]
	global_store_dwordx4 v[88:89], v[92:95], off
	v_cvt_pk_bf16_f32 v76, v76, v77
	v_cvt_pk_bf16_f32 v77, v78, v79
	v_or_b32_e32 v92, 32, v150
	v_ashrrev_i32_e32 v93, 31, v92
	v_cvt_pk_bf16_f32 v78, v72, v73
	v_mad_i64_i32 v[72:73], s[18:19], v120, s65, v[92:93]
	v_lshlrev_b64 v[72:73], 5, v[72:73]
	v_cvt_pk_bf16_f32 v79, v74, v75
	v_lshl_add_u64 v[72:73], v[136:137], 0, v[72:73]
	global_store_dwordx4 v[72:73], v[76:79], off
	v_cvt_pk_bf16_f32 v68, v68, v69
	v_cvt_pk_bf16_f32 v69, v70, v71
	v_or_b32_e32 v76, 48, v150
	v_ashrrev_i32_e32 v77, 31, v76
	v_cvt_pk_bf16_f32 v70, v64, v65
	v_mad_i64_i32 v[64:65], s[18:19], v120, s65, v[76:77]
	v_lshlrev_b64 v[64:65], 5, v[64:65]
	v_cvt_pk_bf16_f32 v71, v66, v67
	v_lshl_add_u64 v[64:65], v[136:137], 0, v[64:65]
	global_store_dwordx4 v[64:65], v[68:71], off
	v_add_u32_e32 v64, 0x80, v150
	v_ashrrev_i32_e32 v65, 31, v64
	v_cvt_pk_bf16_f32 v44, v44, v45
	v_cvt_pk_bf16_f32 v45, v46, v47
	v_cvt_pk_bf16_f32 v46, v40, v41
	v_mad_i64_i32 v[40:41], s[18:19], v120, s65, v[64:65]
	v_lshlrev_b64 v[40:41], 5, v[40:41]
	v_cvt_pk_bf16_f32 v47, v42, v43
	v_lshl_add_u64 v[40:41], v[136:137], 0, v[40:41]
	global_store_dwordx4 v[40:41], v[44:47], off
	v_cvt_pk_bf16_f32 v106, v108, v109
	v_mad_i64_i32 v[108:109], s[18:19], v122, s65, v[112:113]
	v_add_u32_e32 v44, 0x90, v150
	v_ashrrev_i32_e32 v45, 31, v44
	v_cvt_pk_bf16_f32 v28, v28, v29
	v_cvt_pk_bf16_f32 v29, v30, v31
	v_cvt_pk_bf16_f32 v30, v24, v25
	v_mad_i64_i32 v[24:25], s[18:19], v120, s65, v[44:45]
	v_lshlrev_b64 v[108:109], 5, v[108:109]
	v_lshlrev_b64 v[24:25], 5, v[24:25]
	v_cvt_pk_bf16_f32 v104, v116, v117
	v_cvt_pk_bf16_f32 v105, v118, v119
	v_cvt_pk_bf16_f32 v107, v110, v111
	v_lshl_add_u64 v[108:109], v[136:137], 0, v[108:109]
	v_cvt_pk_bf16_f32 v31, v26, v27
	v_lshl_add_u64 v[24:25], v[136:137], 0, v[24:25]
	global_store_dwordx4 v[108:109], v[104:107], off
	global_store_dwordx4 v[24:25], v[28:31], off
	v_mad_i64_i32 v[94:95], s[18:19], v122, s65, v[92:93]
	s_nop 0
	v_add_u32_e32 v28, 0xa0, v150
	v_ashrrev_i32_e32 v29, 31, v28
	v_cvt_pk_bf16_f32 v12, v12, v13
	v_cvt_pk_bf16_f32 v13, v14, v15
	v_cvt_pk_bf16_f32 v14, v8, v9
	v_mad_i64_i32 v[8:9], s[18:19], v120, s65, v[28:29]
	v_lshlrev_b64 v[94:95], 5, v[94:95]
	v_lshlrev_b64 v[8:9], 5, v[8:9]
	v_cvt_pk_bf16_f32 v88, v100, v101
	v_cvt_pk_bf16_f32 v89, v102, v103
	v_cvt_pk_bf16_f32 v90, v96, v97
	v_cvt_pk_bf16_f32 v91, v98, v99
	v_lshl_add_u64 v[94:95], v[136:137], 0, v[94:95]
	v_cvt_pk_bf16_f32 v15, v10, v11
	v_lshl_add_u64 v[8:9], v[136:137], 0, v[8:9]
	global_store_dwordx4 v[94:95], v[88:91], off
	global_store_dwordx4 v[8:9], v[12:15], off
	v_mad_i64_i32 v[78:79], s[18:19], v122, s65, v[76:77]
	s_nop 0
	v_add_u32_e32 v12, 0xb0, v150
	v_ashrrev_i32_e32 v13, 31, v12
	v_cvt_pk_bf16_f32 v60, v60, v61
	v_cvt_pk_bf16_f32 v61, v62, v63
	v_cvt_pk_bf16_f32 v62, v56, v57
	v_mad_i64_i32 v[56:57], s[18:19], v122, s65, v[64:65]
	v_mad_i64_i32 v[46:47], s[18:19], v122, s65, v[44:45]
	v_mad_i64_i32 v[30:31], s[18:19], v122, s65, v[28:29]
	v_mad_i64_i32 v[14:15], s[18:19], v122, s65, v[12:13]
	v_cvt_pk_bf16_f32 v4, v4, v5
	v_cvt_pk_bf16_f32 v5, v6, v7
	v_cvt_pk_bf16_f32 v6, v0, v1
	v_mad_i64_i32 v[0:1], s[18:19], v120, s65, v[12:13]
	v_lshlrev_b64 v[78:79], 5, v[78:79]
	v_lshlrev_b64 v[56:57], 5, v[56:57]
	v_lshlrev_b64 v[46:47], 5, v[46:47]
	v_lshlrev_b64 v[30:31], 5, v[30:31]
	v_lshlrev_b64 v[14:15], 5, v[14:15]
	v_lshlrev_b64 v[0:1], 5, v[0:1]
	v_cvt_pk_bf16_f32 v72, v84, v85
	v_cvt_pk_bf16_f32 v73, v86, v87
	v_cvt_pk_bf16_f32 v74, v80, v81
	v_cvt_pk_bf16_f32 v75, v82, v83
	v_lshl_add_u64 v[78:79], v[136:137], 0, v[78:79]
	v_cvt_pk_bf16_f32 v63, v58, v59
	v_lshl_add_u64 v[56:57], v[136:137], 0, v[56:57]
	v_cvt_pk_bf16_f32 v40, v52, v53
	v_cvt_pk_bf16_f32 v41, v54, v55
	v_cvt_pk_bf16_f32 v42, v48, v49
	v_cvt_pk_bf16_f32 v43, v50, v51
	v_lshl_add_u64 v[46:47], v[136:137], 0, v[46:47]
	v_cvt_pk_bf16_f32 v24, v36, v37
	v_cvt_pk_bf16_f32 v25, v38, v39
	v_cvt_pk_bf16_f32 v26, v32, v33
	v_cvt_pk_bf16_f32 v27, v34, v35
	v_lshl_add_u64 v[30:31], v[136:137], 0, v[30:31]
	v_cvt_pk_bf16_f32 v8, v20, v21
	v_cvt_pk_bf16_f32 v9, v22, v23
	v_cvt_pk_bf16_f32 v10, v16, v17
	v_cvt_pk_bf16_f32 v11, v18, v19
	v_lshl_add_u64 v[14:15], v[136:137], 0, v[14:15]
	v_cvt_pk_bf16_f32 v7, v2, v3
	v_lshl_add_u64 v[0:1], v[136:137], 0, v[0:1]
	s_and_b64 vcc, exec, s[14:15]
	s_mov_b32 s0, s8
	s_mov_b32 s66, s10
	s_mov_b64 s[36:37], s[16:17]
	s_mov_b64 s[18:19], s[12:13]
	global_store_dwordx4 v[78:79], v[72:75], off
	global_store_dwordx4 v[56:57], v[60:63], off
	global_store_dwordx4 v[46:47], v[40:43], off
	global_store_dwordx4 v[30:31], v[24:27], off
	global_store_dwordx4 v[14:15], v[8:11], off
	global_store_dwordx4 v[0:1], v[4:7], off
	s_cbranch_vccz .LBB0_239
	s_waitcnt vmcnt(0)
	s_cmpk_gt_u32 s2, 0xff
	s_cbranch_scc1 .LBB0_247
	s_barrier

.LBB0_329:
	s_ashr_i32 s15, s14, 31
	s_xor_b64 s[16:17], s[28:29], -1
	s_lshl_b64 s[18:19], s[14:15], 20
	s_add_u32 s18, s58, s18
	s_addc_u32 s19, s59, s19
	s_and_b64 s[30:31], s[28:29], exec
	s_cselect_b32 s1, s19, s37
	s_cselect_b32 s15, s18, s36
	s_ashr_i32 s13, s12, 31
	s_lshl_b64 s[30:31], s[12:13], 20
	s_add_u32 s30, s22, s30
	s_addc_u32 s31, s23, s31
	s_and_b64 s[28:29], s[28:29], exec
	s_cselect_b32 s13, s31, s55
	s_cselect_b32 s28, s30, s54
	s_add_u32 s36, s36, 0x80080
	s_addc_u32 s37, s37, 0
	s_add_u32 s29, s54, 0x100
	s_addc_u32 s35, s55, 0
	s_mov_b32 s78, -2
	ds_read_b128 v[146:149], v152
	ds_read_b128 v[156:159], v152 offset:1024
	ds_read_b128 v[160:163], v152 offset:2048
	ds_read_b128 v[164:167], v152 offset:3072
	s_add_u32 s54, s36, 0xfff80080
	s_addc_u32 s55, s37, -1
	s_cmp_eq_u32 s78, 28
	s_cselect_b32 s57, s1, s55
	s_cselect_b32 s56, s15, s54
	s_cselect_b32 s55, s13, s35
	s_cselect_b32 s54, s28, s29
	s_add_i32 m0, s61, 0xc000
	ds_read_b128 v[168:171], v153
	ds_read_b128 v[172:175], v153 offset:1024
	ds_read_b128 v[176:179], v153 offset:2048
	ds_read_b128 v[180:183], v153 offset:3072
	ds_read_b128 v[184:187], v153 offset:4096
	ds_read_b128 v[188:191], v153 offset:5120
	ds_read_b128 v[192:195], v153 offset:6144
	ds_read_b128 v[196:199], v153 offset:7168
	global_load_lds_dwordx4 v138, s[36:37]
	s_add_i32 m0, s61, 0xe000
	s_nop 0
	global_load_lds_dwordx4 v140, s[36:37]
	s_waitcnt lgkmcnt(8)
	s_barrier
	s_waitcnt lgkmcnt(0)
	v_mfma_f32_16x16x32_bf16 v[124:127], v[146:149], v[168:171], 0
	v_mfma_f32_16x16x32_bf16 v[120:123], v[160:163], v[168:171], 0
	v_mfma_f32_16x16x32_bf16 v[108:111], v[146:149], v[176:179], 0
	v_mfma_f32_16x16x32_bf16 v[104:107], v[160:163], v[176:179], 0
	v_mfma_f32_16x16x32_bf16 v[92:95], v[146:149], v[184:187], 0
	v_mfma_f32_16x16x32_bf16 v[88:91], v[160:163], v[184:187], 0
	v_mfma_f32_16x16x32_bf16 v[76:79], v[146:149], v[192:195], 0
	v_mfma_f32_16x16x32_bf16 v[72:75], v[160:163], v[192:195], 0
	v_mfma_f32_16x16x32_bf16 v[124:127], v[156:159], v[172:175], v[124:127]
	v_mfma_f32_16x16x32_bf16 v[120:123], v[164:167], v[172:175], v[120:123]
	v_mfma_f32_16x16x32_bf16 v[108:111], v[156:159], v[180:183], v[108:111]
	v_mfma_f32_16x16x32_bf16 v[104:107], v[164:167], v[180:183], v[104:107]
	v_mfma_f32_16x16x32_bf16 v[92:95], v[156:159], v[188:191], v[92:95]
	v_mfma_f32_16x16x32_bf16 v[88:91], v[164:167], v[188:191], v[88:91]
	v_mfma_f32_16x16x32_bf16 v[76:79], v[156:159], v[196:199], v[76:79]
	v_mfma_f32_16x16x32_bf16 v[72:75], v[164:167], v[196:199], v[72:75]
	s_barrier
	s_add_i32 s79, s75, s60
	s_add_u32 s98, s54, s10
	s_addc_u32 s99, s55, s11
	s_mov_b32 m0, s79
	ds_read_b128 v[200:203], v154
	ds_read_b128 v[204:207], v154 offset:1024
	ds_read_b128 v[208:211], v154 offset:2048
	ds_read_b128 v[212:215], v154 offset:3072
	global_load_lds_dwordx4 v130, s[54:55]
	s_add_i32 m0, s79, 0x2000
	s_nop 0
	global_load_lds_dwordx4 v134, s[54:55]
	s_barrier
	s_waitcnt lgkmcnt(0)
	v_mfma_f32_16x16x32_bf16 v[116:119], v[200:203], v[168:171], 0
	v_mfma_f32_16x16x32_bf16 v[112:115], v[208:211], v[168:171], 0
	v_mfma_f32_16x16x32_bf16 v[100:103], v[200:203], v[176:179], 0
	v_mfma_f32_16x16x32_bf16 v[96:99], v[208:211], v[176:179], 0
	v_mfma_f32_16x16x32_bf16 v[84:87], v[200:203], v[184:187], 0
	v_mfma_f32_16x16x32_bf16 v[80:83], v[208:211], v[184:187], 0
	v_mfma_f32_16x16x32_bf16 v[68:71], v[200:203], v[192:195], 0
	v_mfma_f32_16x16x32_bf16 v[64:67], v[208:211], v[192:195], 0
	v_mfma_f32_16x16x32_bf16 v[116:119], v[204:207], v[172:175], v[116:119]
	v_mfma_f32_16x16x32_bf16 v[112:115], v[212:215], v[172:175], v[112:115]
	v_mfma_f32_16x16x32_bf16 v[100:103], v[204:207], v[180:183], v[100:103]
	v_mfma_f32_16x16x32_bf16 v[96:99], v[212:215], v[180:183], v[96:99]
	v_mfma_f32_16x16x32_bf16 v[84:87], v[204:207], v[188:191], v[84:87]
	v_mfma_f32_16x16x32_bf16 v[80:83], v[212:215], v[188:191], v[80:83]
	v_mfma_f32_16x16x32_bf16 v[68:71], v[204:207], v[196:199], v[68:71]
	v_mfma_f32_16x16x32_bf16 v[64:67], v[212:215], v[196:199], v[64:67]
	s_mov_b32 m0, s61
	s_add_u32 s100, s56, s10
	s_addc_u32 s101, s57, s11
	s_barrier
	ds_read_b128 v[168:171], v153 offset:16384
	ds_read_b128 v[172:175], v153 offset:17408
	ds_read_b128 v[176:179], v153 offset:18432
	ds_read_b128 v[180:183], v153 offset:19456
	ds_read_b128 v[184:187], v153 offset:20480
	ds_read_b128 v[188:191], v153 offset:21504
	ds_read_b128 v[192:195], v153 offset:22528
	ds_read_b128 v[196:199], v153 offset:23552
	global_load_lds_dwordx4 v128, s[56:57]
	s_mov_b32 m0, s62
	s_nop 0
	global_load_lds_dwordx4 v132, s[56:57]
	s_barrier
	s_waitcnt lgkmcnt(0)
	v_mfma_f32_16x16x32_bf16 v[60:63], v[146:149], v[168:171], 0
	v_mfma_f32_16x16x32_bf16 v[56:59], v[160:163], v[168:171], 0
	v_mfma_f32_16x16x32_bf16 v[44:47], v[146:149], v[176:179], 0
	v_mfma_f32_16x16x32_bf16 v[40:43], v[160:163], v[176:179], 0
	v_mfma_f32_16x16x32_bf16 v[28:31], v[146:149], v[184:187], 0
	v_mfma_f32_16x16x32_bf16 v[24:27], v[160:163], v[184:187], 0
	v_mfma_f32_16x16x32_bf16 v[12:15], v[146:149], v[192:195], 0
	v_mfma_f32_16x16x32_bf16 v[8:11], v[160:163], v[192:195], 0
	v_mfma_f32_16x16x32_bf16 v[60:63], v[156:159], v[172:175], v[60:63]
	v_mfma_f32_16x16x32_bf16 v[56:59], v[164:167], v[172:175], v[56:59]
	v_mfma_f32_16x16x32_bf16 v[44:47], v[156:159], v[180:183], v[44:47]
	v_mfma_f32_16x16x32_bf16 v[40:43], v[164:167], v[180:183], v[40:43]
	v_mfma_f32_16x16x32_bf16 v[28:31], v[156:159], v[188:191], v[28:31]
	v_mfma_f32_16x16x32_bf16 v[24:27], v[164:167], v[188:191], v[24:27]
	v_mfma_f32_16x16x32_bf16 v[12:15], v[156:159], v[196:199], v[12:15]
	v_mfma_f32_16x16x32_bf16 v[8:11], v[164:167], v[196:199], v[8:11]
	s_barrier
	s_add_u32 s80, s54, 0x80000
	s_addc_u32 s81, s55, 0
	s_add_i32 s79, s76, s60
	s_mov_b32 m0, s79
	s_nop 0
	global_load_lds_dwordx4 v130, s[80:81]
	s_add_i32 m0, s79, 0x2000
	s_nop 0
	global_load_lds_dwordx4 v134, s[80:81]
	s_waitcnt vmcnt(6)
	s_barrier
	v_mfma_f32_16x16x32_bf16 v[52:55], v[200:203], v[168:171], 0
	v_mfma_f32_16x16x32_bf16 v[48:51], v[208:211], v[168:171], 0
	v_mfma_f32_16x16x32_bf16 v[36:39], v[200:203], v[176:179], 0
	v_mfma_f32_16x16x32_bf16 v[32:35], v[208:211], v[176:179], 0
	v_mfma_f32_16x16x32_bf16 v[20:23], v[200:203], v[184:187], 0
	v_mfma_f32_16x16x32_bf16 v[16:19], v[208:211], v[184:187], 0
	v_mfma_f32_16x16x32_bf16 v[4:7], v[200:203], v[192:195], 0
	v_mfma_f32_16x16x32_bf16 v[0:3], v[208:211], v[192:195], 0
	v_mfma_f32_16x16x32_bf16 v[52:55], v[204:207], v[172:175], v[52:55]
	v_mfma_f32_16x16x32_bf16 v[48:51], v[212:215], v[172:175], v[48:51]
	v_mfma_f32_16x16x32_bf16 v[36:39], v[204:207], v[180:183], v[36:39]
	v_mfma_f32_16x16x32_bf16 v[32:35], v[212:215], v[180:183], v[32:35]
	v_mfma_f32_16x16x32_bf16 v[20:23], v[204:207], v[188:191], v[20:23]
	v_mfma_f32_16x16x32_bf16 v[16:19], v[212:215], v[188:191], v[16:19]
	v_mfma_f32_16x16x32_bf16 v[4:7], v[204:207], v[196:199], v[4:7]
	v_mfma_f32_16x16x32_bf16 v[0:3], v[212:215], v[196:199], v[0:3]
	s_add_i32 s79, 0, 0x18000
	v_add_u32_e32 v155, s79, v150
	s_barrier
	ds_read_b128 v[146:149], v155
	ds_read_b128 v[156:159], v155 offset:1024
	ds_read_b128 v[160:163], v155 offset:2048
	ds_read_b128 v[164:167], v155 offset:3072
	s_add_u32 s56, s56, 0x80000
	s_addc_u32 s57, s57, 0
	s_mov_b32 m0, s63
	ds_read_b128 v[168:171], v153 offset:32768
	ds_read_b128 v[172:175], v153 offset:33792
	ds_read_b128 v[176:179], v153 offset:34816
	ds_read_b128 v[180:183], v153 offset:35840
	ds_read_b128 v[184:187], v153 offset:36864
	ds_read_b128 v[188:191], v153 offset:37888
	ds_read_b128 v[192:195], v153 offset:38912
	ds_read_b128 v[196:199], v153 offset:39936
	global_load_lds_dwordx4 v128, s[56:57]
	s_mov_b32 m0, s64
	s_nop 0
	global_load_lds_dwordx4 v132, s[56:57]
	s_waitcnt lgkmcnt(8)
	s_barrier
	s_waitcnt lgkmcnt(0)
	v_mfma_f32_16x16x32_bf16 v[124:127], v[146:149], v[168:171], v[124:127]
	v_mfma_f32_16x16x32_bf16 v[120:123], v[160:163], v[168:171], v[120:123]
	v_mfma_f32_16x16x32_bf16 v[108:111], v[146:149], v[176:179], v[108:111]
	v_mfma_f32_16x16x32_bf16 v[104:107], v[160:163], v[176:179], v[104:107]
	v_mfma_f32_16x16x32_bf16 v[92:95], v[146:149], v[184:187], v[92:95]
	v_mfma_f32_16x16x32_bf16 v[88:91], v[160:163], v[184:187], v[88:91]
	v_mfma_f32_16x16x32_bf16 v[76:79], v[146:149], v[192:195], v[76:79]
	v_mfma_f32_16x16x32_bf16 v[72:75], v[160:163], v[192:195], v[72:75]
	v_mfma_f32_16x16x32_bf16 v[124:127], v[156:159], v[172:175], v[124:127]
	v_mfma_f32_16x16x32_bf16 v[120:123], v[164:167], v[172:175], v[120:123]
	v_mfma_f32_16x16x32_bf16 v[108:111], v[156:159], v[180:183], v[108:111]
	v_mfma_f32_16x16x32_bf16 v[104:107], v[164:167], v[180:183], v[104:107]
	v_mfma_f32_16x16x32_bf16 v[92:95], v[156:159], v[188:191], v[92:95]
	v_mfma_f32_16x16x32_bf16 v[88:91], v[164:167], v[188:191], v[88:91]
	v_mfma_f32_16x16x32_bf16 v[76:79], v[156:159], v[196:199], v[76:79]
	v_mfma_f32_16x16x32_bf16 v[72:75], v[164:167], v[196:199], v[72:75]
	s_barrier
	s_add_i32 s56, 0, 0x1c000
	s_add_i32 s57, s79, s60
	v_add_u32_e32 v155, s56, v150
	s_mov_b32 m0, s57
	ds_read_b128 v[200:203], v155
	ds_read_b128 v[204:207], v155 offset:1024
	ds_read_b128 v[208:211], v155 offset:2048
	ds_read_b128 v[212:215], v155 offset:3072
	global_load_lds_dwordx4 v130, s[98:99]
	s_add_i32 m0, s57, 0x2000
	s_nop 0
	global_load_lds_dwordx4 v134, s[98:99]
	s_barrier
	s_waitcnt lgkmcnt(0)
	v_mfma_f32_16x16x32_bf16 v[116:119], v[200:203], v[168:171], v[116:119]
	v_mfma_f32_16x16x32_bf16 v[112:115], v[208:211], v[168:171], v[112:115]
	v_mfma_f32_16x16x32_bf16 v[100:103], v[200:203], v[176:179], v[100:103]
	v_mfma_f32_16x16x32_bf16 v[96:99], v[208:211], v[176:179], v[96:99]
	v_mfma_f32_16x16x32_bf16 v[84:87], v[200:203], v[184:187], v[84:87]
	v_mfma_f32_16x16x32_bf16 v[80:83], v[208:211], v[184:187], v[80:83]
	v_mfma_f32_16x16x32_bf16 v[68:71], v[200:203], v[192:195], v[68:71]
	v_mfma_f32_16x16x32_bf16 v[64:67], v[208:211], v[192:195], v[64:67]
	v_mfma_f32_16x16x32_bf16 v[116:119], v[204:207], v[172:175], v[116:119]
	v_mfma_f32_16x16x32_bf16 v[112:115], v[212:215], v[172:175], v[112:115]
	v_mfma_f32_16x16x32_bf16 v[100:103], v[204:207], v[180:183], v[100:103]
	v_mfma_f32_16x16x32_bf16 v[96:99], v[212:215], v[180:183], v[96:99]
	v_mfma_f32_16x16x32_bf16 v[84:87], v[204:207], v[188:191], v[84:87]
	v_mfma_f32_16x16x32_bf16 v[80:83], v[212:215], v[188:191], v[80:83]
	v_mfma_f32_16x16x32_bf16 v[68:71], v[204:207], v[196:199], v[68:71]
	v_mfma_f32_16x16x32_bf16 v[64:67], v[212:215], v[196:199], v[64:67]
	s_mov_b32 m0, s66
	s_barrier
	ds_read_b128 v[168:171], v153 offset:49152
	ds_read_b128 v[172:175], v153 offset:50176
	ds_read_b128 v[176:179], v153 offset:51200
	ds_read_b128 v[180:183], v153 offset:52224
	ds_read_b128 v[184:187], v153 offset:53248
	ds_read_b128 v[188:191], v153 offset:54272
	ds_read_b128 v[192:195], v153 offset:55296
	ds_read_b128 v[196:199], v153 offset:56320
	global_load_lds_dwordx4 v128, s[100:101]
	s_mov_b32 m0, s67
	s_nop 0
	global_load_lds_dwordx4 v132, s[100:101]
	s_barrier
	s_waitcnt lgkmcnt(0)
	v_mfma_f32_16x16x32_bf16 v[60:63], v[146:149], v[168:171], v[60:63]
	v_mfma_f32_16x16x32_bf16 v[56:59], v[160:163], v[168:171], v[56:59]
	v_mfma_f32_16x16x32_bf16 v[44:47], v[146:149], v[176:179], v[44:47]
	v_mfma_f32_16x16x32_bf16 v[40:43], v[160:163], v[176:179], v[40:43]
	v_mfma_f32_16x16x32_bf16 v[28:31], v[146:149], v[184:187], v[28:31]
	v_mfma_f32_16x16x32_bf16 v[24:27], v[160:163], v[184:187], v[24:27]
	v_mfma_f32_16x16x32_bf16 v[12:15], v[146:149], v[192:195], v[12:15]
	v_mfma_f32_16x16x32_bf16 v[8:11], v[160:163], v[192:195], v[8:11]
	v_mfma_f32_16x16x32_bf16 v[60:63], v[156:159], v[172:175], v[60:63]
	v_mfma_f32_16x16x32_bf16 v[56:59], v[164:167], v[172:175], v[56:59]
	v_mfma_f32_16x16x32_bf16 v[44:47], v[156:159], v[180:183], v[44:47]
	v_mfma_f32_16x16x32_bf16 v[40:43], v[164:167], v[180:183], v[40:43]
	v_mfma_f32_16x16x32_bf16 v[28:31], v[156:159], v[188:191], v[28:31]
	v_mfma_f32_16x16x32_bf16 v[24:27], v[164:167], v[188:191], v[24:27]
	v_mfma_f32_16x16x32_bf16 v[12:15], v[156:159], v[196:199], v[12:15]
	v_mfma_f32_16x16x32_bf16 v[8:11], v[164:167], v[196:199], v[8:11]
	s_barrier
	s_add_u32 s54, s54, 0x80080
	s_addc_u32 s55, s55, 0
	s_add_i32 s56, s56, s60
	s_mov_b32 m0, s56
	s_nop 0
	global_load_lds_dwordx4 v130, s[54:55]
	s_add_i32 m0, s56, 0x2000
	s_nop 0
	global_load_lds_dwordx4 v134, s[54:55]
	s_waitcnt vmcnt(6)
	s_barrier
	v_mfma_f32_16x16x32_bf16 v[52:55], v[200:203], v[168:171], v[52:55]
	v_mfma_f32_16x16x32_bf16 v[48:51], v[208:211], v[168:171], v[48:51]
	v_mfma_f32_16x16x32_bf16 v[36:39], v[200:203], v[176:179], v[36:39]
	v_mfma_f32_16x16x32_bf16 v[32:35], v[208:211], v[176:179], v[32:35]
	v_mfma_f32_16x16x32_bf16 v[20:23], v[200:203], v[184:187], v[20:23]
	v_mfma_f32_16x16x32_bf16 v[16:19], v[208:211], v[184:187], v[16:19]
	v_mfma_f32_16x16x32_bf16 v[4:7], v[200:203], v[192:195], v[4:7]
	v_mfma_f32_16x16x32_bf16 v[0:3], v[208:211], v[192:195], v[0:3]
	v_mfma_f32_16x16x32_bf16 v[52:55], v[204:207], v[172:175], v[52:55]
	v_mfma_f32_16x16x32_bf16 v[48:51], v[212:215], v[172:175], v[48:51]
	v_mfma_f32_16x16x32_bf16 v[36:39], v[204:207], v[180:183], v[36:39]
	v_mfma_f32_16x16x32_bf16 v[32:35], v[212:215], v[180:183], v[32:35]
	v_mfma_f32_16x16x32_bf16 v[20:23], v[204:207], v[188:191], v[20:23]
	v_mfma_f32_16x16x32_bf16 v[16:19], v[212:215], v[188:191], v[16:19]
	v_mfma_f32_16x16x32_bf16 v[4:7], v[204:207], v[196:199], v[4:7]
	v_mfma_f32_16x16x32_bf16 v[0:3], v[212:215], v[196:199], v[0:3]
	s_add_i32 s78, s78, 2
	s_add_u32 s36, s36, 0x100
	s_addc_u32 s37, s37, 0
	s_add_u32 s29, s29, 0x100
	s_addc_u32 s35, s35, 0
	s_cmp_gt_u32 s78, 29
	s_barrier
	s_cbranch_scc0 .LBB0_330
.LBB0_330:
	ds_read_b128 v[146:149], v152
	ds_read_b128 v[156:159], v152 offset:1024
	ds_read_b128 v[160:163], v152 offset:2048
	ds_read_b128 v[164:167], v152 offset:3072
	s_add_u32 s54, s36, 0xfff80080
	s_addc_u32 s55, s37, -1
	s_cmp_eq_u32 s78, 28
	s_cselect_b32 s57, s1, s55
	s_cselect_b32 s56, s15, s54
	s_cselect_b32 s55, s13, s35
	s_cselect_b32 s54, s28, s29
	s_add_i32 m0, s61, 0xc000
	ds_read_b128 v[168:171], v153
	ds_read_b128 v[172:175], v153 offset:1024
	ds_read_b128 v[176:179], v153 offset:2048
	ds_read_b128 v[180:183], v153 offset:3072
	ds_read_b128 v[184:187], v153 offset:4096
	ds_read_b128 v[188:191], v153 offset:5120
	ds_read_b128 v[192:195], v153 offset:6144
	ds_read_b128 v[196:199], v153 offset:7168
	global_load_lds_dwordx4 v138, s[36:37]
	s_add_i32 m0, s61, 0xe000
	s_nop 0
	global_load_lds_dwordx4 v140, s[36:37]
	s_waitcnt lgkmcnt(8)
	s_barrier
	s_waitcnt lgkmcnt(0)
	v_mfma_f32_16x16x32_bf16 v[124:127], v[146:149], v[168:171], v[124:127]
	v_mfma_f32_16x16x32_bf16 v[120:123], v[160:163], v[168:171], v[120:123]
	v_mfma_f32_16x16x32_bf16 v[108:111], v[146:149], v[176:179], v[108:111]
	v_mfma_f32_16x16x32_bf16 v[104:107], v[160:163], v[176:179], v[104:107]
	v_mfma_f32_16x16x32_bf16 v[92:95], v[146:149], v[184:187], v[92:95]
	v_mfma_f32_16x16x32_bf16 v[88:91], v[160:163], v[184:187], v[88:91]
	v_mfma_f32_16x16x32_bf16 v[76:79], v[146:149], v[192:195], v[76:79]
	v_mfma_f32_16x16x32_bf16 v[72:75], v[160:163], v[192:195], v[72:75]
	v_mfma_f32_16x16x32_bf16 v[124:127], v[156:159], v[172:175], v[124:127]
	v_mfma_f32_16x16x32_bf16 v[120:123], v[164:167], v[172:175], v[120:123]
	v_mfma_f32_16x16x32_bf16 v[108:111], v[156:159], v[180:183], v[108:111]
	v_mfma_f32_16x16x32_bf16 v[104:107], v[164:167], v[180:183], v[104:107]
	v_mfma_f32_16x16x32_bf16 v[92:95], v[156:159], v[188:191], v[92:95]
	v_mfma_f32_16x16x32_bf16 v[88:91], v[164:167], v[188:191], v[88:91]
	v_mfma_f32_16x16x32_bf16 v[76:79], v[156:159], v[196:199], v[76:79]
	v_mfma_f32_16x16x32_bf16 v[72:75], v[164:167], v[196:199], v[72:75]
	s_barrier
	s_add_i32 s79, s75, s60
	s_add_u32 s98, s54, s10
	s_addc_u32 s99, s55, s11
	s_mov_b32 m0, s79
	ds_read_b128 v[200:203], v154
	ds_read_b128 v[204:207], v154 offset:1024
	ds_read_b128 v[208:211], v154 offset:2048
	ds_read_b128 v[212:215], v154 offset:3072
	global_load_lds_dwordx4 v130, s[54:55]
	s_add_i32 m0, s79, 0x2000
	s_nop 0
	global_load_lds_dwordx4 v134, s[54:55]
	s_barrier
	s_waitcnt lgkmcnt(0)
	v_mfma_f32_16x16x32_bf16 v[116:119], v[200:203], v[168:171], v[116:119]
	v_mfma_f32_16x16x32_bf16 v[112:115], v[208:211], v[168:171], v[112:115]
	v_mfma_f32_16x16x32_bf16 v[100:103], v[200:203], v[176:179], v[100:103]
	v_mfma_f32_16x16x32_bf16 v[96:99], v[208:211], v[176:179], v[96:99]
	v_mfma_f32_16x16x32_bf16 v[84:87], v[200:203], v[184:187], v[84:87]
	v_mfma_f32_16x16x32_bf16 v[80:83], v[208:211], v[184:187], v[80:83]
	v_mfma_f32_16x16x32_bf16 v[68:71], v[200:203], v[192:195], v[68:71]
	v_mfma_f32_16x16x32_bf16 v[64:67], v[208:211], v[192:195], v[64:67]
	v_mfma_f32_16x16x32_bf16 v[116:119], v[204:207], v[172:175], v[116:119]
	v_mfma_f32_16x16x32_bf16 v[112:115], v[212:215], v[172:175], v[112:115]
	v_mfma_f32_16x16x32_bf16 v[100:103], v[204:207], v[180:183], v[100:103]
	v_mfma_f32_16x16x32_bf16 v[96:99], v[212:215], v[180:183], v[96:99]
	v_mfma_f32_16x16x32_bf16 v[84:87], v[204:207], v[188:191], v[84:87]
	v_mfma_f32_16x16x32_bf16 v[80:83], v[212:215], v[188:191], v[80:83]
	v_mfma_f32_16x16x32_bf16 v[68:71], v[204:207], v[196:199], v[68:71]
	v_mfma_f32_16x16x32_bf16 v[64:67], v[212:215], v[196:199], v[64:67]
	s_mov_b32 m0, s61
	s_add_u32 s100, s56, s10
	s_addc_u32 s101, s57, s11
	s_barrier
	ds_read_b128 v[168:171], v153 offset:16384
	ds_read_b128 v[172:175], v153 offset:17408
	ds_read_b128 v[176:179], v153 offset:18432
	ds_read_b128 v[180:183], v153 offset:19456
	ds_read_b128 v[184:187], v153 offset:20480
	ds_read_b128 v[188:191], v153 offset:21504
	ds_read_b128 v[192:195], v153 offset:22528
	ds_read_b128 v[196:199], v153 offset:23552
	global_load_lds_dwordx4 v128, s[56:57]
	s_mov_b32 m0, s62
	s_nop 0
	global_load_lds_dwordx4 v132, s[56:57]
	s_barrier
	s_waitcnt lgkmcnt(0)
	v_mfma_f32_16x16x32_bf16 v[60:63], v[146:149], v[168:171], v[60:63]
	v_mfma_f32_16x16x32_bf16 v[56:59], v[160:163], v[168:171], v[56:59]
	v_mfma_f32_16x16x32_bf16 v[44:47], v[146:149], v[176:179], v[44:47]
	v_mfma_f32_16x16x32_bf16 v[40:43], v[160:163], v[176:179], v[40:43]
	v_mfma_f32_16x16x32_bf16 v[28:31], v[146:149], v[184:187], v[28:31]
	v_mfma_f32_16x16x32_bf16 v[24:27], v[160:163], v[184:187], v[24:27]
	v_mfma_f32_16x16x32_bf16 v[12:15], v[146:149], v[192:195], v[12:15]
	v_mfma_f32_16x16x32_bf16 v[8:11], v[160:163], v[192:195], v[8:11]
	v_mfma_f32_16x16x32_bf16 v[60:63], v[156:159], v[172:175], v[60:63]
	v_mfma_f32_16x16x32_bf16 v[56:59], v[164:167], v[172:175], v[56:59]
	v_mfma_f32_16x16x32_bf16 v[44:47], v[156:159], v[180:183], v[44:47]
	v_mfma_f32_16x16x32_bf16 v[40:43], v[164:167], v[180:183], v[40:43]
	v_mfma_f32_16x16x32_bf16 v[28:31], v[156:159], v[188:191], v[28:31]
	v_mfma_f32_16x16x32_bf16 v[24:27], v[164:167], v[188:191], v[24:27]
	v_mfma_f32_16x16x32_bf16 v[12:15], v[156:159], v[196:199], v[12:15]
	v_mfma_f32_16x16x32_bf16 v[8:11], v[164:167], v[196:199], v[8:11]
	s_barrier
	s_add_u32 s80, s54, 0x80000
	s_addc_u32 s81, s55, 0
	s_add_i32 s79, s76, s60
	s_mov_b32 m0, s79
	s_nop 0
	global_load_lds_dwordx4 v130, s[80:81]
	s_add_i32 m0, s79, 0x2000
	s_nop 0
	global_load_lds_dwordx4 v134, s[80:81]
	s_waitcnt vmcnt(6)
	s_barrier
	v_mfma_f32_16x16x32_bf16 v[52:55], v[200:203], v[168:171], v[52:55]
	v_mfma_f32_16x16x32_bf16 v[48:51], v[208:211], v[168:171], v[48:51]
	v_mfma_f32_16x16x32_bf16 v[36:39], v[200:203], v[176:179], v[36:39]
	v_mfma_f32_16x16x32_bf16 v[32:35], v[208:211], v[176:179], v[32:35]
	v_mfma_f32_16x16x32_bf16 v[20:23], v[200:203], v[184:187], v[20:23]
	v_mfma_f32_16x16x32_bf16 v[16:19], v[208:211], v[184:187], v[16:19]
	v_mfma_f32_16x16x32_bf16 v[4:7], v[200:203], v[192:195], v[4:7]
	v_mfma_f32_16x16x32_bf16 v[0:3], v[208:211], v[192:195], v[0:3]
	v_mfma_f32_16x16x32_bf16 v[52:55], v[204:207], v[172:175], v[52:55]
	v_mfma_f32_16x16x32_bf16 v[48:51], v[212:215], v[172:175], v[48:51]
	v_mfma_f32_16x16x32_bf16 v[36:39], v[204:207], v[180:183], v[36:39]
	v_mfma_f32_16x16x32_bf16 v[32:35], v[212:215], v[180:183], v[32:35]
	v_mfma_f32_16x16x32_bf16 v[20:23], v[204:207], v[188:191], v[20:23]
	v_mfma_f32_16x16x32_bf16 v[16:19], v[212:215], v[188:191], v[16:19]
	v_mfma_f32_16x16x32_bf16 v[4:7], v[204:207], v[196:199], v[4:7]
	v_mfma_f32_16x16x32_bf16 v[0:3], v[212:215], v[196:199], v[0:3]
	s_add_i32 s79, 0, 0x18000
	v_add_u32_e32 v155, s79, v150
	s_barrier
	ds_read_b128 v[146:149], v155
	ds_read_b128 v[156:159], v155 offset:1024
	ds_read_b128 v[160:163], v155 offset:2048
	ds_read_b128 v[164:167], v155 offset:3072
	s_add_u32 s56, s56, 0x80000
	s_addc_u32 s57, s57, 0
	s_mov_b32 m0, s63
	ds_read_b128 v[168:171], v153 offset:32768
	ds_read_b128 v[172:175], v153 offset:33792
	ds_read_b128 v[176:179], v153 offset:34816
	ds_read_b128 v[180:183], v153 offset:35840
	ds_read_b128 v[184:187], v153 offset:36864
	ds_read_b128 v[188:191], v153 offset:37888
	ds_read_b128 v[192:195], v153 offset:38912
	ds_read_b128 v[196:199], v153 offset:39936
	global_load_lds_dwordx4 v128, s[56:57]
	s_mov_b32 m0, s64
	s_nop 0
	global_load_lds_dwordx4 v132, s[56:57]
	s_waitcnt lgkmcnt(8)
	s_barrier
	s_waitcnt lgkmcnt(0)
	v_mfma_f32_16x16x32_bf16 v[124:127], v[146:149], v[168:171], v[124:127]
	v_mfma_f32_16x16x32_bf16 v[120:123], v[160:163], v[168:171], v[120:123]
	v_mfma_f32_16x16x32_bf16 v[108:111], v[146:149], v[176:179], v[108:111]
	v_mfma_f32_16x16x32_bf16 v[104:107], v[160:163], v[176:179], v[104:107]
	v_mfma_f32_16x16x32_bf16 v[92:95], v[146:149], v[184:187], v[92:95]
	v_mfma_f32_16x16x32_bf16 v[88:91], v[160:163], v[184:187], v[88:91]
	v_mfma_f32_16x16x32_bf16 v[76:79], v[146:149], v[192:195], v[76:79]
	v_mfma_f32_16x16x32_bf16 v[72:75], v[160:163], v[192:195], v[72:75]
	v_mfma_f32_16x16x32_bf16 v[124:127], v[156:159], v[172:175], v[124:127]
	v_mfma_f32_16x16x32_bf16 v[120:123], v[164:167], v[172:175], v[120:123]
	v_mfma_f32_16x16x32_bf16 v[108:111], v[156:159], v[180:183], v[108:111]
	v_mfma_f32_16x16x32_bf16 v[104:107], v[164:167], v[180:183], v[104:107]
	v_mfma_f32_16x16x32_bf16 v[92:95], v[156:159], v[188:191], v[92:95]
	v_mfma_f32_16x16x32_bf16 v[88:91], v[164:167], v[188:191], v[88:91]
	v_mfma_f32_16x16x32_bf16 v[76:79], v[156:159], v[196:199], v[76:79]
	v_mfma_f32_16x16x32_bf16 v[72:75], v[164:167], v[196:199], v[72:75]
	s_barrier
	s_add_i32 s56, 0, 0x1c000
	s_add_i32 s57, s79, s60
	v_add_u32_e32 v155, s56, v150
	s_mov_b32 m0, s57
	ds_read_b128 v[200:203], v155
	ds_read_b128 v[204:207], v155 offset:1024
	ds_read_b128 v[208:211], v155 offset:2048
	ds_read_b128 v[212:215], v155 offset:3072
	global_load_lds_dwordx4 v130, s[98:99]
	s_add_i32 m0, s57, 0x2000
	s_nop 0
	global_load_lds_dwordx4 v134, s[98:99]
	s_barrier
	s_waitcnt lgkmcnt(0)
	v_mfma_f32_16x16x32_bf16 v[116:119], v[200:203], v[168:171], v[116:119]
	v_mfma_f32_16x16x32_bf16 v[112:115], v[208:211], v[168:171], v[112:115]
	v_mfma_f32_16x16x32_bf16 v[100:103], v[200:203], v[176:179], v[100:103]
	v_mfma_f32_16x16x32_bf16 v[96:99], v[208:211], v[176:179], v[96:99]
	v_mfma_f32_16x16x32_bf16 v[84:87], v[200:203], v[184:187], v[84:87]
	v_mfma_f32_16x16x32_bf16 v[80:83], v[208:211], v[184:187], v[80:83]
	v_mfma_f32_16x16x32_bf16 v[68:71], v[200:203], v[192:195], v[68:71]
	v_mfma_f32_16x16x32_bf16 v[64:67], v[208:211], v[192:195], v[64:67]
	v_mfma_f32_16x16x32_bf16 v[116:119], v[204:207], v[172:175], v[116:119]
	v_mfma_f32_16x16x32_bf16 v[112:115], v[212:215], v[172:175], v[112:115]
	v_mfma_f32_16x16x32_bf16 v[100:103], v[204:207], v[180:183], v[100:103]
	v_mfma_f32_16x16x32_bf16 v[96:99], v[212:215], v[180:183], v[96:99]
	v_mfma_f32_16x16x32_bf16 v[84:87], v[204:207], v[188:191], v[84:87]
	v_mfma_f32_16x16x32_bf16 v[80:83], v[212:215], v[188:191], v[80:83]
	v_mfma_f32_16x16x32_bf16 v[68:71], v[204:207], v[196:199], v[68:71]
	v_mfma_f32_16x16x32_bf16 v[64:67], v[212:215], v[196:199], v[64:67]
	s_mov_b32 m0, s66
	s_barrier
	ds_read_b128 v[168:171], v153 offset:49152
	ds_read_b128 v[172:175], v153 offset:50176
	ds_read_b128 v[176:179], v153 offset:51200
	ds_read_b128 v[180:183], v153 offset:52224
	ds_read_b128 v[184:187], v153 offset:53248
	ds_read_b128 v[188:191], v153 offset:54272
	ds_read_b128 v[192:195], v153 offset:55296
	ds_read_b128 v[196:199], v153 offset:56320
	global_load_lds_dwordx4 v128, s[100:101]
	s_mov_b32 m0, s67
	s_nop 0
	global_load_lds_dwordx4 v132, s[100:101]
	s_barrier
	s_waitcnt lgkmcnt(0)
	v_mfma_f32_16x16x32_bf16 v[60:63], v[146:149], v[168:171], v[60:63]
	v_mfma_f32_16x16x32_bf16 v[56:59], v[160:163], v[168:171], v[56:59]
	v_mfma_f32_16x16x32_bf16 v[44:47], v[146:149], v[176:179], v[44:47]
	v_mfma_f32_16x16x32_bf16 v[40:43], v[160:163], v[176:179], v[40:43]
	v_mfma_f32_16x16x32_bf16 v[28:31], v[146:149], v[184:187], v[28:31]
	v_mfma_f32_16x16x32_bf16 v[24:27], v[160:163], v[184:187], v[24:27]
	v_mfma_f32_16x16x32_bf16 v[12:15], v[146:149], v[192:195], v[12:15]
	v_mfma_f32_16x16x32_bf16 v[8:11], v[160:163], v[192:195], v[8:11]
	v_mfma_f32_16x16x32_bf16 v[60:63], v[156:159], v[172:175], v[60:63]
	v_mfma_f32_16x16x32_bf16 v[56:59], v[164:167], v[172:175], v[56:59]
	v_mfma_f32_16x16x32_bf16 v[44:47], v[156:159], v[180:183], v[44:47]
	v_mfma_f32_16x16x32_bf16 v[40:43], v[164:167], v[180:183], v[40:43]
	v_mfma_f32_16x16x32_bf16 v[28:31], v[156:159], v[188:191], v[28:31]
	v_mfma_f32_16x16x32_bf16 v[24:27], v[164:167], v[188:191], v[24:27]
	v_mfma_f32_16x16x32_bf16 v[12:15], v[156:159], v[196:199], v[12:15]
	v_mfma_f32_16x16x32_bf16 v[8:11], v[164:167], v[196:199], v[8:11]
	s_barrier
	s_add_u32 s54, s54, 0x80080
	s_addc_u32 s55, s55, 0
	s_add_i32 s56, s56, s60
	s_mov_b32 m0, s56
	s_nop 0
	global_load_lds_dwordx4 v130, s[54:55]
	s_add_i32 m0, s56, 0x2000
	s_nop 0
	global_load_lds_dwordx4 v134, s[54:55]
	s_waitcnt vmcnt(6)
	s_barrier
	v_mfma_f32_16x16x32_bf16 v[52:55], v[200:203], v[168:171], v[52:55]
	v_mfma_f32_16x16x32_bf16 v[48:51], v[208:211], v[168:171], v[48:51]
	v_mfma_f32_16x16x32_bf16 v[36:39], v[200:203], v[176:179], v[36:39]
	v_mfma_f32_16x16x32_bf16 v[32:35], v[208:211], v[176:179], v[32:35]
	v_mfma_f32_16x16x32_bf16 v[20:23], v[200:203], v[184:187], v[20:23]
	v_mfma_f32_16x16x32_bf16 v[16:19], v[208:211], v[184:187], v[16:19]
	v_mfma_f32_16x16x32_bf16 v[4:7], v[200:203], v[192:195], v[4:7]
	v_mfma_f32_16x16x32_bf16 v[0:3], v[208:211], v[192:195], v[0:3]
	v_mfma_f32_16x16x32_bf16 v[52:55], v[204:207], v[172:175], v[52:55]
	v_mfma_f32_16x16x32_bf16 v[48:51], v[212:215], v[172:175], v[48:51]
	v_mfma_f32_16x16x32_bf16 v[36:39], v[204:207], v[180:183], v[36:39]
	v_mfma_f32_16x16x32_bf16 v[32:35], v[212:215], v[180:183], v[32:35]
	v_mfma_f32_16x16x32_bf16 v[20:23], v[204:207], v[188:191], v[20:23]
	v_mfma_f32_16x16x32_bf16 v[16:19], v[212:215], v[188:191], v[16:19]
	v_mfma_f32_16x16x32_bf16 v[4:7], v[204:207], v[196:199], v[4:7]
	v_mfma_f32_16x16x32_bf16 v[0:3], v[212:215], v[196:199], v[0:3]
	s_add_i32 s78, s78, 2
	s_add_u32 s36, s36, 0x100
	s_addc_u32 s37, s37, 0
	s_add_u32 s29, s29, 0x100
	s_addc_u32 s35, s35, 0
	s_cmp_gt_u32 s78, 29
	s_barrier
	s_cbranch_scc0 .LBB0_330
	s_cmp_gt_i32 s34, 3
	v_lshl_add_u32 v146, s0, 8, v145
	v_lshl_or_b32 v148, s34, 8, v151
	s_cselect_b64 s[34:35], -1, 0
	v_ashrrev_i32_e32 v147, 31, v146
	s_mov_b64 s[0:1], -1
	s_and_b64 vcc, exec, s[34:35]
	v_ashrrev_i32_e32 v149, 31, v148
	s_cbranch_vccz .LBB0_333
	v_and_b32_e32 v160, 63, v144
	v_lshrrev_b32_e32 v161, 6, v144
	v_lshlrev_b32_e32 v162, 10, v161
	v_add_u32_e32 v162, 0x20000, v162
	v_lshrrev_b32_e32 v163, 4, v160
	v_and_b32_e32 v164, 15, v160
	v_lshlrev_b32_e32 v165, 8, v163
	v_lshl_add_u32 v165, v164, 1, v165
	v_add_u32_e32 v165, v162, v165
	v_lshl_add_u32 v166, v160, 4, v162
	v_sub_u32_e32 v167, v148, v151
	v_and_b32_e32 v168, 0x60, v151
	v_add_u32_e32 v167, v167, v168
	v_lshl_add_u32 v167, v163, 3, v167
	v_bfe_u32 v168, v160, 2, 2
	v_add_u32_e32 v167, v167, v168
	v_sub_u32_e32 v168, v146, v145
	v_and_b32_e32 v169, 0x40, v145
	v_add_u32_e32 v168, v168, v169
	v_and_b32_e32 v169, 3, v160
	v_lshl_add_u32 v168, v169, 3, v168
	v_mov_b32_e32 v170, v167
	v_mov_b32_e32 v171, 0
	v_lshlrev_b64 v[170:171], 15, v[170:171]
	v_lshl_add_u64 v[170:171], s[8:9], 0, v[170:171]
	v_lshlrev_b32_e32 v172, 1, v168
	v_mov_b32_e32 v173, 0
	v_lshl_add_u64 v[170:171], v[170:171], 0, v[172:173]
	s_mov_b32 s28, 0xfe000000
	s_mov_b32 s29, -1
	v_lshl_add_u64 v[170:171], v[170:171], 0, s[28:29]
	s_mov_b32 s29, 0
	v_cvt_pk_bf16_f32 v190, v124, v125
	v_cvt_pk_bf16_f32 v191, v126, v127
	v_lshrrev_b32_e32 v192, 16, v190
	v_lshrrev_b32_e32 v193, 16, v191
	ds_write_b16 v165, v190 offset:0
	ds_write_b16 v165, v192 offset:64
	ds_write_b16 v165, v191 offset:128
	ds_write_b16 v165, v193 offset:192
	v_cvt_pk_bf16_f32 v198, v108, v109
	v_cvt_pk_bf16_f32 v199, v110, v111
	v_lshrrev_b32_e32 v200, 16, v198
	v_lshrrev_b32_e32 v201, 16, v199
	ds_write_b16 v165, v198 offset:32
	ds_write_b16 v165, v200 offset:96
	ds_write_b16 v165, v199 offset:160
	ds_write_b16 v165, v201 offset:224
	ds_read_b128 v[180:183], v166
	s_waitcnt lgkmcnt(0)
	global_store_dwordx4 v[170:171], v[180:183], off
	v_cvt_pk_bf16_f32 v194, v92, v93
	v_cvt_pk_bf16_f32 v195, v94, v95
	v_lshrrev_b32_e32 v196, 16, v194
	v_lshrrev_b32_e32 v197, 16, v195
	ds_write_b16 v165, v194 offset:0
	ds_write_b16 v165, v196 offset:64
	ds_write_b16 v165, v195 offset:128
	ds_write_b16 v165, v197 offset:192
	v_cvt_pk_bf16_f32 v202, v76, v77
	v_cvt_pk_bf16_f32 v203, v78, v79
	v_lshrrev_b32_e32 v204, 16, v202
	v_lshrrev_b32_e32 v205, 16, v203
	ds_write_b16 v165, v202 offset:32
	ds_write_b16 v165, v204 offset:96
	ds_write_b16 v165, v203 offset:160
	ds_write_b16 v165, v205 offset:224
	ds_read_b128 v[184:187], v166
	s_waitcnt lgkmcnt(0)
	global_store_dwordx4 v[170:171], v[184:187], off offset:64
	v_cvt_pk_bf16_f32 v190, v60, v61
	v_cvt_pk_bf16_f32 v191, v62, v63
	v_lshrrev_b32_e32 v192, 16, v190
	v_lshrrev_b32_e32 v193, 16, v191
	ds_write_b16 v165, v190 offset:0
	ds_write_b16 v165, v192 offset:64
	ds_write_b16 v165, v191 offset:128
	ds_write_b16 v165, v193 offset:192
	v_cvt_pk_bf16_f32 v198, v44, v45
	v_cvt_pk_bf16_f32 v199, v46, v47
	v_lshrrev_b32_e32 v200, 16, v198
	v_lshrrev_b32_e32 v201, 16, v199
	ds_write_b16 v165, v198 offset:32
	ds_write_b16 v165, v200 offset:96
	ds_write_b16 v165, v199 offset:160
	ds_write_b16 v165, v201 offset:224
	ds_read_b128 v[180:183], v166
	s_waitcnt lgkmcnt(0)
	global_store_dwordx4 v[170:171], v[180:183], off offset:256
	v_cvt_pk_bf16_f32 v194, v28, v29
	v_cvt_pk_bf16_f32 v195, v30, v31
	v_lshrrev_b32_e32 v196, 16, v194
	v_lshrrev_b32_e32 v197, 16, v195
	ds_write_b16 v165, v194 offset:0
	ds_write_b16 v165, v196 offset:64
	ds_write_b16 v165, v195 offset:128
	ds_write_b16 v165, v197 offset:192
	v_cvt_pk_bf16_f32 v202, v12, v13
	v_cvt_pk_bf16_f32 v203, v14, v15
	v_lshrrev_b32_e32 v204, 16, v202
	v_lshrrev_b32_e32 v205, 16, v203
	ds_write_b16 v165, v202 offset:32
	ds_write_b16 v165, v204 offset:96
	ds_write_b16 v165, v203 offset:160
	ds_write_b16 v165, v205 offset:224
	ds_read_b128 v[184:187], v166
	s_waitcnt lgkmcnt(0)
	global_store_dwordx4 v[170:171], v[184:187], off offset:320
	s_mov_b32 s28, 0x20000
	v_lshl_add_u64 v[174:175], v[170:171], 0, s[28:29]
	v_cvt_pk_bf16_f32 v190, v120, v121
	v_cvt_pk_bf16_f32 v191, v122, v123
	v_lshrrev_b32_e32 v192, 16, v190
	v_lshrrev_b32_e32 v193, 16, v191
	ds_write_b16 v165, v190 offset:0
	ds_write_b16 v165, v192 offset:64
	ds_write_b16 v165, v191 offset:128
	ds_write_b16 v165, v193 offset:192
	v_cvt_pk_bf16_f32 v198, v104, v105
	v_cvt_pk_bf16_f32 v199, v106, v107
	v_lshrrev_b32_e32 v200, 16, v198
	v_lshrrev_b32_e32 v201, 16, v199
	ds_write_b16 v165, v198 offset:32
	ds_write_b16 v165, v200 offset:96
	ds_write_b16 v165, v199 offset:160
	ds_write_b16 v165, v201 offset:224
	ds_read_b128 v[180:183], v166
	s_waitcnt lgkmcnt(0)
	global_store_dwordx4 v[174:175], v[180:183], off
	v_cvt_pk_bf16_f32 v194, v88, v89
	v_cvt_pk_bf16_f32 v195, v90, v91
	v_lshrrev_b32_e32 v196, 16, v194
	v_lshrrev_b32_e32 v197, 16, v195
	ds_write_b16 v165, v194 offset:0
	ds_write_b16 v165, v196 offset:64
	ds_write_b16 v165, v195 offset:128
	ds_write_b16 v165, v197 offset:192
	v_cvt_pk_bf16_f32 v202, v72, v73
	v_cvt_pk_bf16_f32 v203, v74, v75
	v_lshrrev_b32_e32 v204, 16, v202
	v_lshrrev_b32_e32 v205, 16, v203
	ds_write_b16 v165, v202 offset:32
	ds_write_b16 v165, v204 offset:96
	ds_write_b16 v165, v203 offset:160
	ds_write_b16 v165, v205 offset:224
	ds_read_b128 v[184:187], v166
	s_waitcnt lgkmcnt(0)
	global_store_dwordx4 v[174:175], v[184:187], off offset:64
	v_cvt_pk_bf16_f32 v190, v56, v57
	v_cvt_pk_bf16_f32 v191, v58, v59
	v_lshrrev_b32_e32 v192, 16, v190
	v_lshrrev_b32_e32 v193, 16, v191
	ds_write_b16 v165, v190 offset:0
	ds_write_b16 v165, v192 offset:64
	ds_write_b16 v165, v191 offset:128
	ds_write_b16 v165, v193 offset:192
	v_cvt_pk_bf16_f32 v198, v40, v41
	v_cvt_pk_bf16_f32 v199, v42, v43
	v_lshrrev_b32_e32 v200, 16, v198
	v_lshrrev_b32_e32 v201, 16, v199
	ds_write_b16 v165, v198 offset:32
	ds_write_b16 v165, v200 offset:96
	ds_write_b16 v165, v199 offset:160
	ds_write_b16 v165, v201 offset:224
	ds_read_b128 v[180:183], v166
	s_waitcnt lgkmcnt(0)
	global_store_dwordx4 v[174:175], v[180:183], off offset:256
	v_cvt_pk_bf16_f32 v194, v24, v25
	v_cvt_pk_bf16_f32 v195, v26, v27
	v_lshrrev_b32_e32 v196, 16, v194
	v_lshrrev_b32_e32 v197, 16, v195
	ds_write_b16 v165, v194 offset:0
	ds_write_b16 v165, v196 offset:64
	ds_write_b16 v165, v195 offset:128
	ds_write_b16 v165, v197 offset:192
	v_cvt_pk_bf16_f32 v202, v8, v9
	v_cvt_pk_bf16_f32 v203, v10, v11
	v_lshrrev_b32_e32 v204, 16, v202
	v_lshrrev_b32_e32 v205, 16, v203
	ds_write_b16 v165, v202 offset:32
	ds_write_b16 v165, v204 offset:96
	ds_write_b16 v165, v203 offset:160
	ds_write_b16 v165, v205 offset:224
	ds_read_b128 v[184:187], v166
	s_waitcnt lgkmcnt(0)
	global_store_dwordx4 v[174:175], v[184:187], off offset:320
	s_mov_b32 s28, 0x400000
	v_lshl_add_u64 v[174:175], v[170:171], 0, s[28:29]
	v_cvt_pk_bf16_f32 v190, v116, v117
	v_cvt_pk_bf16_f32 v191, v118, v119
	v_lshrrev_b32_e32 v192, 16, v190
	v_lshrrev_b32_e32 v193, 16, v191
	ds_write_b16 v165, v190 offset:0
	ds_write_b16 v165, v192 offset:64
	ds_write_b16 v165, v191 offset:128
	ds_write_b16 v165, v193 offset:192
	v_cvt_pk_bf16_f32 v198, v100, v101
	v_cvt_pk_bf16_f32 v199, v102, v103
	v_lshrrev_b32_e32 v200, 16, v198
	v_lshrrev_b32_e32 v201, 16, v199
	ds_write_b16 v165, v198 offset:32
	ds_write_b16 v165, v200 offset:96
	ds_write_b16 v165, v199 offset:160
	ds_write_b16 v165, v201 offset:224
	ds_read_b128 v[180:183], v166
	s_waitcnt lgkmcnt(0)
	global_store_dwordx4 v[174:175], v[180:183], off
	v_cvt_pk_bf16_f32 v194, v84, v85
	v_cvt_pk_bf16_f32 v195, v86, v87
	v_lshrrev_b32_e32 v196, 16, v194
	v_lshrrev_b32_e32 v197, 16, v195
	ds_write_b16 v165, v194 offset:0
	ds_write_b16 v165, v196 offset:64
	ds_write_b16 v165, v195 offset:128
	ds_write_b16 v165, v197 offset:192
	v_cvt_pk_bf16_f32 v202, v68, v69
	v_cvt_pk_bf16_f32 v203, v70, v71
	v_lshrrev_b32_e32 v204, 16, v202
	v_lshrrev_b32_e32 v205, 16, v203
	ds_write_b16 v165, v202 offset:32
	ds_write_b16 v165, v204 offset:96
	ds_write_b16 v165, v203 offset:160
	ds_write_b16 v165, v205 offset:224
	ds_read_b128 v[184:187], v166
	s_waitcnt lgkmcnt(0)
	global_store_dwordx4 v[174:175], v[184:187], off offset:64
	v_cvt_pk_bf16_f32 v190, v52, v53
	v_cvt_pk_bf16_f32 v191, v54, v55
	v_lshrrev_b32_e32 v192, 16, v190
	v_lshrrev_b32_e32 v193, 16, v191
	ds_write_b16 v165, v190 offset:0
	ds_write_b16 v165, v192 offset:64
	ds_write_b16 v165, v191 offset:128
	ds_write_b16 v165, v193 offset:192
	v_cvt_pk_bf16_f32 v198, v36, v37
	v_cvt_pk_bf16_f32 v199, v38, v39
	v_lshrrev_b32_e32 v200, 16, v198
	v_lshrrev_b32_e32 v201, 16, v199
	ds_write_b16 v165, v198 offset:32
	ds_write_b16 v165, v200 offset:96
	ds_write_b16 v165, v199 offset:160
	ds_write_b16 v165, v201 offset:224
	ds_read_b128 v[180:183], v166
	s_waitcnt lgkmcnt(0)
	global_store_dwordx4 v[174:175], v[180:183], off offset:256
	v_cvt_pk_bf16_f32 v194, v20, v21
	v_cvt_pk_bf16_f32 v195, v22, v23
	v_lshrrev_b32_e32 v196, 16, v194
	v_lshrrev_b32_e32 v197, 16, v195
	ds_write_b16 v165, v194 offset:0
	ds_write_b16 v165, v196 offset:64
	ds_write_b16 v165, v195 offset:128
	ds_write_b16 v165, v197 offset:192
	v_cvt_pk_bf16_f32 v202, v4, v5
	v_cvt_pk_bf16_f32 v203, v6, v7
	v_lshrrev_b32_e32 v204, 16, v202
	v_lshrrev_b32_e32 v205, 16, v203
	ds_write_b16 v165, v202 offset:32
	ds_write_b16 v165, v204 offset:96
	ds_write_b16 v165, v203 offset:160
	ds_write_b16 v165, v205 offset:224
	ds_read_b128 v[184:187], v166
	s_waitcnt lgkmcnt(0)
	global_store_dwordx4 v[174:175], v[184:187], off offset:320
	s_mov_b32 s28, 0x420000
	v_lshl_add_u64 v[174:175], v[170:171], 0, s[28:29]
	v_cvt_pk_bf16_f32 v190, v112, v113
	v_cvt_pk_bf16_f32 v191, v114, v115
	v_lshrrev_b32_e32 v192, 16, v190
	v_lshrrev_b32_e32 v193, 16, v191
	ds_write_b16 v165, v190 offset:0
	ds_write_b16 v165, v192 offset:64
	ds_write_b16 v165, v191 offset:128
	ds_write_b16 v165, v193 offset:192
	v_cvt_pk_bf16_f32 v198, v96, v97
	v_cvt_pk_bf16_f32 v199, v98, v99
	v_lshrrev_b32_e32 v200, 16, v198
	v_lshrrev_b32_e32 v201, 16, v199
	ds_write_b16 v165, v198 offset:32
	ds_write_b16 v165, v200 offset:96
	ds_write_b16 v165, v199 offset:160
	ds_write_b16 v165, v201 offset:224
	ds_read_b128 v[180:183], v166
	s_waitcnt lgkmcnt(0)
	global_store_dwordx4 v[174:175], v[180:183], off
	v_cvt_pk_bf16_f32 v194, v80, v81
	v_cvt_pk_bf16_f32 v195, v82, v83
	v_lshrrev_b32_e32 v196, 16, v194
	v_lshrrev_b32_e32 v197, 16, v195
	ds_write_b16 v165, v194 offset:0
	ds_write_b16 v165, v196 offset:64
	ds_write_b16 v165, v195 offset:128
	ds_write_b16 v165, v197 offset:192
	v_cvt_pk_bf16_f32 v202, v64, v65
	v_cvt_pk_bf16_f32 v203, v66, v67
	v_lshrrev_b32_e32 v204, 16, v202
	v_lshrrev_b32_e32 v205, 16, v203
	ds_write_b16 v165, v202 offset:32
	ds_write_b16 v165, v204 offset:96
	ds_write_b16 v165, v203 offset:160
	ds_write_b16 v165, v205 offset:224
	ds_read_b128 v[184:187], v166
	s_waitcnt lgkmcnt(0)
	global_store_dwordx4 v[174:175], v[184:187], off offset:64
	v_cvt_pk_bf16_f32 v190, v48, v49
	v_cvt_pk_bf16_f32 v191, v50, v51
	v_lshrrev_b32_e32 v192, 16, v190
	v_lshrrev_b32_e32 v193, 16, v191
	ds_write_b16 v165, v190 offset:0
	ds_write_b16 v165, v192 offset:64
	ds_write_b16 v165, v191 offset:128
	ds_write_b16 v165, v193 offset:192
	v_cvt_pk_bf16_f32 v198, v32, v33
	v_cvt_pk_bf16_f32 v199, v34, v35
	v_lshrrev_b32_e32 v200, 16, v198
	v_lshrrev_b32_e32 v201, 16, v199
	ds_write_b16 v165, v198 offset:32
	ds_write_b16 v165, v200 offset:96
	ds_write_b16 v165, v199 offset:160
	ds_write_b16 v165, v201 offset:224
	ds_read_b128 v[180:183], v166
	s_waitcnt lgkmcnt(0)
	global_store_dwordx4 v[174:175], v[180:183], off offset:256
	v_cvt_pk_bf16_f32 v194, v16, v17
	v_cvt_pk_bf16_f32 v195, v18, v19
	v_lshrrev_b32_e32 v196, 16, v194
	v_lshrrev_b32_e32 v197, 16, v195
	ds_write_b16 v165, v194 offset:0
	ds_write_b16 v165, v196 offset:64
	ds_write_b16 v165, v195 offset:128
	ds_write_b16 v165, v197 offset:192
	v_cvt_pk_bf16_f32 v202, v0, v1
	v_cvt_pk_bf16_f32 v203, v2, v3
	v_lshrrev_b32_e32 v204, 16, v202
	v_lshrrev_b32_e32 v205, 16, v203
	ds_write_b16 v165, v202 offset:32
	ds_write_b16 v165, v204 offset:96
	ds_write_b16 v165, v203 offset:160
	ds_write_b16 v165, v205 offset:224
	ds_read_b128 v[184:187], v166
	s_waitcnt lgkmcnt(0)
	global_store_dwordx4 v[174:175], v[184:187], off offset:320
	s_branch .LBB0_319
	v_lshlrev_b64 v[156:157], 15, v[148:149]
	v_lshl_add_u64 v[156:157], s[8:9], 0, v[156:157]
	v_lshl_add_u64 v[156:157], v[146:147], 1, v[156:157]
	v_add_co_u32_e32 v158, vcc, 0xfe000000, v156
	v_cvt_pk_bf16_f32 v155, v124, s0
	s_nop 0
	v_addc_co_u32_e32 v159, vcc, -1, v157, vcc
	global_store_short v[158:159], v155, off
	v_add_co_u32_e32 v158, vcc, 0xfe020000, v156
	v_cvt_pk_bf16_f32 v155, v120, s0
	s_nop 0
	v_addc_co_u32_e32 v159, vcc, -1, v157, vcc
	global_store_short v[158:159], v155, off
	v_add_co_u32_e32 v158, vcc, 0xfe008000, v156
	v_cvt_pk_bf16_f32 v155, v125, s0
	s_nop 0
	v_addc_co_u32_e32 v159, vcc, -1, v157, vcc
	global_store_short v[158:159], v155, off
	v_add_co_u32_e32 v158, vcc, 0xfe028000, v156
	v_cvt_pk_bf16_f32 v155, v121, s0
	s_nop 0
	v_addc_co_u32_e32 v159, vcc, -1, v157, vcc
	global_store_short v[158:159], v155, off
	v_add_co_u32_e32 v158, vcc, 0xfe010000, v156
	v_cvt_pk_bf16_f32 v155, v126, s0
	s_nop 0
	v_addc_co_u32_e32 v159, vcc, -1, v157, vcc
	global_store_short v[158:159], v155, off
	v_add_co_u32_e32 v158, vcc, 0xfe030000, v156
	v_cvt_pk_bf16_f32 v155, v122, s0
	s_nop 0
	v_addc_co_u32_e32 v159, vcc, -1, v157, vcc
	global_store_short v[158:159], v155, off
	v_add_co_u32_e32 v158, vcc, 0xfe018000, v156
	v_cvt_pk_bf16_f32 v155, v127, s0
	s_nop 0
	v_addc_co_u32_e32 v159, vcc, -1, v157, vcc
	v_add_co_u32_e32 v156, vcc, 0xfe038000, v156
	global_store_short v[158:159], v155, off
	v_cvt_pk_bf16_f32 v155, v123, s0
	v_addc_co_u32_e32 v157, vcc, -1, v157, vcc
	global_store_short v[156:157], v155, off
	s_mov_b64 s[0:1], 0

.LBB0_931:
	s_ashr_i32 s15, s14, 31
	s_xor_b64 s[16:17], s[28:29], -1
	s_lshl_b64 s[18:19], s[14:15], 19
	s_add_u32 s18, s42, s18
	s_addc_u32 s19, s43, s19
	s_and_b64 s[30:31], s[28:29], exec
	s_cselect_b32 s15, s19, s37
	s_cselect_b32 s63, s18, s36
	s_ashr_i32 s13, s12, 31
	s_lshl_b64 s[30:31], s[12:13], 19
	s_add_u32 s30, s44, s30
	s_addc_u32 s31, s45, s31
	s_and_b64 s[28:29], s[28:29], exec
	s_cselect_b32 s13, s31, s39
	s_cselect_b32 s28, s30, s38
	s_add_u32 s36, s36, 0x40080
	s_addc_u32 s37, s37, 0
	s_add_u32 s29, s38, 0x100
	s_addc_u32 s64, s39, 0
	s_mov_b32 s65, -2
	ds_read_b128 v[128:131], v169
	ds_read_b128 v[132:135], v169 offset:1024
	ds_read_b128 v[136:139], v169 offset:2048
	ds_read_b128 v[140:143], v169 offset:3072
	s_add_u32 s38, s36, 0xfffc0080
	s_addc_u32 s39, s37, -1
	s_cmp_eq_u32 s65, 12
	s_cselect_b32 s41, s15, s39
	s_cselect_b32 s40, s63, s38
	s_cselect_b32 s39, s13, s64
	s_cselect_b32 s38, s28, s29
	s_add_i32 m0, s35, 0xc000
	ds_read_b128 v[160:163], v170
	ds_read_b128 v[172:175], v170 offset:1024
	ds_read_b128 v[176:179], v170 offset:2048
	ds_read_b128 v[180:183], v170 offset:3072
	ds_read_b128 v[184:187], v170 offset:4096
	ds_read_b128 v[188:191], v170 offset:5120
	ds_read_b128 v[192:195], v170 offset:6144
	ds_read_b128 v[196:199], v170 offset:7168
	global_load_lds_dwordx4 v154, s[36:37]
	s_add_i32 m0, s35, 0xe000
	s_nop 0
	global_load_lds_dwordx4 v156, s[36:37]
	s_waitcnt lgkmcnt(8)
	s_barrier
	s_waitcnt lgkmcnt(0)
	v_mfma_f32_16x16x32_bf16 v[124:127], v[128:131], v[160:163], 0
	v_mfma_f32_16x16x32_bf16 v[120:123], v[136:139], v[160:163], 0
	v_mfma_f32_16x16x32_bf16 v[116:119], v[128:131], v[176:179], 0
	v_mfma_f32_16x16x32_bf16 v[100:103], v[136:139], v[176:179], 0
	v_mfma_f32_16x16x32_bf16 v[92:95], v[128:131], v[184:187], 0
	v_mfma_f32_16x16x32_bf16 v[84:87], v[136:139], v[184:187], 0
	v_mfma_f32_16x16x32_bf16 v[76:79], v[128:131], v[192:195], 0
	v_mfma_f32_16x16x32_bf16 v[68:71], v[136:139], v[192:195], 0
	v_mfma_f32_16x16x32_bf16 v[124:127], v[132:135], v[172:175], v[124:127]
	v_mfma_f32_16x16x32_bf16 v[120:123], v[140:143], v[172:175], v[120:123]
	v_mfma_f32_16x16x32_bf16 v[116:119], v[132:135], v[180:183], v[116:119]
	v_mfma_f32_16x16x32_bf16 v[100:103], v[140:143], v[180:183], v[100:103]
	v_mfma_f32_16x16x32_bf16 v[92:95], v[132:135], v[188:191], v[92:95]
	v_mfma_f32_16x16x32_bf16 v[84:87], v[140:143], v[188:191], v[84:87]
	v_mfma_f32_16x16x32_bf16 v[76:79], v[132:135], v[196:199], v[76:79]
	v_mfma_f32_16x16x32_bf16 v[68:71], v[140:143], v[196:199], v[68:71]
	s_barrier
	s_add_i32 s66, s57, s46
	s_add_u32 s98, s38, s8
	s_addc_u32 s99, s39, s9
	s_mov_b32 m0, s66
	ds_read_b128 v[200:203], v171
	ds_read_b128 v[204:207], v171 offset:1024
	ds_read_b128 v[208:211], v171 offset:2048
	ds_read_b128 v[212:215], v171 offset:3072
	global_load_lds_dwordx4 v148, s[38:39]
	s_add_i32 m0, s66, 0x2000
	s_nop 0
	global_load_lds_dwordx4 v152, s[38:39]
	s_barrier
	s_waitcnt lgkmcnt(0)
	v_mfma_f32_16x16x32_bf16 v[112:115], v[200:203], v[160:163], 0
	v_mfma_f32_16x16x32_bf16 v[108:111], v[208:211], v[160:163], 0
	v_mfma_f32_16x16x32_bf16 v[104:107], v[200:203], v[176:179], 0
	v_mfma_f32_16x16x32_bf16 v[96:99], v[208:211], v[176:179], 0
	v_mfma_f32_16x16x32_bf16 v[88:91], v[200:203], v[184:187], 0
	v_mfma_f32_16x16x32_bf16 v[80:83], v[208:211], v[184:187], 0
	v_mfma_f32_16x16x32_bf16 v[72:75], v[200:203], v[192:195], 0
	v_mfma_f32_16x16x32_bf16 v[64:67], v[208:211], v[192:195], 0
	v_mfma_f32_16x16x32_bf16 v[112:115], v[204:207], v[172:175], v[112:115]
	v_mfma_f32_16x16x32_bf16 v[108:111], v[212:215], v[172:175], v[108:111]
	v_mfma_f32_16x16x32_bf16 v[104:107], v[204:207], v[180:183], v[104:107]
	v_mfma_f32_16x16x32_bf16 v[96:99], v[212:215], v[180:183], v[96:99]
	v_mfma_f32_16x16x32_bf16 v[88:91], v[204:207], v[188:191], v[88:91]
	v_mfma_f32_16x16x32_bf16 v[80:83], v[212:215], v[188:191], v[80:83]
	v_mfma_f32_16x16x32_bf16 v[72:75], v[204:207], v[196:199], v[72:75]
	v_mfma_f32_16x16x32_bf16 v[64:67], v[212:215], v[196:199], v[64:67]
	s_mov_b32 m0, s35
	s_add_u32 s100, s40, s8
	s_addc_u32 s101, s41, s9
	s_barrier
	ds_read_b128 v[160:163], v170 offset:16384
	ds_read_b128 v[172:175], v170 offset:17408
	ds_read_b128 v[176:179], v170 offset:18432
	ds_read_b128 v[180:183], v170 offset:19456
	ds_read_b128 v[184:187], v170 offset:20480
	ds_read_b128 v[188:191], v170 offset:21504
	ds_read_b128 v[192:195], v170 offset:22528
	ds_read_b128 v[196:199], v170 offset:23552
	global_load_lds_dwordx4 v146, s[40:41]
	s_mov_b32 m0, s47
	s_nop 0
	global_load_lds_dwordx4 v150, s[40:41]
	s_barrier
	s_waitcnt lgkmcnt(0)
	v_mfma_f32_16x16x32_bf16 v[60:63], v[128:131], v[160:163], 0
	v_mfma_f32_16x16x32_bf16 v[52:55], v[136:139], v[160:163], 0
	v_mfma_f32_16x16x32_bf16 v[44:47], v[128:131], v[176:179], 0
	v_mfma_f32_16x16x32_bf16 v[36:39], v[136:139], v[176:179], 0
	v_mfma_f32_16x16x32_bf16 v[28:31], v[128:131], v[184:187], 0
	v_mfma_f32_16x16x32_bf16 v[20:23], v[136:139], v[184:187], 0
	v_mfma_f32_16x16x32_bf16 v[12:15], v[128:131], v[192:195], 0
	v_mfma_f32_16x16x32_bf16 v[4:7], v[136:139], v[192:195], 0
	v_mfma_f32_16x16x32_bf16 v[60:63], v[132:135], v[172:175], v[60:63]
	v_mfma_f32_16x16x32_bf16 v[52:55], v[140:143], v[172:175], v[52:55]
	v_mfma_f32_16x16x32_bf16 v[44:47], v[132:135], v[180:183], v[44:47]
	v_mfma_f32_16x16x32_bf16 v[36:39], v[140:143], v[180:183], v[36:39]
	v_mfma_f32_16x16x32_bf16 v[28:31], v[132:135], v[188:191], v[28:31]
	v_mfma_f32_16x16x32_bf16 v[20:23], v[140:143], v[188:191], v[20:23]
	v_mfma_f32_16x16x32_bf16 v[12:15], v[132:135], v[196:199], v[12:15]
	v_mfma_f32_16x16x32_bf16 v[4:7], v[140:143], v[196:199], v[4:7]
	s_barrier
	s_add_u32 s66, s38, 0x40000
	s_addc_u32 s67, s39, 0
	s_add_i32 s68, s58, s46
	s_mov_b32 m0, s68
	s_nop 0
	global_load_lds_dwordx4 v148, s[66:67]
	s_add_i32 m0, s68, 0x2000
	s_nop 0
	global_load_lds_dwordx4 v152, s[66:67]
	s_waitcnt vmcnt(6)
	s_barrier
	v_mfma_f32_16x16x32_bf16 v[56:59], v[200:203], v[160:163], 0
	v_mfma_f32_16x16x32_bf16 v[48:51], v[208:211], v[160:163], 0
	v_mfma_f32_16x16x32_bf16 v[40:43], v[200:203], v[176:179], 0
	v_mfma_f32_16x16x32_bf16 v[32:35], v[208:211], v[176:179], 0
	v_mfma_f32_16x16x32_bf16 v[24:27], v[200:203], v[184:187], 0
	v_mfma_f32_16x16x32_bf16 v[16:19], v[208:211], v[184:187], 0
	v_mfma_f32_16x16x32_bf16 v[8:11], v[200:203], v[192:195], 0
	v_mfma_f32_16x16x32_bf16 v[0:3], v[208:211], v[192:195], 0
	v_mfma_f32_16x16x32_bf16 v[56:59], v[204:207], v[172:175], v[56:59]
	v_mfma_f32_16x16x32_bf16 v[48:51], v[212:215], v[172:175], v[48:51]
	v_mfma_f32_16x16x32_bf16 v[40:43], v[204:207], v[180:183], v[40:43]
	v_mfma_f32_16x16x32_bf16 v[32:35], v[212:215], v[180:183], v[32:35]
	v_mfma_f32_16x16x32_bf16 v[24:27], v[204:207], v[188:191], v[24:27]
	v_mfma_f32_16x16x32_bf16 v[16:19], v[212:215], v[188:191], v[16:19]
	v_mfma_f32_16x16x32_bf16 v[8:11], v[204:207], v[196:199], v[8:11]
	v_mfma_f32_16x16x32_bf16 v[0:3], v[212:215], v[196:199], v[0:3]
	s_add_i32 s66, 0, 0x18000
	v_add_u32_e32 v140, s66, v167
	s_barrier
	ds_read_b128 v[128:131], v140
	ds_read_b128 v[132:135], v140 offset:1024
	ds_read_b128 v[136:139], v140 offset:2048
	ds_read_b128 v[140:143], v140 offset:3072
	s_add_u32 s40, s40, 0x40000
	s_addc_u32 s41, s41, 0
	s_mov_b32 m0, s48
	ds_read_b128 v[160:163], v170 offset:32768
	ds_read_b128 v[172:175], v170 offset:33792
	ds_read_b128 v[176:179], v170 offset:34816
	ds_read_b128 v[180:183], v170 offset:35840
	ds_read_b128 v[184:187], v170 offset:36864
	ds_read_b128 v[188:191], v170 offset:37888
	ds_read_b128 v[192:195], v170 offset:38912
	ds_read_b128 v[196:199], v170 offset:39936
	global_load_lds_dwordx4 v146, s[40:41]
	s_mov_b32 m0, s49
	s_nop 0
	global_load_lds_dwordx4 v150, s[40:41]
	s_waitcnt lgkmcnt(8)
	s_barrier
	s_waitcnt lgkmcnt(0)
	v_mfma_f32_16x16x32_bf16 v[124:127], v[128:131], v[160:163], v[124:127]
	v_mfma_f32_16x16x32_bf16 v[120:123], v[136:139], v[160:163], v[120:123]
	v_mfma_f32_16x16x32_bf16 v[116:119], v[128:131], v[176:179], v[116:119]
	v_mfma_f32_16x16x32_bf16 v[100:103], v[136:139], v[176:179], v[100:103]
	v_mfma_f32_16x16x32_bf16 v[92:95], v[128:131], v[184:187], v[92:95]
	v_mfma_f32_16x16x32_bf16 v[84:87], v[136:139], v[184:187], v[84:87]
	v_mfma_f32_16x16x32_bf16 v[76:79], v[128:131], v[192:195], v[76:79]
	v_mfma_f32_16x16x32_bf16 v[68:71], v[136:139], v[192:195], v[68:71]
	v_mfma_f32_16x16x32_bf16 v[124:127], v[132:135], v[172:175], v[124:127]
	v_mfma_f32_16x16x32_bf16 v[120:123], v[140:143], v[172:175], v[120:123]
	v_mfma_f32_16x16x32_bf16 v[116:119], v[132:135], v[180:183], v[116:119]
	v_mfma_f32_16x16x32_bf16 v[100:103], v[140:143], v[180:183], v[100:103]
	v_mfma_f32_16x16x32_bf16 v[92:95], v[132:135], v[188:191], v[92:95]
	v_mfma_f32_16x16x32_bf16 v[84:87], v[140:143], v[188:191], v[84:87]
	v_mfma_f32_16x16x32_bf16 v[76:79], v[132:135], v[196:199], v[76:79]
	v_mfma_f32_16x16x32_bf16 v[68:71], v[140:143], v[196:199], v[68:71]
	s_barrier
	s_add_i32 s40, 0, 0x1c000
	s_add_i32 s41, s66, s46
	v_add_u32_e32 v212, s40, v167
	s_mov_b32 m0, s41
	ds_read_b128 v[200:203], v212
	ds_read_b128 v[204:207], v212 offset:1024
	ds_read_b128 v[208:211], v212 offset:2048
	ds_read_b128 v[212:215], v212 offset:3072
	global_load_lds_dwordx4 v148, s[98:99]
	s_add_i32 m0, s41, 0x2000
	s_nop 0
	global_load_lds_dwordx4 v152, s[98:99]
	s_barrier
	s_waitcnt lgkmcnt(0)
	v_mfma_f32_16x16x32_bf16 v[112:115], v[200:203], v[160:163], v[112:115]
	v_mfma_f32_16x16x32_bf16 v[108:111], v[208:211], v[160:163], v[108:111]
	v_mfma_f32_16x16x32_bf16 v[104:107], v[200:203], v[176:179], v[104:107]
	v_mfma_f32_16x16x32_bf16 v[96:99], v[208:211], v[176:179], v[96:99]
	v_mfma_f32_16x16x32_bf16 v[88:91], v[200:203], v[184:187], v[88:91]
	v_mfma_f32_16x16x32_bf16 v[80:83], v[208:211], v[184:187], v[80:83]
	v_mfma_f32_16x16x32_bf16 v[72:75], v[200:203], v[192:195], v[72:75]
	v_mfma_f32_16x16x32_bf16 v[64:67], v[208:211], v[192:195], v[64:67]
	v_mfma_f32_16x16x32_bf16 v[112:115], v[204:207], v[172:175], v[112:115]
	v_mfma_f32_16x16x32_bf16 v[108:111], v[212:215], v[172:175], v[108:111]
	v_mfma_f32_16x16x32_bf16 v[104:107], v[204:207], v[180:183], v[104:107]
	v_mfma_f32_16x16x32_bf16 v[96:99], v[212:215], v[180:183], v[96:99]
	v_mfma_f32_16x16x32_bf16 v[88:91], v[204:207], v[188:191], v[88:91]
	v_mfma_f32_16x16x32_bf16 v[80:83], v[212:215], v[188:191], v[80:83]
	v_mfma_f32_16x16x32_bf16 v[72:75], v[204:207], v[196:199], v[72:75]
	v_mfma_f32_16x16x32_bf16 v[64:67], v[212:215], v[196:199], v[64:67]
	s_mov_b32 m0, s51
	s_barrier
	ds_read_b128 v[160:163], v170 offset:49152
	ds_read_b128 v[172:175], v170 offset:50176
	ds_read_b128 v[176:179], v170 offset:51200
	ds_read_b128 v[180:183], v170 offset:52224
	ds_read_b128 v[184:187], v170 offset:53248
	ds_read_b128 v[188:191], v170 offset:54272
	ds_read_b128 v[192:195], v170 offset:55296
	ds_read_b128 v[196:199], v170 offset:56320
	global_load_lds_dwordx4 v146, s[100:101]
	s_mov_b32 m0, s54
	s_nop 0
	global_load_lds_dwordx4 v150, s[100:101]
	s_barrier
	s_waitcnt lgkmcnt(0)
	v_mfma_f32_16x16x32_bf16 v[60:63], v[128:131], v[160:163], v[60:63]
	v_mfma_f32_16x16x32_bf16 v[52:55], v[136:139], v[160:163], v[52:55]
	v_mfma_f32_16x16x32_bf16 v[44:47], v[128:131], v[176:179], v[44:47]
	v_mfma_f32_16x16x32_bf16 v[36:39], v[136:139], v[176:179], v[36:39]
	v_mfma_f32_16x16x32_bf16 v[28:31], v[128:131], v[184:187], v[28:31]
	v_mfma_f32_16x16x32_bf16 v[20:23], v[136:139], v[184:187], v[20:23]
	v_mfma_f32_16x16x32_bf16 v[12:15], v[128:131], v[192:195], v[12:15]
	v_mfma_f32_16x16x32_bf16 v[4:7], v[136:139], v[192:195], v[4:7]
	v_mfma_f32_16x16x32_bf16 v[60:63], v[132:135], v[172:175], v[60:63]
	v_mfma_f32_16x16x32_bf16 v[52:55], v[140:143], v[172:175], v[52:55]
	v_mfma_f32_16x16x32_bf16 v[44:47], v[132:135], v[180:183], v[44:47]
	v_mfma_f32_16x16x32_bf16 v[36:39], v[140:143], v[180:183], v[36:39]
	v_mfma_f32_16x16x32_bf16 v[28:31], v[132:135], v[188:191], v[28:31]
	v_mfma_f32_16x16x32_bf16 v[20:23], v[140:143], v[188:191], v[20:23]
	v_mfma_f32_16x16x32_bf16 v[12:15], v[132:135], v[196:199], v[12:15]
	v_mfma_f32_16x16x32_bf16 v[4:7], v[140:143], v[196:199], v[4:7]
	s_barrier
	s_add_u32 s38, s38, 0x40080
	s_addc_u32 s39, s39, 0
	s_add_i32 s40, s40, s46
	s_mov_b32 m0, s40
	s_nop 0
	global_load_lds_dwordx4 v148, s[38:39]
	s_add_i32 m0, s40, 0x2000
	s_nop 0
	global_load_lds_dwordx4 v152, s[38:39]
	s_waitcnt vmcnt(6)
	s_barrier
	v_mfma_f32_16x16x32_bf16 v[56:59], v[200:203], v[160:163], v[56:59]
	v_mfma_f32_16x16x32_bf16 v[48:51], v[208:211], v[160:163], v[48:51]
	v_mfma_f32_16x16x32_bf16 v[40:43], v[200:203], v[176:179], v[40:43]
	v_mfma_f32_16x16x32_bf16 v[32:35], v[208:211], v[176:179], v[32:35]
	v_mfma_f32_16x16x32_bf16 v[24:27], v[200:203], v[184:187], v[24:27]
	v_mfma_f32_16x16x32_bf16 v[16:19], v[208:211], v[184:187], v[16:19]
	v_mfma_f32_16x16x32_bf16 v[8:11], v[200:203], v[192:195], v[8:11]
	v_mfma_f32_16x16x32_bf16 v[0:3], v[208:211], v[192:195], v[0:3]
	v_mfma_f32_16x16x32_bf16 v[56:59], v[204:207], v[172:175], v[56:59]
	v_mfma_f32_16x16x32_bf16 v[48:51], v[212:215], v[172:175], v[48:51]
	v_mfma_f32_16x16x32_bf16 v[40:43], v[204:207], v[180:183], v[40:43]
	v_mfma_f32_16x16x32_bf16 v[32:35], v[212:215], v[180:183], v[32:35]
	v_mfma_f32_16x16x32_bf16 v[24:27], v[204:207], v[188:191], v[24:27]
	v_mfma_f32_16x16x32_bf16 v[16:19], v[212:215], v[188:191], v[16:19]
	v_mfma_f32_16x16x32_bf16 v[8:11], v[204:207], v[196:199], v[8:11]
	v_mfma_f32_16x16x32_bf16 v[0:3], v[212:215], v[196:199], v[0:3]
	s_add_i32 s65, s65, 2
	s_add_u32 s36, s36, 0x100
	s_addc_u32 s37, s37, 0
	s_add_u32 s29, s29, 0x100
	s_addc_u32 s64, s64, 0
	s_cmp_gt_u32 s65, 13
	s_barrier
	s_cbranch_scc0 .LBB0_932
.LBB0_932:
	ds_read_b128 v[128:131], v169
	ds_read_b128 v[132:135], v169 offset:1024
	ds_read_b128 v[136:139], v169 offset:2048
	ds_read_b128 v[140:143], v169 offset:3072
	s_add_u32 s38, s36, 0xfffc0080
	s_addc_u32 s39, s37, -1
	s_cmp_eq_u32 s65, 12
	s_cselect_b32 s41, s15, s39
	s_cselect_b32 s40, s63, s38
	s_cselect_b32 s39, s13, s64
	s_cselect_b32 s38, s28, s29
	s_add_i32 m0, s35, 0xc000
	ds_read_b128 v[160:163], v170
	ds_read_b128 v[172:175], v170 offset:1024
	ds_read_b128 v[176:179], v170 offset:2048
	ds_read_b128 v[180:183], v170 offset:3072
	ds_read_b128 v[184:187], v170 offset:4096
	ds_read_b128 v[188:191], v170 offset:5120
	ds_read_b128 v[192:195], v170 offset:6144
	ds_read_b128 v[196:199], v170 offset:7168
	global_load_lds_dwordx4 v154, s[36:37]
	s_add_i32 m0, s35, 0xe000
	s_nop 0
	global_load_lds_dwordx4 v156, s[36:37]
	s_waitcnt lgkmcnt(8)
	s_barrier
	s_waitcnt lgkmcnt(0)
	v_mfma_f32_16x16x32_bf16 v[124:127], v[128:131], v[160:163], v[124:127]
	v_mfma_f32_16x16x32_bf16 v[120:123], v[136:139], v[160:163], v[120:123]
	v_mfma_f32_16x16x32_bf16 v[116:119], v[128:131], v[176:179], v[116:119]
	v_mfma_f32_16x16x32_bf16 v[100:103], v[136:139], v[176:179], v[100:103]
	v_mfma_f32_16x16x32_bf16 v[92:95], v[128:131], v[184:187], v[92:95]
	v_mfma_f32_16x16x32_bf16 v[84:87], v[136:139], v[184:187], v[84:87]
	v_mfma_f32_16x16x32_bf16 v[76:79], v[128:131], v[192:195], v[76:79]
	v_mfma_f32_16x16x32_bf16 v[68:71], v[136:139], v[192:195], v[68:71]
	v_mfma_f32_16x16x32_bf16 v[124:127], v[132:135], v[172:175], v[124:127]
	v_mfma_f32_16x16x32_bf16 v[120:123], v[140:143], v[172:175], v[120:123]
	v_mfma_f32_16x16x32_bf16 v[116:119], v[132:135], v[180:183], v[116:119]
	v_mfma_f32_16x16x32_bf16 v[100:103], v[140:143], v[180:183], v[100:103]
	v_mfma_f32_16x16x32_bf16 v[92:95], v[132:135], v[188:191], v[92:95]
	v_mfma_f32_16x16x32_bf16 v[84:87], v[140:143], v[188:191], v[84:87]
	v_mfma_f32_16x16x32_bf16 v[76:79], v[132:135], v[196:199], v[76:79]
	v_mfma_f32_16x16x32_bf16 v[68:71], v[140:143], v[196:199], v[68:71]
	s_barrier
	s_add_i32 s66, s57, s46
	s_add_u32 s98, s38, s8
	s_addc_u32 s99, s39, s9
	s_mov_b32 m0, s66
	ds_read_b128 v[200:203], v171
	ds_read_b128 v[204:207], v171 offset:1024
	ds_read_b128 v[208:211], v171 offset:2048
	ds_read_b128 v[212:215], v171 offset:3072
	global_load_lds_dwordx4 v148, s[38:39]
	s_add_i32 m0, s66, 0x2000
	s_nop 0
	global_load_lds_dwordx4 v152, s[38:39]
	s_barrier
	s_waitcnt lgkmcnt(0)
	v_mfma_f32_16x16x32_bf16 v[112:115], v[200:203], v[160:163], v[112:115]
	v_mfma_f32_16x16x32_bf16 v[108:111], v[208:211], v[160:163], v[108:111]
	v_mfma_f32_16x16x32_bf16 v[104:107], v[200:203], v[176:179], v[104:107]
	v_mfma_f32_16x16x32_bf16 v[96:99], v[208:211], v[176:179], v[96:99]
	v_mfma_f32_16x16x32_bf16 v[88:91], v[200:203], v[184:187], v[88:91]
	v_mfma_f32_16x16x32_bf16 v[80:83], v[208:211], v[184:187], v[80:83]
	v_mfma_f32_16x16x32_bf16 v[72:75], v[200:203], v[192:195], v[72:75]
	v_mfma_f32_16x16x32_bf16 v[64:67], v[208:211], v[192:195], v[64:67]
	v_mfma_f32_16x16x32_bf16 v[112:115], v[204:207], v[172:175], v[112:115]
	v_mfma_f32_16x16x32_bf16 v[108:111], v[212:215], v[172:175], v[108:111]
	v_mfma_f32_16x16x32_bf16 v[104:107], v[204:207], v[180:183], v[104:107]
	v_mfma_f32_16x16x32_bf16 v[96:99], v[212:215], v[180:183], v[96:99]
	v_mfma_f32_16x16x32_bf16 v[88:91], v[204:207], v[188:191], v[88:91]
	v_mfma_f32_16x16x32_bf16 v[80:83], v[212:215], v[188:191], v[80:83]
	v_mfma_f32_16x16x32_bf16 v[72:75], v[204:207], v[196:199], v[72:75]
	v_mfma_f32_16x16x32_bf16 v[64:67], v[212:215], v[196:199], v[64:67]
	s_mov_b32 m0, s35
	s_add_u32 s100, s40, s8
	s_addc_u32 s101, s41, s9
	s_barrier
	ds_read_b128 v[160:163], v170 offset:16384
	ds_read_b128 v[172:175], v170 offset:17408
	ds_read_b128 v[176:179], v170 offset:18432
	ds_read_b128 v[180:183], v170 offset:19456
	ds_read_b128 v[184:187], v170 offset:20480
	ds_read_b128 v[188:191], v170 offset:21504
	ds_read_b128 v[192:195], v170 offset:22528
	ds_read_b128 v[196:199], v170 offset:23552
	global_load_lds_dwordx4 v146, s[40:41]
	s_mov_b32 m0, s47
	s_nop 0
	global_load_lds_dwordx4 v150, s[40:41]
	s_barrier
	s_waitcnt lgkmcnt(0)
	v_mfma_f32_16x16x32_bf16 v[60:63], v[128:131], v[160:163], v[60:63]
	v_mfma_f32_16x16x32_bf16 v[52:55], v[136:139], v[160:163], v[52:55]
	v_mfma_f32_16x16x32_bf16 v[44:47], v[128:131], v[176:179], v[44:47]
	v_mfma_f32_16x16x32_bf16 v[36:39], v[136:139], v[176:179], v[36:39]
	v_mfma_f32_16x16x32_bf16 v[28:31], v[128:131], v[184:187], v[28:31]
	v_mfma_f32_16x16x32_bf16 v[20:23], v[136:139], v[184:187], v[20:23]
	v_mfma_f32_16x16x32_bf16 v[12:15], v[128:131], v[192:195], v[12:15]
	v_mfma_f32_16x16x32_bf16 v[4:7], v[136:139], v[192:195], v[4:7]
	v_mfma_f32_16x16x32_bf16 v[60:63], v[132:135], v[172:175], v[60:63]
	v_mfma_f32_16x16x32_bf16 v[52:55], v[140:143], v[172:175], v[52:55]
	v_mfma_f32_16x16x32_bf16 v[44:47], v[132:135], v[180:183], v[44:47]
	v_mfma_f32_16x16x32_bf16 v[36:39], v[140:143], v[180:183], v[36:39]
	v_mfma_f32_16x16x32_bf16 v[28:31], v[132:135], v[188:191], v[28:31]
	v_mfma_f32_16x16x32_bf16 v[20:23], v[140:143], v[188:191], v[20:23]
	v_mfma_f32_16x16x32_bf16 v[12:15], v[132:135], v[196:199], v[12:15]
	v_mfma_f32_16x16x32_bf16 v[4:7], v[140:143], v[196:199], v[4:7]
	s_barrier
	s_add_u32 s66, s38, 0x40000
	s_addc_u32 s67, s39, 0
	s_add_i32 s68, s58, s46
	s_mov_b32 m0, s68
	s_nop 0
	global_load_lds_dwordx4 v148, s[66:67]
	s_add_i32 m0, s68, 0x2000
	s_nop 0
	global_load_lds_dwordx4 v152, s[66:67]
	s_waitcnt vmcnt(6)
	s_barrier
	v_mfma_f32_16x16x32_bf16 v[56:59], v[200:203], v[160:163], v[56:59]
	v_mfma_f32_16x16x32_bf16 v[48:51], v[208:211], v[160:163], v[48:51]
	v_mfma_f32_16x16x32_bf16 v[40:43], v[200:203], v[176:179], v[40:43]
	v_mfma_f32_16x16x32_bf16 v[32:35], v[208:211], v[176:179], v[32:35]
	v_mfma_f32_16x16x32_bf16 v[24:27], v[200:203], v[184:187], v[24:27]
	v_mfma_f32_16x16x32_bf16 v[16:19], v[208:211], v[184:187], v[16:19]
	v_mfma_f32_16x16x32_bf16 v[8:11], v[200:203], v[192:195], v[8:11]
	v_mfma_f32_16x16x32_bf16 v[0:3], v[208:211], v[192:195], v[0:3]
	v_mfma_f32_16x16x32_bf16 v[56:59], v[204:207], v[172:175], v[56:59]
	v_mfma_f32_16x16x32_bf16 v[48:51], v[212:215], v[172:175], v[48:51]
	v_mfma_f32_16x16x32_bf16 v[40:43], v[204:207], v[180:183], v[40:43]
	v_mfma_f32_16x16x32_bf16 v[32:35], v[212:215], v[180:183], v[32:35]
	v_mfma_f32_16x16x32_bf16 v[24:27], v[204:207], v[188:191], v[24:27]
	v_mfma_f32_16x16x32_bf16 v[16:19], v[212:215], v[188:191], v[16:19]
	v_mfma_f32_16x16x32_bf16 v[8:11], v[204:207], v[196:199], v[8:11]
	v_mfma_f32_16x16x32_bf16 v[0:3], v[212:215], v[196:199], v[0:3]
	s_add_i32 s66, 0, 0x18000
	v_add_u32_e32 v140, s66, v167
	s_barrier
	ds_read_b128 v[128:131], v140
	ds_read_b128 v[132:135], v140 offset:1024
	ds_read_b128 v[136:139], v140 offset:2048
	ds_read_b128 v[140:143], v140 offset:3072
	s_add_u32 s40, s40, 0x40000
	s_addc_u32 s41, s41, 0
	s_mov_b32 m0, s48
	ds_read_b128 v[160:163], v170 offset:32768
	ds_read_b128 v[172:175], v170 offset:33792
	ds_read_b128 v[176:179], v170 offset:34816
	ds_read_b128 v[180:183], v170 offset:35840
	ds_read_b128 v[184:187], v170 offset:36864
	ds_read_b128 v[188:191], v170 offset:37888
	ds_read_b128 v[192:195], v170 offset:38912
	ds_read_b128 v[196:199], v170 offset:39936
	global_load_lds_dwordx4 v146, s[40:41]
	s_mov_b32 m0, s49
	s_nop 0
	global_load_lds_dwordx4 v150, s[40:41]
	s_waitcnt lgkmcnt(8)
	s_barrier
	s_waitcnt lgkmcnt(0)
	v_mfma_f32_16x16x32_bf16 v[124:127], v[128:131], v[160:163], v[124:127]
	v_mfma_f32_16x16x32_bf16 v[120:123], v[136:139], v[160:163], v[120:123]
	v_mfma_f32_16x16x32_bf16 v[116:119], v[128:131], v[176:179], v[116:119]
	v_mfma_f32_16x16x32_bf16 v[100:103], v[136:139], v[176:179], v[100:103]
	v_mfma_f32_16x16x32_bf16 v[92:95], v[128:131], v[184:187], v[92:95]
	v_mfma_f32_16x16x32_bf16 v[84:87], v[136:139], v[184:187], v[84:87]
	v_mfma_f32_16x16x32_bf16 v[76:79], v[128:131], v[192:195], v[76:79]
	v_mfma_f32_16x16x32_bf16 v[68:71], v[136:139], v[192:195], v[68:71]
	v_mfma_f32_16x16x32_bf16 v[124:127], v[132:135], v[172:175], v[124:127]
	v_mfma_f32_16x16x32_bf16 v[120:123], v[140:143], v[172:175], v[120:123]
	v_mfma_f32_16x16x32_bf16 v[116:119], v[132:135], v[180:183], v[116:119]
	v_mfma_f32_16x16x32_bf16 v[100:103], v[140:143], v[180:183], v[100:103]
	v_mfma_f32_16x16x32_bf16 v[92:95], v[132:135], v[188:191], v[92:95]
	v_mfma_f32_16x16x32_bf16 v[84:87], v[140:143], v[188:191], v[84:87]
	v_mfma_f32_16x16x32_bf16 v[76:79], v[132:135], v[196:199], v[76:79]
	v_mfma_f32_16x16x32_bf16 v[68:71], v[140:143], v[196:199], v[68:71]
	s_barrier
	s_add_i32 s40, 0, 0x1c000
	s_add_i32 s41, s66, s46
	v_add_u32_e32 v212, s40, v167
	s_mov_b32 m0, s41
	ds_read_b128 v[200:203], v212
	ds_read_b128 v[204:207], v212 offset:1024
	ds_read_b128 v[208:211], v212 offset:2048
	ds_read_b128 v[212:215], v212 offset:3072
	global_load_lds_dwordx4 v148, s[98:99]
	s_add_i32 m0, s41, 0x2000
	s_nop 0
	global_load_lds_dwordx4 v152, s[98:99]
	s_barrier
	s_waitcnt lgkmcnt(0)
	v_mfma_f32_16x16x32_bf16 v[112:115], v[200:203], v[160:163], v[112:115]
	v_mfma_f32_16x16x32_bf16 v[108:111], v[208:211], v[160:163], v[108:111]
	v_mfma_f32_16x16x32_bf16 v[104:107], v[200:203], v[176:179], v[104:107]
	v_mfma_f32_16x16x32_bf16 v[96:99], v[208:211], v[176:179], v[96:99]
	v_mfma_f32_16x16x32_bf16 v[88:91], v[200:203], v[184:187], v[88:91]
	v_mfma_f32_16x16x32_bf16 v[80:83], v[208:211], v[184:187], v[80:83]
	v_mfma_f32_16x16x32_bf16 v[72:75], v[200:203], v[192:195], v[72:75]
	v_mfma_f32_16x16x32_bf16 v[64:67], v[208:211], v[192:195], v[64:67]
	v_mfma_f32_16x16x32_bf16 v[112:115], v[204:207], v[172:175], v[112:115]
	v_mfma_f32_16x16x32_bf16 v[108:111], v[212:215], v[172:175], v[108:111]
	v_mfma_f32_16x16x32_bf16 v[104:107], v[204:207], v[180:183], v[104:107]
	v_mfma_f32_16x16x32_bf16 v[96:99], v[212:215], v[180:183], v[96:99]
	v_mfma_f32_16x16x32_bf16 v[88:91], v[204:207], v[188:191], v[88:91]
	v_mfma_f32_16x16x32_bf16 v[80:83], v[212:215], v[188:191], v[80:83]
	v_mfma_f32_16x16x32_bf16 v[72:75], v[204:207], v[196:199], v[72:75]
	v_mfma_f32_16x16x32_bf16 v[64:67], v[212:215], v[196:199], v[64:67]
	s_mov_b32 m0, s51
	s_barrier
	ds_read_b128 v[160:163], v170 offset:49152
	ds_read_b128 v[172:175], v170 offset:50176
	ds_read_b128 v[176:179], v170 offset:51200
	ds_read_b128 v[180:183], v170 offset:52224
	ds_read_b128 v[184:187], v170 offset:53248
	ds_read_b128 v[188:191], v170 offset:54272
	ds_read_b128 v[192:195], v170 offset:55296
	ds_read_b128 v[196:199], v170 offset:56320
	global_load_lds_dwordx4 v146, s[100:101]
	s_mov_b32 m0, s54
	s_nop 0
	global_load_lds_dwordx4 v150, s[100:101]
	s_barrier
	s_waitcnt lgkmcnt(0)
	v_mfma_f32_16x16x32_bf16 v[60:63], v[128:131], v[160:163], v[60:63]
	v_mfma_f32_16x16x32_bf16 v[52:55], v[136:139], v[160:163], v[52:55]
	v_mfma_f32_16x16x32_bf16 v[44:47], v[128:131], v[176:179], v[44:47]
	v_mfma_f32_16x16x32_bf16 v[36:39], v[136:139], v[176:179], v[36:39]
	v_mfma_f32_16x16x32_bf16 v[28:31], v[128:131], v[184:187], v[28:31]
	v_mfma_f32_16x16x32_bf16 v[20:23], v[136:139], v[184:187], v[20:23]
	v_mfma_f32_16x16x32_bf16 v[12:15], v[128:131], v[192:195], v[12:15]
	v_mfma_f32_16x16x32_bf16 v[4:7], v[136:139], v[192:195], v[4:7]
	v_mfma_f32_16x16x32_bf16 v[60:63], v[132:135], v[172:175], v[60:63]
	v_mfma_f32_16x16x32_bf16 v[52:55], v[140:143], v[172:175], v[52:55]
	v_mfma_f32_16x16x32_bf16 v[44:47], v[132:135], v[180:183], v[44:47]
	v_mfma_f32_16x16x32_bf16 v[36:39], v[140:143], v[180:183], v[36:39]
	v_mfma_f32_16x16x32_bf16 v[28:31], v[132:135], v[188:191], v[28:31]
	v_mfma_f32_16x16x32_bf16 v[20:23], v[140:143], v[188:191], v[20:23]
	v_mfma_f32_16x16x32_bf16 v[12:15], v[132:135], v[196:199], v[12:15]
	v_mfma_f32_16x16x32_bf16 v[4:7], v[140:143], v[196:199], v[4:7]
	s_barrier
	s_add_u32 s38, s38, 0x40080
	s_addc_u32 s39, s39, 0
	s_add_i32 s40, s40, s46
	s_mov_b32 m0, s40
	s_nop 0
	global_load_lds_dwordx4 v148, s[38:39]
	s_add_i32 m0, s40, 0x2000
	s_nop 0
	global_load_lds_dwordx4 v152, s[38:39]
	s_waitcnt vmcnt(6)
	s_barrier
	v_mfma_f32_16x16x32_bf16 v[56:59], v[200:203], v[160:163], v[56:59]
	v_mfma_f32_16x16x32_bf16 v[48:51], v[208:211], v[160:163], v[48:51]
	v_mfma_f32_16x16x32_bf16 v[40:43], v[200:203], v[176:179], v[40:43]
	v_mfma_f32_16x16x32_bf16 v[32:35], v[208:211], v[176:179], v[32:35]
	v_mfma_f32_16x16x32_bf16 v[24:27], v[200:203], v[184:187], v[24:27]
	v_mfma_f32_16x16x32_bf16 v[16:19], v[208:211], v[184:187], v[16:19]
	v_mfma_f32_16x16x32_bf16 v[8:11], v[200:203], v[192:195], v[8:11]
	v_mfma_f32_16x16x32_bf16 v[0:3], v[208:211], v[192:195], v[0:3]
	v_mfma_f32_16x16x32_bf16 v[56:59], v[204:207], v[172:175], v[56:59]
	v_mfma_f32_16x16x32_bf16 v[48:51], v[212:215], v[172:175], v[48:51]
	v_mfma_f32_16x16x32_bf16 v[40:43], v[204:207], v[180:183], v[40:43]
	v_mfma_f32_16x16x32_bf16 v[32:35], v[212:215], v[180:183], v[32:35]
	v_mfma_f32_16x16x32_bf16 v[24:27], v[204:207], v[188:191], v[24:27]
	v_mfma_f32_16x16x32_bf16 v[16:19], v[212:215], v[188:191], v[16:19]
	v_mfma_f32_16x16x32_bf16 v[8:11], v[204:207], v[196:199], v[8:11]
	v_mfma_f32_16x16x32_bf16 v[0:3], v[212:215], v[196:199], v[0:3]
	s_add_i32 s65, s65, 2
	s_add_u32 s36, s36, 0x100
	s_addc_u32 s37, s37, 0
	s_add_u32 s29, s29, 0x100
	s_addc_u32 s64, s64, 0
	s_cmp_gt_u32 s65, 13
	s_barrier
	s_cbranch_scc0 .LBB0_932
	v_lshl_or_b32 v160, s62, 7, v168
	v_ashrrev_i32_e32 v161, 31, v160
	v_lshlrev_b64 v[128:129], 2, v[160:161]
	v_readlane_b32 s64, v248, 24
	v_lshl_add_u64 v[130:131], s[10:11], 0, v[128:129]
	v_readlane_b32 s70, v248, 30
	v_readlane_b32 s71, v248, 31
	global_load_dwordx4 v[136:139], v[130:131], off
	v_lshl_add_u32 v162, s34, 8, v166
	v_lshl_add_u64 v[128:129], s[70:71], 0, v[128:129]
	global_load_dwordx4 v[140:143], v[128:129], off
	global_load_dwordx4 v[132:135], v[130:131], off offset:16
	s_nop 0
	global_load_dwordx4 v[128:131], v[128:129], off offset:16
	v_ashrrev_i32_e32 v163, 31, v162
	v_lshlrev_b64 v[172:173], 12, v[162:163]
	v_lshlrev_b64 v[164:165], 1, v[160:161]
	v_lshl_add_u64 v[160:161], s[6:7], 0, v[172:173]
	v_lshl_add_u64 v[160:161], v[160:161], 0, v[164:165]
	s_mov_b32 s62, s12
	s_mov_b32 s34, s14
	s_mov_b64 s[38:39], s[30:31]
	s_mov_b64 s[36:37], s[18:19]
	v_readlane_b32 s65, v248, 25
	v_readlane_b32 s66, v248, 26
	v_readlane_b32 s67, v248, 27
	v_readlane_b32 s68, v248, 28
	v_readlane_b32 s69, v248, 29
	v_readlane_b32 s72, v248, 32
	v_readlane_b32 s73, v248, 33
	v_readlane_b32 s74, v248, 34
	v_readlane_b32 s75, v248, 35
	v_readlane_b32 s76, v248, 36
	v_readlane_b32 s77, v248, 37
	v_readlane_b32 s78, v248, 38
	v_readlane_b32 s79, v248, 39
	s_waitcnt vmcnt(0)
	v_add_f32_e32 v163, v112, v136
	v_add_f32_e32 v172, v113, v137
	v_add_f32_e32 v48, v48, v132
	v_add_f32_e32 v49, v49, v133
	v_pk_add_f32 v[112:113], v[126:127], v[142:143]
	v_add_f32_e32 v126, v114, v138
	v_add_f32_e32 v127, v115, v139
	v_add_f32_e32 v173, v108, v132
	v_add_f32_e32 v174, v109, v133
	v_pk_add_f32 v[108:109], v[122:123], v[130:131]
	v_pk_add_f32 v[114:115], v[120:121], v[128:129]
	v_add_f32_e32 v120, v110, v134
	v_add_f32_e32 v121, v111, v135
	v_add_f32_e32 v122, v104, v136
	v_add_f32_e32 v123, v105, v137
	v_pk_add_f32 v[110:111], v[116:117], v[140:141]
	v_add_f32_e32 v106, v106, v138
	v_add_f32_e32 v107, v107, v139
	v_mul_f32_e32 v116, 0xbfb8aa3b, v163
	v_mul_f32_e32 v117, 0xbfb8aa3b, v172
	v_mul_f32_e32 v48, 0xbfb8aa3b, v48
	v_mul_f32_e32 v49, 0xbfb8aa3b, v49
	v_add_f32_e32 v50, v50, v134
	v_add_f32_e32 v51, v51, v135
	v_pk_add_f32 v[104:105], v[118:119], v[142:143]
	v_mul_f32_e32 v118, 0xbfb8aa3b, v126
	v_mul_f32_e32 v119, 0xbfb8aa3b, v127
	v_mul_f32_e32 v126, 0xbfb8aa3b, v173
	v_mul_f32_e32 v127, 0xbfb8aa3b, v174
	v_mul_f32_e32 v120, 0xbfb8aa3b, v120
	v_mul_f32_e32 v121, 0xbfb8aa3b, v121
	v_mul_f32_e32 v122, 0xbfb8aa3b, v122
	v_mul_f32_e32 v123, 0xbfb8aa3b, v123
	v_mul_f32_e32 v106, 0xbfb8aa3b, v106
	v_mul_f32_e32 v107, 0xbfb8aa3b, v107
	v_exp_f32_e32 v116, v116
	v_exp_f32_e32 v117, v117
	v_exp_f32_e32 v48, v48
	v_exp_f32_e32 v49, v49
	v_mul_f32_e32 v50, 0xbfb8aa3b, v50
	v_mul_f32_e32 v51, 0xbfb8aa3b, v51
	v_add_f32_e32 v32, v32, v132
	v_add_f32_e32 v33, v33, v133
	v_exp_f32_e32 v118, v118
	v_exp_f32_e32 v119, v119
	v_exp_f32_e32 v126, v126
	v_exp_f32_e32 v127, v127
	v_exp_f32_e32 v120, v120
	v_exp_f32_e32 v121, v121
	v_exp_f32_e32 v122, v122
	v_exp_f32_e32 v123, v123
	v_exp_f32_e32 v106, v106
	v_exp_f32_e32 v107, v107
	v_exp_f32_e32 v50, v50
	v_exp_f32_e32 v51, v51
	v_mul_f32_e32 v32, 0xbfb8aa3b, v32
	v_mul_f32_e32 v33, 0xbfb8aa3b, v33
	v_add_f32_e32 v34, v34, v134
	v_add_f32_e32 v35, v35, v135
	v_add_f32_e32 v96, v96, v132
	v_add_f32_e32 v97, v97, v133
	v_exp_f32_e32 v32, v32
	v_exp_f32_e32 v33, v33
	v_mul_f32_e32 v34, 0xbfb8aa3b, v34
	v_mul_f32_e32 v35, 0xbfb8aa3b, v35
	v_add_f32_e32 v16, v16, v132
	v_add_f32_e32 v17, v17, v133
	v_mul_f32_e32 v96, 0xbfb8aa3b, v96
	v_mul_f32_e32 v97, 0xbfb8aa3b, v97
	v_add_f32_e32 v88, v88, v136
	v_add_f32_e32 v89, v89, v137
	v_add_f32_e32 v72, v72, v136
	v_add_f32_e32 v73, v73, v137
	v_exp_f32_e32 v34, v34
	v_exp_f32_e32 v35, v35
	v_mul_f32_e32 v16, 0xbfb8aa3b, v16
	v_mul_f32_e32 v17, 0xbfb8aa3b, v17
	v_add_f32_e32 v18, v18, v134
	v_add_f32_e32 v19, v19, v135
	v_exp_f32_e32 v163, v96
	v_exp_f32_e32 v172, v97
	v_add_f32_e32 v96, 1.0, v116
	v_add_f32_e32 v97, 1.0, v117
	v_mul_f32_e32 v88, 0xbfb8aa3b, v88
	v_mul_f32_e32 v89, 0xbfb8aa3b, v89
	v_add_f32_e32 v80, v80, v132
	v_add_f32_e32 v81, v81, v133
	v_mul_f32_e32 v72, 0xbfb8aa3b, v72
	v_mul_f32_e32 v73, 0xbfb8aa3b, v73
	v_add_f32_e32 v64, v64, v132
	v_add_f32_e32 v65, v65, v133
	v_add_f32_e32 v48, 1.0, v48
	v_add_f32_e32 v49, 1.0, v49
	v_exp_f32_e32 v16, v16
	v_exp_f32_e32 v17, v17
	v_mul_f32_e32 v18, 0xbfb8aa3b, v18
	v_mul_f32_e32 v19, 0xbfb8aa3b, v19
	v_add_f32_e32 v0, v0, v132
	v_add_f32_e32 v1, v1, v133
	v_add_f32_e32 v116, 1.0, v118
	v_add_f32_e32 v117, 1.0, v119
	v_add_f32_e32 v118, 1.0, v126
	v_add_f32_e32 v119, 1.0, v127
	v_add_f32_e32 v120, 1.0, v120
	v_add_f32_e32 v121, 1.0, v121
	v_add_f32_e32 v122, 1.0, v122
	v_add_f32_e32 v123, 1.0, v123
	v_add_f32_e32 v126, 1.0, v106
	v_add_f32_e32 v127, 1.0, v107
	v_rcp_f32_e32 v96, v96
	v_rcp_f32_e32 v97, v97
	v_add_f32_e32 v98, v98, v134
	v_add_f32_e32 v99, v99, v135
	v_exp_f32_e32 v88, v88
	v_exp_f32_e32 v89, v89
	v_mul_f32_e32 v80, 0xbfb8aa3b, v80
	v_mul_f32_e32 v81, 0xbfb8aa3b, v81
	v_add_f32_e32 v82, v82, v134
	v_add_f32_e32 v83, v83, v135
	v_exp_f32_e32 v72, v72
	v_exp_f32_e32 v73, v73
	v_mul_f32_e32 v64, 0xbfb8aa3b, v64
	v_mul_f32_e32 v65, 0xbfb8aa3b, v65
	v_add_f32_e32 v66, v66, v134
	v_add_f32_e32 v67, v67, v135
	v_rcp_f32_e32 v48, v48
	v_rcp_f32_e32 v49, v49
	v_add_f32_e32 v50, 1.0, v50
	v_add_f32_e32 v51, 1.0, v51
	v_exp_f32_e32 v18, v18
	v_exp_f32_e32 v19, v19
	v_mul_f32_e32 v0, 0xbfb8aa3b, v0
	v_mul_f32_e32 v1, 0xbfb8aa3b, v1
	v_add_f32_e32 v2, v2, v134
	v_add_f32_e32 v3, v3, v135
	v_rcp_f32_e32 v106, v116
	v_rcp_f32_e32 v107, v117
	v_rcp_f32_e32 v116, v118
	v_rcp_f32_e32 v117, v119
	v_rcp_f32_e32 v118, v120
	v_rcp_f32_e32 v119, v121
	v_rcp_f32_e32 v120, v122
	v_rcp_f32_e32 v121, v123
	v_rcp_f32_e32 v122, v126
	v_rcp_f32_e32 v123, v127
	v_mul_f32_e32 v98, 0xbfb8aa3b, v98
	v_mul_f32_e32 v99, 0xbfb8aa3b, v99
	v_add_f32_e32 v90, v90, v138
	v_add_f32_e32 v91, v91, v139
	v_exp_f32_e32 v80, v80
	v_exp_f32_e32 v81, v81
	v_mul_f32_e32 v82, 0xbfb8aa3b, v82
	v_mul_f32_e32 v83, 0xbfb8aa3b, v83
	v_add_f32_e32 v74, v74, v138
	v_add_f32_e32 v75, v75, v139
	v_exp_f32_e32 v64, v64
	v_exp_f32_e32 v65, v65
	v_mul_f32_e32 v66, 0xbfb8aa3b, v66
	v_mul_f32_e32 v67, 0xbfb8aa3b, v67
	v_add_f32_e32 v56, v56, v136
	v_add_f32_e32 v57, v57, v137
	v_add_f32_e32 v58, v58, v138
	v_add_f32_e32 v59, v59, v139
	v_rcp_f32_e32 v50, v50
	v_rcp_f32_e32 v51, v51
	v_add_f32_e32 v40, v40, v136
	v_add_f32_e32 v41, v41, v137
	v_add_f32_e32 v42, v42, v138
	v_add_f32_e32 v43, v43, v139
	v_add_f32_e32 v32, 1.0, v32
	v_add_f32_e32 v33, 1.0, v33
	v_add_f32_e32 v24, v24, v136
	v_add_f32_e32 v25, v25, v137
	v_add_f32_e32 v26, v26, v138
	v_add_f32_e32 v27, v27, v139
	v_add_f32_e32 v8, v8, v136
	v_add_f32_e32 v9, v9, v137
	v_add_f32_e32 v10, v10, v138
	v_add_f32_e32 v11, v11, v139
	v_exp_f32_e32 v0, v0
	v_exp_f32_e32 v1, v1
	v_mul_f32_e32 v2, 0xbfb8aa3b, v2
	v_mul_f32_e32 v3, 0xbfb8aa3b, v3
	v_exp_f32_e32 v98, v98
	v_exp_f32_e32 v99, v99
	v_mul_f32_e32 v90, 0xbfb8aa3b, v90
	v_mul_f32_e32 v91, 0xbfb8aa3b, v91
	v_exp_f32_e32 v82, v82
	v_exp_f32_e32 v83, v83
	v_mul_f32_e32 v74, 0xbfb8aa3b, v74
	v_mul_f32_e32 v75, 0xbfb8aa3b, v75
	v_exp_f32_e32 v66, v66
	v_exp_f32_e32 v67, v67
	v_mul_f32_e32 v56, 0xbfb8aa3b, v56
	v_mul_f32_e32 v57, 0xbfb8aa3b, v57
	v_mul_f32_e32 v58, 0xbfb8aa3b, v58
	v_mul_f32_e32 v59, 0xbfb8aa3b, v59
	v_mul_f32_e32 v40, 0xbfb8aa3b, v40
	v_mul_f32_e32 v41, 0xbfb8aa3b, v41
	v_mul_f32_e32 v42, 0xbfb8aa3b, v42
	v_mul_f32_e32 v43, 0xbfb8aa3b, v43
	v_rcp_f32_e32 v32, v32
	v_rcp_f32_e32 v33, v33
	v_add_f32_e32 v34, 1.0, v34
	v_add_f32_e32 v35, 1.0, v35
	v_mul_f32_e32 v24, 0xbfb8aa3b, v24
	v_mul_f32_e32 v25, 0xbfb8aa3b, v25
	v_mul_f32_e32 v26, 0xbfb8aa3b, v26
	v_mul_f32_e32 v27, 0xbfb8aa3b, v27
	v_mul_f32_e32 v8, 0xbfb8aa3b, v8
	v_mul_f32_e32 v9, 0xbfb8aa3b, v9
	v_mul_f32_e32 v10, 0xbfb8aa3b, v10
	v_mul_f32_e32 v11, 0xbfb8aa3b, v11
	v_exp_f32_e32 v2, v2
	v_exp_f32_e32 v3, v3
	v_pk_add_f32 v[124:125], v[124:125], v[140:141]
	v_exp_f32_e32 v90, v90
	v_exp_f32_e32 v91, v91
	v_exp_f32_e32 v74, v74
	v_exp_f32_e32 v75, v75
	v_exp_f32_e32 v56, v56
	v_exp_f32_e32 v57, v57
	v_exp_f32_e32 v58, v58
	v_exp_f32_e32 v59, v59
	v_pk_add_f32 v[52:53], v[52:53], v[128:129]
	v_exp_f32_e32 v40, v40
	v_exp_f32_e32 v41, v41
	v_exp_f32_e32 v42, v42
	v_exp_f32_e32 v43, v43
	v_rcp_f32_e32 v34, v34
	v_rcp_f32_e32 v35, v35
	v_exp_f32_e32 v24, v24
	v_exp_f32_e32 v25, v25
	v_exp_f32_e32 v26, v26
	v_exp_f32_e32 v27, v27
	v_add_f32_e32 v16, 1.0, v16
	v_add_f32_e32 v17, 1.0, v17
	v_exp_f32_e32 v8, v8
	v_exp_f32_e32 v9, v9
	v_exp_f32_e32 v10, v10
	v_exp_f32_e32 v11, v11
	v_pk_mul_f32 v[96:97], v[124:125], v[96:97]
	v_add_f32_e32 v88, 1.0, v88
	v_add_f32_e32 v89, 1.0, v89
	v_add_f32_e32 v72, 1.0, v72
	v_add_f32_e32 v73, 1.0, v73
	v_pk_add_f32 v[54:55], v[54:55], v[130:131]
	v_pk_mul_f32 v[52:53], v[52:53], v[48:49]
	v_rcp_f32_e32 v16, v16
	v_rcp_f32_e32 v17, v17
	v_add_f32_e32 v18, 1.0, v18
	v_add_f32_e32 v19, 1.0, v19
	v_pk_mul_f32 v[106:107], v[112:113], v[106:107]
	v_pk_mul_f32 v[112:113], v[114:115], v[116:117]
	v_pk_mul_f32 v[114:115], v[104:105], v[122:123]
	v_cvt_pk_bf16_f32 v104, v96, v97
	v_add_f32_e32 v96, 1.0, v163
	v_add_f32_e32 v97, 1.0, v172
	v_rcp_f32_e32 v88, v88
	v_rcp_f32_e32 v89, v89
	v_add_f32_e32 v80, 1.0, v80
	v_add_f32_e32 v81, 1.0, v81
	v_rcp_f32_e32 v72, v72
	v_rcp_f32_e32 v73, v73
	v_add_f32_e32 v64, 1.0, v64
	v_add_f32_e32 v65, 1.0, v65
	v_pk_mul_f32 v[54:55], v[54:55], v[50:51]
	v_cvt_pk_bf16_f32 v50, v52, v53
	v_add_co_u32_e32 v52, vcc, s59, v160
	v_pk_add_f32 v[36:37], v[36:37], v[128:129]
	v_rcp_f32_e32 v18, v18
	v_rcp_f32_e32 v19, v19
	v_add_f32_e32 v0, 1.0, v0
	v_add_f32_e32 v1, 1.0, v1
	v_rcp_f32_e32 v96, v96
	v_rcp_f32_e32 v97, v97
	v_add_f32_e32 v98, 1.0, v98
	v_add_f32_e32 v99, 1.0, v99
	v_rcp_f32_e32 v80, v80
	v_rcp_f32_e32 v81, v81
	v_add_f32_e32 v82, 1.0, v82
	v_add_f32_e32 v83, 1.0, v83
	v_rcp_f32_e32 v64, v64
	v_rcp_f32_e32 v65, v65
	v_add_f32_e32 v66, 1.0, v66
	v_add_f32_e32 v67, 1.0, v67
	v_addc_co_u32_e32 v53, vcc, 0, v161, vcc
	v_pk_add_f32 v[38:39], v[38:39], v[130:131]
	v_pk_mul_f32 v[36:37], v[36:37], v[32:33]
	v_rcp_f32_e32 v0, v0
	v_rcp_f32_e32 v1, v1
	v_add_f32_e32 v2, 1.0, v2
	v_add_f32_e32 v3, 1.0, v3
	v_pk_mul_f32 v[108:109], v[108:109], v[118:119]
	v_rcp_f32_e32 v98, v98
	v_rcp_f32_e32 v99, v99
	v_add_f32_e32 v90, 1.0, v90
	v_add_f32_e32 v91, 1.0, v91
	v_rcp_f32_e32 v82, v82
	v_rcp_f32_e32 v83, v83
	v_add_f32_e32 v74, 1.0, v74
	v_add_f32_e32 v75, 1.0, v75
	v_rcp_f32_e32 v66, v66
	v_rcp_f32_e32 v67, v67
	v_add_f32_e32 v56, 1.0, v56
	v_add_f32_e32 v57, 1.0, v57
	v_add_f32_e32 v58, 1.0, v58
	v_add_f32_e32 v59, 1.0, v59
	v_add_f32_e32 v40, 1.0, v40
	v_add_f32_e32 v41, 1.0, v41
	v_add_f32_e32 v42, 1.0, v42
	v_add_f32_e32 v43, 1.0, v43
	v_pk_mul_f32 v[38:39], v[38:39], v[34:35]
	v_cvt_pk_bf16_f32 v34, v36, v37
	v_add_co_u32_e32 v36, vcc, s60, v160
	v_add_f32_e32 v24, 1.0, v24
	v_add_f32_e32 v25, 1.0, v25
	v_add_f32_e32 v26, 1.0, v26
	v_add_f32_e32 v27, 1.0, v27
	v_pk_add_f32 v[20:21], v[20:21], v[128:129]
	v_add_f32_e32 v8, 1.0, v8
	v_add_f32_e32 v9, 1.0, v9
	v_add_f32_e32 v10, 1.0, v10
	v_add_f32_e32 v11, 1.0, v11
	v_rcp_f32_e32 v2, v2
	v_rcp_f32_e32 v3, v3
	v_cvt_pk_bf16_f32 v105, v106, v107
	v_cvt_pk_bf16_f32 v106, v112, v113
	v_cvt_pk_bf16_f32 v107, v108, v109
	v_pk_add_f32 v[92:93], v[92:93], v[140:141]
	v_rcp_f32_e32 v90, v90
	v_rcp_f32_e32 v91, v91
	v_pk_add_f32 v[76:77], v[76:77], v[140:141]
	v_rcp_f32_e32 v74, v74
	v_rcp_f32_e32 v75, v75
	v_rcp_f32_e32 v56, v56
	v_rcp_f32_e32 v57, v57
	v_rcp_f32_e32 v58, v58
	v_rcp_f32_e32 v59, v59
	v_rcp_f32_e32 v40, v40
	v_rcp_f32_e32 v41, v41
	v_rcp_f32_e32 v42, v42
	v_rcp_f32_e32 v43, v43
	v_addc_co_u32_e32 v37, vcc, 0, v161, vcc
	v_rcp_f32_e32 v24, v24
	v_rcp_f32_e32 v25, v25
	v_rcp_f32_e32 v26, v26
	v_rcp_f32_e32 v27, v27
	v_pk_add_f32 v[22:23], v[22:23], v[130:131]
	v_pk_mul_f32 v[20:21], v[20:21], v[16:17]
	v_rcp_f32_e32 v8, v8
	v_rcp_f32_e32 v9, v9
	v_rcp_f32_e32 v10, v10
	v_rcp_f32_e32 v11, v11
	global_store_dwordx4 v[160:161], v[104:107], off
	v_pk_add_f32 v[100:101], v[100:101], v[128:129]
	v_pk_mul_f32 v[88:89], v[92:93], v[88:89]
	v_or_b32_e32 v104, 16, v162
	v_pk_add_f32 v[84:85], v[84:85], v[128:129]
	v_or_b32_e32 v92, 32, v162
	v_pk_mul_f32 v[72:73], v[76:77], v[72:73]
	v_pk_add_f32 v[68:69], v[68:69], v[128:129]
	v_or_b32_e32 v76, 48, v162
	v_pk_mul_f32 v[22:23], v[22:23], v[18:19]
	v_cvt_pk_bf16_f32 v18, v20, v21
	v_add_co_u32_e32 v20, vcc, s61, v160
	v_pk_add_f32 v[4:5], v[4:5], v[128:129]
	v_pk_add_f32 v[102:103], v[102:103], v[130:131]
	v_pk_mul_f32 v[100:101], v[100:101], v[96:97]
	v_ashrrev_i32_e32 v105, 31, v104
	v_pk_add_f32 v[86:87], v[86:87], v[130:131]
	v_pk_mul_f32 v[84:85], v[84:85], v[80:81]
	v_ashrrev_i32_e32 v93, 31, v92
	v_pk_add_f32 v[70:71], v[70:71], v[130:131]
	v_pk_mul_f32 v[68:69], v[68:69], v[64:65]
	v_ashrrev_i32_e32 v77, 31, v76
	v_addc_co_u32_e32 v21, vcc, 0, v161, vcc
	v_pk_add_f32 v[6:7], v[6:7], v[130:131]
	v_pk_mul_f32 v[4:5], v[4:5], v[0:1]
	v_pk_mul_f32 v[102:103], v[102:103], v[98:99]
	v_cvt_pk_bf16_f32 v98, v100, v101
	v_lshlrev_b64 v[100:101], 12, v[104:105]
	v_pk_add_f32 v[94:95], v[94:95], v[142:143]
	v_pk_mul_f32 v[86:87], v[86:87], v[82:83]
	v_cvt_pk_bf16_f32 v82, v84, v85
	v_lshlrev_b64 v[84:85], 12, v[92:93]
	v_pk_add_f32 v[78:79], v[78:79], v[142:143]
	v_pk_mul_f32 v[70:71], v[70:71], v[66:67]
	v_cvt_pk_bf16_f32 v66, v68, v69
	v_lshlrev_b64 v[68:69], 12, v[76:77]
	v_pk_add_f32 v[62:63], v[62:63], v[142:143]
	v_pk_add_f32 v[60:61], v[60:61], v[140:141]
	v_pk_add_f32 v[46:47], v[46:47], v[142:143]
	v_pk_add_f32 v[44:45], v[44:45], v[140:141]
	v_pk_add_f32 v[30:31], v[30:31], v[142:143]
	v_pk_add_f32 v[28:29], v[28:29], v[140:141]
	v_pk_add_f32 v[14:15], v[14:15], v[142:143]
	v_pk_add_f32 v[12:13], v[12:13], v[140:141]
	v_pk_mul_f32 v[6:7], v[6:7], v[2:3]
	v_cvt_pk_bf16_f32 v2, v4, v5
	v_add_co_u32_e32 v4, vcc, 0xb0000, v160
	v_pk_mul_f32 v[110:111], v[110:111], v[120:121]
	v_lshl_add_u64 v[100:101], s[6:7], 0, v[100:101]
	v_pk_mul_f32 v[90:91], v[94:95], v[90:91]
	v_lshl_add_u64 v[84:85], s[6:7], 0, v[84:85]
	v_pk_mul_f32 v[74:75], v[78:79], v[74:75]
	v_lshl_add_u64 v[68:69], s[6:7], 0, v[68:69]
	v_pk_mul_f32 v[56:57], v[60:61], v[56:57]
	v_pk_mul_f32 v[58:59], v[62:63], v[58:59]
	v_pk_mul_f32 v[40:41], v[44:45], v[40:41]
	v_pk_mul_f32 v[42:43], v[46:47], v[42:43]
	v_pk_mul_f32 v[24:25], v[28:29], v[24:25]
	v_pk_mul_f32 v[26:27], v[30:31], v[26:27]
	v_pk_mul_f32 v[8:9], v[12:13], v[8:9]
	v_pk_mul_f32 v[10:11], v[14:15], v[10:11]
	v_addc_co_u32_e32 v5, vcc, 0, v161, vcc
	v_cvt_pk_bf16_f32 v96, v110, v111
	v_cvt_pk_bf16_f32 v97, v114, v115
	v_cvt_pk_bf16_f32 v99, v102, v103
	v_lshl_add_u64 v[100:101], v[100:101], 0, v[164:165]
	v_cvt_pk_bf16_f32 v80, v88, v89
	v_cvt_pk_bf16_f32 v81, v90, v91
	v_cvt_pk_bf16_f32 v83, v86, v87
	v_lshl_add_u64 v[84:85], v[84:85], 0, v[164:165]
	v_cvt_pk_bf16_f32 v64, v72, v73
	v_cvt_pk_bf16_f32 v65, v74, v75
	v_cvt_pk_bf16_f32 v67, v70, v71
	v_lshl_add_u64 v[68:69], v[68:69], 0, v[164:165]
	v_cvt_pk_bf16_f32 v48, v56, v57
	v_cvt_pk_bf16_f32 v49, v58, v59
	v_cvt_pk_bf16_f32 v51, v54, v55
	v_cvt_pk_bf16_f32 v32, v40, v41
	v_cvt_pk_bf16_f32 v33, v42, v43
	v_cvt_pk_bf16_f32 v35, v38, v39
	v_cvt_pk_bf16_f32 v16, v24, v25
	v_cvt_pk_bf16_f32 v17, v26, v27
	v_cvt_pk_bf16_f32 v19, v22, v23
	v_cvt_pk_bf16_f32 v0, v8, v9
	v_cvt_pk_bf16_f32 v1, v10, v11
	v_cvt_pk_bf16_f32 v3, v6, v7
	s_and_b64 vcc, exec, s[16:17]
	global_store_dwordx4 v[100:101], v[96:99], off
	global_store_dwordx4 v[84:85], v[80:83], off
	global_store_dwordx4 v[68:69], v[64:67], off
	global_store_dwordx4 v[52:53], v[48:51], off
	global_store_dwordx4 v[36:37], v[32:35], off
	global_store_dwordx4 v[20:21], v[16:19], off
	global_store_dwordx4 v[4:5], v[0:3], off
	s_cbranch_vccz .LBB0_923
	s_branch .LBB0_935

.LBB0_1073:
	s_ashr_i32 s31, s30, 31
	s_xor_b64 s[34:35], s[28:29], -1
	s_lshl_b64 s[36:37], s[30:31], 20
	s_add_u32 s36, s48, s36
	s_addc_u32 s37, s49, s37
	s_and_b64 s[38:39], s[28:29], exec
	s_cselect_b32 s31, s37, s43
	s_cselect_b32 s68, s36, s42
	s_ashr_i32 s19, s18, 31
	s_lshl_b64 s[38:39], s[18:19], 20
	s_add_u32 s38, s50, s38
	s_addc_u32 s39, s51, s39
	s_and_b64 s[28:29], s[28:29], exec
	s_cselect_b32 s19, s39, s45
	s_cselect_b32 s28, s38, s44
	s_add_u32 s42, s42, 0x80080
	s_addc_u32 s43, s43, 0
	s_add_u32 s29, s44, 0x100
	s_addc_u32 s69, s45, 0
	s_mov_b32 s70, -2
	ds_read_b128 v[128:131], v165
	ds_read_b128 v[132:135], v165 offset:1024
	ds_read_b128 v[136:139], v165 offset:2048
	ds_read_b128 v[140:143], v165 offset:3072
	s_add_u32 s44, s42, 0xfff80080
	s_addc_u32 s45, s43, -1
	s_cmp_eq_u32 s70, 28
	s_cselect_b32 s47, s31, s45
	s_cselect_b32 s46, s68, s44
	s_cselect_b32 s45, s19, s69
	s_cselect_b32 s44, s28, s29
	s_add_i32 m0, s41, 0xc000
	ds_read_b128 v[156:159], v166
	ds_read_b128 v[168:171], v166 offset:1024
	ds_read_b128 v[172:175], v166 offset:2048
	ds_read_b128 v[176:179], v166 offset:3072
	ds_read_b128 v[180:183], v166 offset:4096
	ds_read_b128 v[184:187], v166 offset:5120
	ds_read_b128 v[188:191], v166 offset:6144
	ds_read_b128 v[192:195], v166 offset:7168
	global_load_lds_dwordx4 v150, s[42:43]
	s_add_i32 m0, s41, 0xe000
	s_nop 0
	global_load_lds_dwordx4 v152, s[42:43]
	s_waitcnt lgkmcnt(8)
	s_barrier
	s_waitcnt lgkmcnt(0)
	v_mfma_f32_16x16x32_bf16 v[124:127], v[128:131], v[156:159], 0
	v_mfma_f32_16x16x32_bf16 v[120:123], v[136:139], v[156:159], 0
	v_mfma_f32_16x16x32_bf16 v[112:115], v[128:131], v[172:175], 0
	v_mfma_f32_16x16x32_bf16 v[104:107], v[136:139], v[172:175], 0
	v_mfma_f32_16x16x32_bf16 v[96:99], v[128:131], v[180:183], 0
	v_mfma_f32_16x16x32_bf16 v[88:91], v[136:139], v[180:183], 0
	v_mfma_f32_16x16x32_bf16 v[80:83], v[128:131], v[188:191], 0
	v_mfma_f32_16x16x32_bf16 v[72:75], v[136:139], v[188:191], 0
	v_mfma_f32_16x16x32_bf16 v[124:127], v[132:135], v[168:171], v[124:127]
	v_mfma_f32_16x16x32_bf16 v[120:123], v[140:143], v[168:171], v[120:123]
	v_mfma_f32_16x16x32_bf16 v[112:115], v[132:135], v[176:179], v[112:115]
	v_mfma_f32_16x16x32_bf16 v[104:107], v[140:143], v[176:179], v[104:107]
	v_mfma_f32_16x16x32_bf16 v[96:99], v[132:135], v[184:187], v[96:99]
	v_mfma_f32_16x16x32_bf16 v[88:91], v[140:143], v[184:187], v[88:91]
	v_mfma_f32_16x16x32_bf16 v[80:83], v[132:135], v[192:195], v[80:83]
	v_mfma_f32_16x16x32_bf16 v[72:75], v[140:143], v[192:195], v[72:75]
	s_barrier
	s_add_i32 s71, s65, s54
	s_add_u32 s98, s44, s8
	s_addc_u32 s99, s45, s9
	s_mov_b32 m0, s71
	ds_read_b128 v[196:199], v167
	ds_read_b128 v[200:203], v167 offset:1024
	ds_read_b128 v[204:207], v167 offset:2048
	ds_read_b128 v[208:211], v167 offset:3072
	global_load_lds_dwordx4 v146, s[44:45]
	s_add_i32 m0, s71, 0x2000
	s_nop 0
	global_load_lds_dwordx4 v148, s[44:45]
	s_barrier
	s_waitcnt lgkmcnt(0)
	v_mfma_f32_16x16x32_bf16 v[116:119], v[196:199], v[156:159], 0
	v_mfma_f32_16x16x32_bf16 v[108:111], v[204:207], v[156:159], 0
	v_mfma_f32_16x16x32_bf16 v[100:103], v[196:199], v[172:175], 0
	v_mfma_f32_16x16x32_bf16 v[92:95], v[204:207], v[172:175], 0
	v_mfma_f32_16x16x32_bf16 v[84:87], v[196:199], v[180:183], 0
	v_mfma_f32_16x16x32_bf16 v[76:79], v[204:207], v[180:183], 0
	v_mfma_f32_16x16x32_bf16 v[68:71], v[196:199], v[188:191], 0
	v_mfma_f32_16x16x32_bf16 v[64:67], v[204:207], v[188:191], 0
	v_mfma_f32_16x16x32_bf16 v[116:119], v[200:203], v[168:171], v[116:119]
	v_mfma_f32_16x16x32_bf16 v[108:111], v[208:211], v[168:171], v[108:111]
	v_mfma_f32_16x16x32_bf16 v[100:103], v[200:203], v[176:179], v[100:103]
	v_mfma_f32_16x16x32_bf16 v[92:95], v[208:211], v[176:179], v[92:95]
	v_mfma_f32_16x16x32_bf16 v[84:87], v[200:203], v[184:187], v[84:87]
	v_mfma_f32_16x16x32_bf16 v[76:79], v[208:211], v[184:187], v[76:79]
	v_mfma_f32_16x16x32_bf16 v[68:71], v[200:203], v[192:195], v[68:71]
	v_mfma_f32_16x16x32_bf16 v[64:67], v[208:211], v[192:195], v[64:67]
	s_mov_b32 m0, s41
	s_add_u32 s100, s46, s8
	s_addc_u32 s101, s47, s9
	s_barrier
	ds_read_b128 v[156:159], v166 offset:16384
	ds_read_b128 v[168:171], v166 offset:17408
	ds_read_b128 v[172:175], v166 offset:18432
	ds_read_b128 v[176:179], v166 offset:19456
	ds_read_b128 v[180:183], v166 offset:20480
	ds_read_b128 v[184:187], v166 offset:21504
	ds_read_b128 v[188:191], v166 offset:22528
	ds_read_b128 v[192:195], v166 offset:23552
	global_load_lds_dwordx4 v146, s[46:47]
	s_mov_b32 m0, s55
	s_nop 0
	global_load_lds_dwordx4 v148, s[46:47]
	s_barrier
	s_waitcnt lgkmcnt(0)
	v_mfma_f32_16x16x32_bf16 v[60:63], v[128:131], v[156:159], 0
	v_mfma_f32_16x16x32_bf16 v[56:59], v[136:139], v[156:159], 0
	v_mfma_f32_16x16x32_bf16 v[48:51], v[128:131], v[172:175], 0
	v_mfma_f32_16x16x32_bf16 v[40:43], v[136:139], v[172:175], 0
	v_mfma_f32_16x16x32_bf16 v[32:35], v[128:131], v[180:183], 0
	v_mfma_f32_16x16x32_bf16 v[24:27], v[136:139], v[180:183], 0
	v_mfma_f32_16x16x32_bf16 v[16:19], v[128:131], v[188:191], 0
	v_mfma_f32_16x16x32_bf16 v[8:11], v[136:139], v[188:191], 0
	v_mfma_f32_16x16x32_bf16 v[60:63], v[132:135], v[168:171], v[60:63]
	v_mfma_f32_16x16x32_bf16 v[56:59], v[140:143], v[168:171], v[56:59]
	v_mfma_f32_16x16x32_bf16 v[48:51], v[132:135], v[176:179], v[48:51]
	v_mfma_f32_16x16x32_bf16 v[40:43], v[140:143], v[176:179], v[40:43]
	v_mfma_f32_16x16x32_bf16 v[32:35], v[132:135], v[184:187], v[32:35]
	v_mfma_f32_16x16x32_bf16 v[24:27], v[140:143], v[184:187], v[24:27]
	v_mfma_f32_16x16x32_bf16 v[16:19], v[132:135], v[192:195], v[16:19]
	v_mfma_f32_16x16x32_bf16 v[8:11], v[140:143], v[192:195], v[8:11]
	s_barrier
	s_add_u32 s72, s44, 0x80000
	s_addc_u32 s73, s45, 0
	s_add_i32 s71, s66, s54
	s_mov_b32 m0, s71
	s_nop 0
	global_load_lds_dwordx4 v146, s[72:73]
	s_add_i32 m0, s71, 0x2000
	s_nop 0
	global_load_lds_dwordx4 v148, s[72:73]
	s_waitcnt vmcnt(6)
	s_barrier
	v_mfma_f32_16x16x32_bf16 v[52:55], v[196:199], v[156:159], 0
	v_mfma_f32_16x16x32_bf16 v[44:47], v[204:207], v[156:159], 0
	v_mfma_f32_16x16x32_bf16 v[36:39], v[196:199], v[172:175], 0
	v_mfma_f32_16x16x32_bf16 v[28:31], v[204:207], v[172:175], 0
	v_mfma_f32_16x16x32_bf16 v[20:23], v[196:199], v[180:183], 0
	v_mfma_f32_16x16x32_bf16 v[12:15], v[204:207], v[180:183], 0
	v_mfma_f32_16x16x32_bf16 v[4:7], v[196:199], v[188:191], 0
	v_mfma_f32_16x16x32_bf16 v[0:3], v[204:207], v[188:191], 0
	v_mfma_f32_16x16x32_bf16 v[52:55], v[200:203], v[168:171], v[52:55]
	v_mfma_f32_16x16x32_bf16 v[44:47], v[208:211], v[168:171], v[44:47]
	v_mfma_f32_16x16x32_bf16 v[36:39], v[200:203], v[176:179], v[36:39]
	v_mfma_f32_16x16x32_bf16 v[28:31], v[208:211], v[176:179], v[28:31]
	v_mfma_f32_16x16x32_bf16 v[20:23], v[200:203], v[184:187], v[20:23]
	v_mfma_f32_16x16x32_bf16 v[12:15], v[208:211], v[184:187], v[12:15]
	v_mfma_f32_16x16x32_bf16 v[4:7], v[200:203], v[192:195], v[4:7]
	v_mfma_f32_16x16x32_bf16 v[0:3], v[208:211], v[192:195], v[0:3]
	s_add_i32 s71, 0, 0x18000
	v_add_u32_e32 v140, s71, v163
	s_barrier
	ds_read_b128 v[128:131], v140
	ds_read_b128 v[132:135], v140 offset:1024
	ds_read_b128 v[136:139], v140 offset:2048
	ds_read_b128 v[140:143], v140 offset:3072
	s_add_u32 s46, s46, 0x80000
	s_addc_u32 s47, s47, 0
	s_mov_b32 m0, s56
	ds_read_b128 v[156:159], v166 offset:32768
	ds_read_b128 v[168:171], v166 offset:33792
	ds_read_b128 v[172:175], v166 offset:34816
	ds_read_b128 v[176:179], v166 offset:35840
	ds_read_b128 v[180:183], v166 offset:36864
	ds_read_b128 v[184:187], v166 offset:37888
	ds_read_b128 v[188:191], v166 offset:38912
	ds_read_b128 v[192:195], v166 offset:39936
	global_load_lds_dwordx4 v146, s[46:47]
	s_mov_b32 m0, s57
	s_nop 0
	global_load_lds_dwordx4 v148, s[46:47]
	s_waitcnt lgkmcnt(8)
	s_barrier
	s_waitcnt lgkmcnt(0)
	v_mfma_f32_16x16x32_bf16 v[124:127], v[128:131], v[156:159], v[124:127]
	v_mfma_f32_16x16x32_bf16 v[120:123], v[136:139], v[156:159], v[120:123]
	v_mfma_f32_16x16x32_bf16 v[112:115], v[128:131], v[172:175], v[112:115]
	v_mfma_f32_16x16x32_bf16 v[104:107], v[136:139], v[172:175], v[104:107]
	v_mfma_f32_16x16x32_bf16 v[96:99], v[128:131], v[180:183], v[96:99]
	v_mfma_f32_16x16x32_bf16 v[88:91], v[136:139], v[180:183], v[88:91]
	v_mfma_f32_16x16x32_bf16 v[80:83], v[128:131], v[188:191], v[80:83]
	v_mfma_f32_16x16x32_bf16 v[72:75], v[136:139], v[188:191], v[72:75]
	v_mfma_f32_16x16x32_bf16 v[124:127], v[132:135], v[168:171], v[124:127]
	v_mfma_f32_16x16x32_bf16 v[120:123], v[140:143], v[168:171], v[120:123]
	v_mfma_f32_16x16x32_bf16 v[112:115], v[132:135], v[176:179], v[112:115]
	v_mfma_f32_16x16x32_bf16 v[104:107], v[140:143], v[176:179], v[104:107]
	v_mfma_f32_16x16x32_bf16 v[96:99], v[132:135], v[184:187], v[96:99]
	v_mfma_f32_16x16x32_bf16 v[88:91], v[140:143], v[184:187], v[88:91]
	v_mfma_f32_16x16x32_bf16 v[80:83], v[132:135], v[192:195], v[80:83]
	v_mfma_f32_16x16x32_bf16 v[72:75], v[140:143], v[192:195], v[72:75]
	s_barrier
	s_add_i32 s46, 0, 0x1c000
	s_add_i32 s47, s71, s54
	v_add_u32_e32 v208, s46, v163
	s_mov_b32 m0, s47
	ds_read_b128 v[196:199], v208
	ds_read_b128 v[200:203], v208 offset:1024
	ds_read_b128 v[204:207], v208 offset:2048
	ds_read_b128 v[208:211], v208 offset:3072
	global_load_lds_dwordx4 v146, s[98:99]
	s_add_i32 m0, s47, 0x2000
	s_nop 0
	global_load_lds_dwordx4 v148, s[98:99]
	s_barrier
	s_waitcnt lgkmcnt(0)
	v_mfma_f32_16x16x32_bf16 v[116:119], v[196:199], v[156:159], v[116:119]
	v_mfma_f32_16x16x32_bf16 v[108:111], v[204:207], v[156:159], v[108:111]
	v_mfma_f32_16x16x32_bf16 v[100:103], v[196:199], v[172:175], v[100:103]
	v_mfma_f32_16x16x32_bf16 v[92:95], v[204:207], v[172:175], v[92:95]
	v_mfma_f32_16x16x32_bf16 v[84:87], v[196:199], v[180:183], v[84:87]
	v_mfma_f32_16x16x32_bf16 v[76:79], v[204:207], v[180:183], v[76:79]
	v_mfma_f32_16x16x32_bf16 v[68:71], v[196:199], v[188:191], v[68:71]
	v_mfma_f32_16x16x32_bf16 v[64:67], v[204:207], v[188:191], v[64:67]
	v_mfma_f32_16x16x32_bf16 v[116:119], v[200:203], v[168:171], v[116:119]
	v_mfma_f32_16x16x32_bf16 v[108:111], v[208:211], v[168:171], v[108:111]
	v_mfma_f32_16x16x32_bf16 v[100:103], v[200:203], v[176:179], v[100:103]
	v_mfma_f32_16x16x32_bf16 v[92:95], v[208:211], v[176:179], v[92:95]
	v_mfma_f32_16x16x32_bf16 v[84:87], v[200:203], v[184:187], v[84:87]
	v_mfma_f32_16x16x32_bf16 v[76:79], v[208:211], v[184:187], v[76:79]
	v_mfma_f32_16x16x32_bf16 v[68:71], v[200:203], v[192:195], v[68:71]
	v_mfma_f32_16x16x32_bf16 v[64:67], v[208:211], v[192:195], v[64:67]
	s_mov_b32 m0, s61
	s_barrier
	ds_read_b128 v[156:159], v166 offset:49152
	ds_read_b128 v[168:171], v166 offset:50176
	ds_read_b128 v[172:175], v166 offset:51200
	ds_read_b128 v[176:179], v166 offset:52224
	ds_read_b128 v[180:183], v166 offset:53248
	ds_read_b128 v[184:187], v166 offset:54272
	ds_read_b128 v[188:191], v166 offset:55296
	ds_read_b128 v[192:195], v166 offset:56320
	global_load_lds_dwordx4 v146, s[100:101]
	s_mov_b32 m0, s62
	s_nop 0
	global_load_lds_dwordx4 v148, s[100:101]
	s_barrier
	s_waitcnt lgkmcnt(0)
	v_mfma_f32_16x16x32_bf16 v[60:63], v[128:131], v[156:159], v[60:63]
	v_mfma_f32_16x16x32_bf16 v[56:59], v[136:139], v[156:159], v[56:59]
	v_mfma_f32_16x16x32_bf16 v[48:51], v[128:131], v[172:175], v[48:51]
	v_mfma_f32_16x16x32_bf16 v[40:43], v[136:139], v[172:175], v[40:43]
	v_mfma_f32_16x16x32_bf16 v[32:35], v[128:131], v[180:183], v[32:35]
	v_mfma_f32_16x16x32_bf16 v[24:27], v[136:139], v[180:183], v[24:27]
	v_mfma_f32_16x16x32_bf16 v[16:19], v[128:131], v[188:191], v[16:19]
	v_mfma_f32_16x16x32_bf16 v[8:11], v[136:139], v[188:191], v[8:11]
	v_mfma_f32_16x16x32_bf16 v[60:63], v[132:135], v[168:171], v[60:63]
	v_mfma_f32_16x16x32_bf16 v[56:59], v[140:143], v[168:171], v[56:59]
	v_mfma_f32_16x16x32_bf16 v[48:51], v[132:135], v[176:179], v[48:51]
	v_mfma_f32_16x16x32_bf16 v[40:43], v[140:143], v[176:179], v[40:43]
	v_mfma_f32_16x16x32_bf16 v[32:35], v[132:135], v[184:187], v[32:35]
	v_mfma_f32_16x16x32_bf16 v[24:27], v[140:143], v[184:187], v[24:27]
	v_mfma_f32_16x16x32_bf16 v[16:19], v[132:135], v[192:195], v[16:19]
	v_mfma_f32_16x16x32_bf16 v[8:11], v[140:143], v[192:195], v[8:11]
	s_barrier
	s_add_u32 s44, s44, 0x80080
	s_addc_u32 s45, s45, 0
	s_add_i32 s46, s46, s54
	s_mov_b32 m0, s46
	s_nop 0
	global_load_lds_dwordx4 v146, s[44:45]
	s_add_i32 m0, s46, 0x2000
	s_nop 0
	global_load_lds_dwordx4 v148, s[44:45]
	s_waitcnt vmcnt(6)
	s_barrier
	v_mfma_f32_16x16x32_bf16 v[52:55], v[196:199], v[156:159], v[52:55]
	v_mfma_f32_16x16x32_bf16 v[44:47], v[204:207], v[156:159], v[44:47]
	v_mfma_f32_16x16x32_bf16 v[36:39], v[196:199], v[172:175], v[36:39]
	v_mfma_f32_16x16x32_bf16 v[28:31], v[204:207], v[172:175], v[28:31]
	v_mfma_f32_16x16x32_bf16 v[20:23], v[196:199], v[180:183], v[20:23]
	v_mfma_f32_16x16x32_bf16 v[12:15], v[204:207], v[180:183], v[12:15]
	v_mfma_f32_16x16x32_bf16 v[4:7], v[196:199], v[188:191], v[4:7]
	v_mfma_f32_16x16x32_bf16 v[0:3], v[204:207], v[188:191], v[0:3]
	v_mfma_f32_16x16x32_bf16 v[52:55], v[200:203], v[168:171], v[52:55]
	v_mfma_f32_16x16x32_bf16 v[44:47], v[208:211], v[168:171], v[44:47]
	v_mfma_f32_16x16x32_bf16 v[36:39], v[200:203], v[176:179], v[36:39]
	v_mfma_f32_16x16x32_bf16 v[28:31], v[208:211], v[176:179], v[28:31]
	v_mfma_f32_16x16x32_bf16 v[20:23], v[200:203], v[184:187], v[20:23]
	v_mfma_f32_16x16x32_bf16 v[12:15], v[208:211], v[184:187], v[12:15]
	v_mfma_f32_16x16x32_bf16 v[4:7], v[200:203], v[192:195], v[4:7]
	v_mfma_f32_16x16x32_bf16 v[0:3], v[208:211], v[192:195], v[0:3]
	s_add_i32 s70, s70, 2
	s_add_u32 s42, s42, 0x100
	s_addc_u32 s43, s43, 0
	s_add_u32 s29, s29, 0x100
	s_addc_u32 s69, s69, 0
	s_cmp_gt_u32 s70, 29
	s_barrier
	s_cbranch_scc0 .LBB0_1074
.LBB0_1074:
	ds_read_b128 v[128:131], v165
	ds_read_b128 v[132:135], v165 offset:1024
	ds_read_b128 v[136:139], v165 offset:2048
	ds_read_b128 v[140:143], v165 offset:3072
	s_add_u32 s44, s42, 0xfff80080
	s_addc_u32 s45, s43, -1
	s_cmp_eq_u32 s70, 28
	s_cselect_b32 s47, s31, s45
	s_cselect_b32 s46, s68, s44
	s_cselect_b32 s45, s19, s69
	s_cselect_b32 s44, s28, s29
	s_add_i32 m0, s41, 0xc000
	ds_read_b128 v[156:159], v166
	ds_read_b128 v[168:171], v166 offset:1024
	ds_read_b128 v[172:175], v166 offset:2048
	ds_read_b128 v[176:179], v166 offset:3072
	ds_read_b128 v[180:183], v166 offset:4096
	ds_read_b128 v[184:187], v166 offset:5120
	ds_read_b128 v[188:191], v166 offset:6144
	ds_read_b128 v[192:195], v166 offset:7168
	global_load_lds_dwordx4 v150, s[42:43]
	s_add_i32 m0, s41, 0xe000
	s_nop 0
	global_load_lds_dwordx4 v152, s[42:43]
	s_waitcnt lgkmcnt(8)
	s_barrier
	s_waitcnt lgkmcnt(0)
	v_mfma_f32_16x16x32_bf16 v[124:127], v[128:131], v[156:159], v[124:127]
	v_mfma_f32_16x16x32_bf16 v[120:123], v[136:139], v[156:159], v[120:123]
	v_mfma_f32_16x16x32_bf16 v[112:115], v[128:131], v[172:175], v[112:115]
	v_mfma_f32_16x16x32_bf16 v[104:107], v[136:139], v[172:175], v[104:107]
	v_mfma_f32_16x16x32_bf16 v[96:99], v[128:131], v[180:183], v[96:99]
	v_mfma_f32_16x16x32_bf16 v[88:91], v[136:139], v[180:183], v[88:91]
	v_mfma_f32_16x16x32_bf16 v[80:83], v[128:131], v[188:191], v[80:83]
	v_mfma_f32_16x16x32_bf16 v[72:75], v[136:139], v[188:191], v[72:75]
	v_mfma_f32_16x16x32_bf16 v[124:127], v[132:135], v[168:171], v[124:127]
	v_mfma_f32_16x16x32_bf16 v[120:123], v[140:143], v[168:171], v[120:123]
	v_mfma_f32_16x16x32_bf16 v[112:115], v[132:135], v[176:179], v[112:115]
	v_mfma_f32_16x16x32_bf16 v[104:107], v[140:143], v[176:179], v[104:107]
	v_mfma_f32_16x16x32_bf16 v[96:99], v[132:135], v[184:187], v[96:99]
	v_mfma_f32_16x16x32_bf16 v[88:91], v[140:143], v[184:187], v[88:91]
	v_mfma_f32_16x16x32_bf16 v[80:83], v[132:135], v[192:195], v[80:83]
	v_mfma_f32_16x16x32_bf16 v[72:75], v[140:143], v[192:195], v[72:75]
	s_barrier
	s_add_i32 s71, s65, s54
	s_add_u32 s98, s44, s8
	s_addc_u32 s99, s45, s9
	s_mov_b32 m0, s71
	ds_read_b128 v[196:199], v167
	ds_read_b128 v[200:203], v167 offset:1024
	ds_read_b128 v[204:207], v167 offset:2048
	ds_read_b128 v[208:211], v167 offset:3072
	global_load_lds_dwordx4 v146, s[44:45]
	s_add_i32 m0, s71, 0x2000
	s_nop 0
	global_load_lds_dwordx4 v148, s[44:45]
	s_barrier
	s_waitcnt lgkmcnt(0)
	v_mfma_f32_16x16x32_bf16 v[116:119], v[196:199], v[156:159], v[116:119]
	v_mfma_f32_16x16x32_bf16 v[108:111], v[204:207], v[156:159], v[108:111]
	v_mfma_f32_16x16x32_bf16 v[100:103], v[196:199], v[172:175], v[100:103]
	v_mfma_f32_16x16x32_bf16 v[92:95], v[204:207], v[172:175], v[92:95]
	v_mfma_f32_16x16x32_bf16 v[84:87], v[196:199], v[180:183], v[84:87]
	v_mfma_f32_16x16x32_bf16 v[76:79], v[204:207], v[180:183], v[76:79]
	v_mfma_f32_16x16x32_bf16 v[68:71], v[196:199], v[188:191], v[68:71]
	v_mfma_f32_16x16x32_bf16 v[64:67], v[204:207], v[188:191], v[64:67]
	v_mfma_f32_16x16x32_bf16 v[116:119], v[200:203], v[168:171], v[116:119]
	v_mfma_f32_16x16x32_bf16 v[108:111], v[208:211], v[168:171], v[108:111]
	v_mfma_f32_16x16x32_bf16 v[100:103], v[200:203], v[176:179], v[100:103]
	v_mfma_f32_16x16x32_bf16 v[92:95], v[208:211], v[176:179], v[92:95]
	v_mfma_f32_16x16x32_bf16 v[84:87], v[200:203], v[184:187], v[84:87]
	v_mfma_f32_16x16x32_bf16 v[76:79], v[208:211], v[184:187], v[76:79]
	v_mfma_f32_16x16x32_bf16 v[68:71], v[200:203], v[192:195], v[68:71]
	v_mfma_f32_16x16x32_bf16 v[64:67], v[208:211], v[192:195], v[64:67]
	s_mov_b32 m0, s41
	s_add_u32 s100, s46, s8
	s_addc_u32 s101, s47, s9
	s_barrier
	ds_read_b128 v[156:159], v166 offset:16384
	ds_read_b128 v[168:171], v166 offset:17408
	ds_read_b128 v[172:175], v166 offset:18432
	ds_read_b128 v[176:179], v166 offset:19456
	ds_read_b128 v[180:183], v166 offset:20480
	ds_read_b128 v[184:187], v166 offset:21504
	ds_read_b128 v[188:191], v166 offset:22528
	ds_read_b128 v[192:195], v166 offset:23552
	global_load_lds_dwordx4 v146, s[46:47]
	s_mov_b32 m0, s55
	s_nop 0
	global_load_lds_dwordx4 v148, s[46:47]
	s_barrier
	s_waitcnt lgkmcnt(0)
	v_mfma_f32_16x16x32_bf16 v[60:63], v[128:131], v[156:159], v[60:63]
	v_mfma_f32_16x16x32_bf16 v[56:59], v[136:139], v[156:159], v[56:59]
	v_mfma_f32_16x16x32_bf16 v[48:51], v[128:131], v[172:175], v[48:51]
	v_mfma_f32_16x16x32_bf16 v[40:43], v[136:139], v[172:175], v[40:43]
	v_mfma_f32_16x16x32_bf16 v[32:35], v[128:131], v[180:183], v[32:35]
	v_mfma_f32_16x16x32_bf16 v[24:27], v[136:139], v[180:183], v[24:27]
	v_mfma_f32_16x16x32_bf16 v[16:19], v[128:131], v[188:191], v[16:19]
	v_mfma_f32_16x16x32_bf16 v[8:11], v[136:139], v[188:191], v[8:11]
	v_mfma_f32_16x16x32_bf16 v[60:63], v[132:135], v[168:171], v[60:63]
	v_mfma_f32_16x16x32_bf16 v[56:59], v[140:143], v[168:171], v[56:59]
	v_mfma_f32_16x16x32_bf16 v[48:51], v[132:135], v[176:179], v[48:51]
	v_mfma_f32_16x16x32_bf16 v[40:43], v[140:143], v[176:179], v[40:43]
	v_mfma_f32_16x16x32_bf16 v[32:35], v[132:135], v[184:187], v[32:35]
	v_mfma_f32_16x16x32_bf16 v[24:27], v[140:143], v[184:187], v[24:27]
	v_mfma_f32_16x16x32_bf16 v[16:19], v[132:135], v[192:195], v[16:19]
	v_mfma_f32_16x16x32_bf16 v[8:11], v[140:143], v[192:195], v[8:11]
	s_barrier
	s_add_u32 s72, s44, 0x80000
	s_addc_u32 s73, s45, 0
	s_add_i32 s71, s66, s54
	s_mov_b32 m0, s71
	s_nop 0
	global_load_lds_dwordx4 v146, s[72:73]
	s_add_i32 m0, s71, 0x2000
	s_nop 0
	global_load_lds_dwordx4 v148, s[72:73]
	s_waitcnt vmcnt(6)
	s_barrier
	v_mfma_f32_16x16x32_bf16 v[52:55], v[196:199], v[156:159], v[52:55]
	v_mfma_f32_16x16x32_bf16 v[44:47], v[204:207], v[156:159], v[44:47]
	v_mfma_f32_16x16x32_bf16 v[36:39], v[196:199], v[172:175], v[36:39]
	v_mfma_f32_16x16x32_bf16 v[28:31], v[204:207], v[172:175], v[28:31]
	v_mfma_f32_16x16x32_bf16 v[20:23], v[196:199], v[180:183], v[20:23]
	v_mfma_f32_16x16x32_bf16 v[12:15], v[204:207], v[180:183], v[12:15]
	v_mfma_f32_16x16x32_bf16 v[4:7], v[196:199], v[188:191], v[4:7]
	v_mfma_f32_16x16x32_bf16 v[0:3], v[204:207], v[188:191], v[0:3]
	v_mfma_f32_16x16x32_bf16 v[52:55], v[200:203], v[168:171], v[52:55]
	v_mfma_f32_16x16x32_bf16 v[44:47], v[208:211], v[168:171], v[44:47]
	v_mfma_f32_16x16x32_bf16 v[36:39], v[200:203], v[176:179], v[36:39]
	v_mfma_f32_16x16x32_bf16 v[28:31], v[208:211], v[176:179], v[28:31]
	v_mfma_f32_16x16x32_bf16 v[20:23], v[200:203], v[184:187], v[20:23]
	v_mfma_f32_16x16x32_bf16 v[12:15], v[208:211], v[184:187], v[12:15]
	v_mfma_f32_16x16x32_bf16 v[4:7], v[200:203], v[192:195], v[4:7]
	v_mfma_f32_16x16x32_bf16 v[0:3], v[208:211], v[192:195], v[0:3]
	s_add_i32 s71, 0, 0x18000
	v_add_u32_e32 v140, s71, v163
	s_barrier
	ds_read_b128 v[128:131], v140
	ds_read_b128 v[132:135], v140 offset:1024
	ds_read_b128 v[136:139], v140 offset:2048
	ds_read_b128 v[140:143], v140 offset:3072
	s_add_u32 s46, s46, 0x80000
	s_addc_u32 s47, s47, 0
	s_mov_b32 m0, s56
	ds_read_b128 v[156:159], v166 offset:32768
	ds_read_b128 v[168:171], v166 offset:33792
	ds_read_b128 v[172:175], v166 offset:34816
	ds_read_b128 v[176:179], v166 offset:35840
	ds_read_b128 v[180:183], v166 offset:36864
	ds_read_b128 v[184:187], v166 offset:37888
	ds_read_b128 v[188:191], v166 offset:38912
	ds_read_b128 v[192:195], v166 offset:39936
	global_load_lds_dwordx4 v146, s[46:47]
	s_mov_b32 m0, s57
	s_nop 0
	global_load_lds_dwordx4 v148, s[46:47]
	s_waitcnt lgkmcnt(8)
	s_barrier
	s_waitcnt lgkmcnt(0)
	v_mfma_f32_16x16x32_bf16 v[124:127], v[128:131], v[156:159], v[124:127]
	v_mfma_f32_16x16x32_bf16 v[120:123], v[136:139], v[156:159], v[120:123]
	v_mfma_f32_16x16x32_bf16 v[112:115], v[128:131], v[172:175], v[112:115]
	v_mfma_f32_16x16x32_bf16 v[104:107], v[136:139], v[172:175], v[104:107]
	v_mfma_f32_16x16x32_bf16 v[96:99], v[128:131], v[180:183], v[96:99]
	v_mfma_f32_16x16x32_bf16 v[88:91], v[136:139], v[180:183], v[88:91]
	v_mfma_f32_16x16x32_bf16 v[80:83], v[128:131], v[188:191], v[80:83]
	v_mfma_f32_16x16x32_bf16 v[72:75], v[136:139], v[188:191], v[72:75]
	v_mfma_f32_16x16x32_bf16 v[124:127], v[132:135], v[168:171], v[124:127]
	v_mfma_f32_16x16x32_bf16 v[120:123], v[140:143], v[168:171], v[120:123]
	v_mfma_f32_16x16x32_bf16 v[112:115], v[132:135], v[176:179], v[112:115]
	v_mfma_f32_16x16x32_bf16 v[104:107], v[140:143], v[176:179], v[104:107]
	v_mfma_f32_16x16x32_bf16 v[96:99], v[132:135], v[184:187], v[96:99]
	v_mfma_f32_16x16x32_bf16 v[88:91], v[140:143], v[184:187], v[88:91]
	v_mfma_f32_16x16x32_bf16 v[80:83], v[132:135], v[192:195], v[80:83]
	v_mfma_f32_16x16x32_bf16 v[72:75], v[140:143], v[192:195], v[72:75]
	s_barrier
	s_add_i32 s46, 0, 0x1c000
	s_add_i32 s47, s71, s54
	v_add_u32_e32 v208, s46, v163
	s_mov_b32 m0, s47
	ds_read_b128 v[196:199], v208
	ds_read_b128 v[200:203], v208 offset:1024
	ds_read_b128 v[204:207], v208 offset:2048
	ds_read_b128 v[208:211], v208 offset:3072
	global_load_lds_dwordx4 v146, s[98:99]
	s_add_i32 m0, s47, 0x2000
	s_nop 0
	global_load_lds_dwordx4 v148, s[98:99]
	s_barrier
	s_waitcnt lgkmcnt(0)
	v_mfma_f32_16x16x32_bf16 v[116:119], v[196:199], v[156:159], v[116:119]
	v_mfma_f32_16x16x32_bf16 v[108:111], v[204:207], v[156:159], v[108:111]
	v_mfma_f32_16x16x32_bf16 v[100:103], v[196:199], v[172:175], v[100:103]
	v_mfma_f32_16x16x32_bf16 v[92:95], v[204:207], v[172:175], v[92:95]
	v_mfma_f32_16x16x32_bf16 v[84:87], v[196:199], v[180:183], v[84:87]
	v_mfma_f32_16x16x32_bf16 v[76:79], v[204:207], v[180:183], v[76:79]
	v_mfma_f32_16x16x32_bf16 v[68:71], v[196:199], v[188:191], v[68:71]
	v_mfma_f32_16x16x32_bf16 v[64:67], v[204:207], v[188:191], v[64:67]
	v_mfma_f32_16x16x32_bf16 v[116:119], v[200:203], v[168:171], v[116:119]
	v_mfma_f32_16x16x32_bf16 v[108:111], v[208:211], v[168:171], v[108:111]
	v_mfma_f32_16x16x32_bf16 v[100:103], v[200:203], v[176:179], v[100:103]
	v_mfma_f32_16x16x32_bf16 v[92:95], v[208:211], v[176:179], v[92:95]
	v_mfma_f32_16x16x32_bf16 v[84:87], v[200:203], v[184:187], v[84:87]
	v_mfma_f32_16x16x32_bf16 v[76:79], v[208:211], v[184:187], v[76:79]
	v_mfma_f32_16x16x32_bf16 v[68:71], v[200:203], v[192:195], v[68:71]
	v_mfma_f32_16x16x32_bf16 v[64:67], v[208:211], v[192:195], v[64:67]
	s_mov_b32 m0, s61
	s_barrier
	ds_read_b128 v[156:159], v166 offset:49152
	ds_read_b128 v[168:171], v166 offset:50176
	ds_read_b128 v[172:175], v166 offset:51200
	ds_read_b128 v[176:179], v166 offset:52224
	ds_read_b128 v[180:183], v166 offset:53248
	ds_read_b128 v[184:187], v166 offset:54272
	ds_read_b128 v[188:191], v166 offset:55296
	ds_read_b128 v[192:195], v166 offset:56320
	global_load_lds_dwordx4 v146, s[100:101]
	s_mov_b32 m0, s62
	s_nop 0
	global_load_lds_dwordx4 v148, s[100:101]
	s_barrier
	s_waitcnt lgkmcnt(0)
	v_mfma_f32_16x16x32_bf16 v[60:63], v[128:131], v[156:159], v[60:63]
	v_mfma_f32_16x16x32_bf16 v[56:59], v[136:139], v[156:159], v[56:59]
	v_mfma_f32_16x16x32_bf16 v[48:51], v[128:131], v[172:175], v[48:51]
	v_mfma_f32_16x16x32_bf16 v[40:43], v[136:139], v[172:175], v[40:43]
	v_mfma_f32_16x16x32_bf16 v[32:35], v[128:131], v[180:183], v[32:35]
	v_mfma_f32_16x16x32_bf16 v[24:27], v[136:139], v[180:183], v[24:27]
	v_mfma_f32_16x16x32_bf16 v[16:19], v[128:131], v[188:191], v[16:19]
	v_mfma_f32_16x16x32_bf16 v[8:11], v[136:139], v[188:191], v[8:11]
	v_mfma_f32_16x16x32_bf16 v[60:63], v[132:135], v[168:171], v[60:63]
	v_mfma_f32_16x16x32_bf16 v[56:59], v[140:143], v[168:171], v[56:59]
	v_mfma_f32_16x16x32_bf16 v[48:51], v[132:135], v[176:179], v[48:51]
	v_mfma_f32_16x16x32_bf16 v[40:43], v[140:143], v[176:179], v[40:43]
	v_mfma_f32_16x16x32_bf16 v[32:35], v[132:135], v[184:187], v[32:35]
	v_mfma_f32_16x16x32_bf16 v[24:27], v[140:143], v[184:187], v[24:27]
	v_mfma_f32_16x16x32_bf16 v[16:19], v[132:135], v[192:195], v[16:19]
	v_mfma_f32_16x16x32_bf16 v[8:11], v[140:143], v[192:195], v[8:11]
	s_barrier
	s_add_u32 s44, s44, 0x80080
	s_addc_u32 s45, s45, 0
	s_add_i32 s46, s46, s54
	s_mov_b32 m0, s46
	s_nop 0
	global_load_lds_dwordx4 v146, s[44:45]
	s_add_i32 m0, s46, 0x2000
	s_nop 0
	global_load_lds_dwordx4 v148, s[44:45]
	s_waitcnt vmcnt(6)
	s_barrier
	v_mfma_f32_16x16x32_bf16 v[52:55], v[196:199], v[156:159], v[52:55]
	v_mfma_f32_16x16x32_bf16 v[44:47], v[204:207], v[156:159], v[44:47]
	v_mfma_f32_16x16x32_bf16 v[36:39], v[196:199], v[172:175], v[36:39]
	v_mfma_f32_16x16x32_bf16 v[28:31], v[204:207], v[172:175], v[28:31]
	v_mfma_f32_16x16x32_bf16 v[20:23], v[196:199], v[180:183], v[20:23]
	v_mfma_f32_16x16x32_bf16 v[12:15], v[204:207], v[180:183], v[12:15]
	v_mfma_f32_16x16x32_bf16 v[4:7], v[196:199], v[188:191], v[4:7]
	v_mfma_f32_16x16x32_bf16 v[0:3], v[204:207], v[188:191], v[0:3]
	v_mfma_f32_16x16x32_bf16 v[52:55], v[200:203], v[168:171], v[52:55]
	v_mfma_f32_16x16x32_bf16 v[44:47], v[208:211], v[168:171], v[44:47]
	v_mfma_f32_16x16x32_bf16 v[36:39], v[200:203], v[176:179], v[36:39]
	v_mfma_f32_16x16x32_bf16 v[28:31], v[208:211], v[176:179], v[28:31]
	v_mfma_f32_16x16x32_bf16 v[20:23], v[200:203], v[184:187], v[20:23]
	v_mfma_f32_16x16x32_bf16 v[12:15], v[208:211], v[184:187], v[12:15]
	v_mfma_f32_16x16x32_bf16 v[4:7], v[200:203], v[192:195], v[4:7]
	v_mfma_f32_16x16x32_bf16 v[0:3], v[208:211], v[192:195], v[0:3]
	s_add_i32 s70, s70, 2
	s_add_u32 s42, s42, 0x100
	s_addc_u32 s43, s43, 0
	s_add_u32 s29, s29, 0x100
	s_addc_u32 s69, s69, 0
	s_cmp_gt_u32 s70, 29
	s_barrier
	s_cbranch_scc0 .LBB0_1074
	s_ashr_i32 s19, s40, 3
	v_lshl_add_u32 v160, s40, 8, v162
	v_lshl_or_b32 v158, s67, 8, v164
	s_mul_hi_i32 s29, s19, 0xc000
	s_mul_i32 s19, s19, 0xc000
	v_ashrrev_i32_e32 v161, 31, v160
	s_add_u32 s28, s59, s19
	v_ashrrev_i32_e32 v159, 31, v158
	v_lshlrev_b64 v[130:131], 11, v[160:161]
	s_addc_u32 s29, s60, s29
	v_lshl_add_u64 v[156:157], v[130:131], 0, v[158:159]
	v_lshl_add_u64 v[128:129], v[158:159], 2, s[28:29]
	v_lshl_add_u64 v[172:173], v[156:157], 2, s[52:53]
	global_load_dwordx4 v[136:139], v[128:129], off
	v_lshlrev_b64 v[174:175], 1, v[156:157]
	v_lshl_add_u64 v[176:177], s[6:7], 0, v[174:175]
	global_load_dwordx4 v[140:143], v[128:129], off offset:64
	global_load_dwordx4 v[132:135], v[128:129], off offset:512
	s_nop 0
	global_load_dwordx4 v[128:131], v[128:129], off offset:576
	s_mov_b32 s67, s18
	s_mov_b32 s40, s30
	s_mov_b64 s[44:45], s[38:39]
	s_mov_b64 s[42:43], s[36:37]
	s_mov_b32 s29, 0
	global_load_dwordx4 v[180:183], v[172:173], off
	global_load_dwordx4 v[184:187], v[172:173], off offset:64
	global_load_dwordx4 v[188:191], v[172:173], off offset:512
	global_load_dwordx4 v[192:195], v[172:173], off offset:576
	s_mov_b32 s28, 0x20000
	v_lshl_add_u64 v[168:169], v[172:173], 0, s[28:29]
	global_load_dwordx4 v[196:199], v[168:169], off
	global_load_dwordx4 v[200:203], v[168:169], off offset:64
	global_load_dwordx4 v[204:207], v[168:169], off offset:512
	global_load_dwordx4 v[208:211], v[168:169], off offset:576
	s_mov_b32 s28, 0x40000
	v_lshl_add_u64 v[168:169], v[172:173], 0, s[28:29]
	global_load_dwordx4 v[212:215], v[168:169], off
	global_load_dwordx4 v[216:219], v[168:169], off offset:64
	global_load_dwordx4 v[220:223], v[168:169], off offset:512
	global_load_dwordx4 v[224:227], v[168:169], off offset:576
	s_mov_b32 s28, 0x60000
	v_lshl_add_u64 v[168:169], v[172:173], 0, s[28:29]
	global_load_dwordx4 v[228:231], v[168:169], off
	global_load_dwordx4 v[232:235], v[168:169], off offset:64
	global_load_dwordx4 v[236:239], v[168:169], off offset:512
	global_load_dwordx4 v[240:243], v[168:169], off offset:576
	s_mov_b32 s28, 0x100000
	v_lshl_add_u64 v[168:169], v[172:173], 0, s[28:29]
	s_waitcnt vmcnt(15)
	v_pk_fma_f32 v[124:125], v[124:125], v[136:137], v[180:181]
	v_pk_fma_f32 v[126:127], v[126:127], v[138:139], v[182:183]
	v_cvt_pk_bf16_f32 v124, v124, v125
	v_cvt_pk_bf16_f32 v125, v126, v127
	global_store_dwordx2 v[176:177], v[124:125], off
	global_load_dwordx4 v[180:183], v[168:169], off
	s_waitcnt vmcnt(16)
	v_pk_fma_f32 v[120:121], v[120:121], v[140:141], v[184:185]
	v_pk_fma_f32 v[122:123], v[122:123], v[142:143], v[186:187]
	v_cvt_pk_bf16_f32 v120, v120, v121
	v_cvt_pk_bf16_f32 v121, v122, v123
	global_store_dwordx2 v[176:177], v[120:121], off offset:32
	global_load_dwordx4 v[184:187], v[168:169], off offset:64
	s_waitcnt vmcnt(17)
	v_pk_fma_f32 v[116:117], v[116:117], v[132:133], v[188:189]
	v_pk_fma_f32 v[118:119], v[118:119], v[134:135], v[190:191]
	v_cvt_pk_bf16_f32 v116, v116, v117
	v_cvt_pk_bf16_f32 v117, v118, v119
	global_store_dwordx2 v[176:177], v[116:117], off offset:256
	global_load_dwordx4 v[188:191], v[168:169], off offset:512
	s_waitcnt vmcnt(18)
	v_pk_fma_f32 v[108:109], v[108:109], v[128:129], v[192:193]
	v_pk_fma_f32 v[110:111], v[110:111], v[130:131], v[194:195]
	v_cvt_pk_bf16_f32 v108, v108, v109
	v_cvt_pk_bf16_f32 v109, v110, v111
	global_store_dwordx2 v[176:177], v[108:109], off offset:288
	global_load_dwordx4 v[192:195], v[168:169], off offset:576
	s_mov_b32 s28, 0x10000
	v_lshl_add_u64 v[170:171], v[176:177], 0, s[28:29]
	s_mov_b32 s28, 0x120000
	v_lshl_add_u64 v[168:169], v[172:173], 0, s[28:29]
	s_waitcnt vmcnt(19)
	v_pk_fma_f32 v[112:113], v[112:113], v[136:137], v[196:197]
	v_pk_fma_f32 v[114:115], v[114:115], v[138:139], v[198:199]
	v_cvt_pk_bf16_f32 v112, v112, v113
	v_cvt_pk_bf16_f32 v113, v114, v115
	global_store_dwordx2 v[170:171], v[112:113], off
	global_load_dwordx4 v[196:199], v[168:169], off
	s_waitcnt vmcnt(20)
	v_pk_fma_f32 v[104:105], v[104:105], v[140:141], v[200:201]
	v_pk_fma_f32 v[106:107], v[106:107], v[142:143], v[202:203]
	v_cvt_pk_bf16_f32 v104, v104, v105
	v_cvt_pk_bf16_f32 v105, v106, v107
	global_store_dwordx2 v[170:171], v[104:105], off offset:32
	global_load_dwordx4 v[200:203], v[168:169], off offset:64
	s_waitcnt vmcnt(21)
	v_pk_fma_f32 v[100:101], v[100:101], v[132:133], v[204:205]
	v_pk_fma_f32 v[102:103], v[102:103], v[134:135], v[206:207]
	v_cvt_pk_bf16_f32 v100, v100, v101
	v_cvt_pk_bf16_f32 v101, v102, v103
	global_store_dwordx2 v[170:171], v[100:101], off offset:256
	global_load_dwordx4 v[204:207], v[168:169], off offset:512
	s_waitcnt vmcnt(22)
	v_pk_fma_f32 v[92:93], v[92:93], v[128:129], v[208:209]
	v_pk_fma_f32 v[94:95], v[94:95], v[130:131], v[210:211]
	v_cvt_pk_bf16_f32 v92, v92, v93
	v_cvt_pk_bf16_f32 v93, v94, v95
	global_store_dwordx2 v[170:171], v[92:93], off offset:288
	global_load_dwordx4 v[208:211], v[168:169], off offset:576
	s_mov_b32 s28, 0x20000
	v_lshl_add_u64 v[170:171], v[176:177], 0, s[28:29]
	s_mov_b32 s28, 0x140000
	v_lshl_add_u64 v[168:169], v[172:173], 0, s[28:29]
	s_waitcnt vmcnt(23)
	v_pk_fma_f32 v[96:97], v[96:97], v[136:137], v[212:213]
	v_pk_fma_f32 v[98:99], v[98:99], v[138:139], v[214:215]
	v_cvt_pk_bf16_f32 v96, v96, v97
	v_cvt_pk_bf16_f32 v97, v98, v99
	global_store_dwordx2 v[170:171], v[96:97], off
	global_load_dwordx4 v[212:215], v[168:169], off
	s_waitcnt vmcnt(24)
	v_pk_fma_f32 v[88:89], v[88:89], v[140:141], v[216:217]
	v_pk_fma_f32 v[90:91], v[90:91], v[142:143], v[218:219]
	v_cvt_pk_bf16_f32 v88, v88, v89
	v_cvt_pk_bf16_f32 v89, v90, v91
	global_store_dwordx2 v[170:171], v[88:89], off offset:32
	global_load_dwordx4 v[216:219], v[168:169], off offset:64
	s_waitcnt vmcnt(25)
	v_pk_fma_f32 v[84:85], v[84:85], v[132:133], v[220:221]
	v_pk_fma_f32 v[86:87], v[86:87], v[134:135], v[222:223]
	v_cvt_pk_bf16_f32 v84, v84, v85
	v_cvt_pk_bf16_f32 v85, v86, v87
	global_store_dwordx2 v[170:171], v[84:85], off offset:256
	global_load_dwordx4 v[220:223], v[168:169], off offset:512
	s_waitcnt vmcnt(26)
	v_pk_fma_f32 v[76:77], v[76:77], v[128:129], v[224:225]
	v_pk_fma_f32 v[78:79], v[78:79], v[130:131], v[226:227]
	v_cvt_pk_bf16_f32 v76, v76, v77
	v_cvt_pk_bf16_f32 v77, v78, v79
	global_store_dwordx2 v[170:171], v[76:77], off offset:288
	global_load_dwordx4 v[224:227], v[168:169], off offset:576
	s_mov_b32 s28, 0x30000
	v_lshl_add_u64 v[170:171], v[176:177], 0, s[28:29]
	s_mov_b32 s28, 0x160000
	v_lshl_add_u64 v[168:169], v[172:173], 0, s[28:29]
	s_waitcnt vmcnt(27)
	v_pk_fma_f32 v[80:81], v[80:81], v[136:137], v[228:229]
	v_pk_fma_f32 v[82:83], v[82:83], v[138:139], v[230:231]
	v_cvt_pk_bf16_f32 v80, v80, v81
	v_cvt_pk_bf16_f32 v81, v82, v83
	global_store_dwordx2 v[170:171], v[80:81], off
	global_load_dwordx4 v[228:231], v[168:169], off
	s_waitcnt vmcnt(28)
	v_pk_fma_f32 v[72:73], v[72:73], v[140:141], v[232:233]
	v_pk_fma_f32 v[74:75], v[74:75], v[142:143], v[234:235]
	v_cvt_pk_bf16_f32 v72, v72, v73
	v_cvt_pk_bf16_f32 v73, v74, v75
	global_store_dwordx2 v[170:171], v[72:73], off offset:32
	global_load_dwordx4 v[232:235], v[168:169], off offset:64
	s_waitcnt vmcnt(29)
	v_pk_fma_f32 v[68:69], v[68:69], v[132:133], v[236:237]
	v_pk_fma_f32 v[70:71], v[70:71], v[134:135], v[238:239]
	v_cvt_pk_bf16_f32 v68, v68, v69
	v_cvt_pk_bf16_f32 v69, v70, v71
	global_store_dwordx2 v[170:171], v[68:69], off offset:256
	global_load_dwordx4 v[236:239], v[168:169], off offset:512
	s_waitcnt vmcnt(30)
	v_pk_fma_f32 v[64:65], v[64:65], v[128:129], v[240:241]
	v_pk_fma_f32 v[66:67], v[66:67], v[130:131], v[242:243]
	v_cvt_pk_bf16_f32 v64, v64, v65
	v_cvt_pk_bf16_f32 v65, v66, v67
	global_store_dwordx2 v[170:171], v[64:65], off offset:288
	global_load_dwordx4 v[240:243], v[168:169], off offset:576
	s_mov_b32 s28, 0x80000
	v_lshl_add_u64 v[170:171], v[176:177], 0, s[28:29]
	s_waitcnt vmcnt(30)
	v_pk_fma_f32 v[60:61], v[60:61], v[136:137], v[180:181]
	v_pk_fma_f32 v[62:63], v[62:63], v[138:139], v[182:183]
	v_cvt_pk_bf16_f32 v60, v60, v61
	v_cvt_pk_bf16_f32 v61, v62, v63
	global_store_dwordx2 v[170:171], v[60:61], off
	s_waitcnt vmcnt(29)
	v_pk_fma_f32 v[56:57], v[56:57], v[140:141], v[184:185]
	v_pk_fma_f32 v[58:59], v[58:59], v[142:143], v[186:187]
	v_cvt_pk_bf16_f32 v56, v56, v57
	v_cvt_pk_bf16_f32 v57, v58, v59
	global_store_dwordx2 v[170:171], v[56:57], off offset:32
	s_waitcnt vmcnt(28)
	v_pk_fma_f32 v[52:53], v[52:53], v[132:133], v[188:189]
	v_pk_fma_f32 v[54:55], v[54:55], v[134:135], v[190:191]
	v_cvt_pk_bf16_f32 v52, v52, v53
	v_cvt_pk_bf16_f32 v53, v54, v55
	global_store_dwordx2 v[170:171], v[52:53], off offset:256
	s_waitcnt vmcnt(27)
	v_pk_fma_f32 v[44:45], v[44:45], v[128:129], v[192:193]
	v_pk_fma_f32 v[46:47], v[46:47], v[130:131], v[194:195]
	v_cvt_pk_bf16_f32 v44, v44, v45
	v_cvt_pk_bf16_f32 v45, v46, v47
	global_store_dwordx2 v[170:171], v[44:45], off offset:288
	s_mov_b32 s28, 0x90000
	v_lshl_add_u64 v[170:171], v[176:177], 0, s[28:29]
	s_waitcnt vmcnt(26)
	v_pk_fma_f32 v[48:49], v[48:49], v[136:137], v[196:197]
	v_pk_fma_f32 v[50:51], v[50:51], v[138:139], v[198:199]
	v_cvt_pk_bf16_f32 v48, v48, v49
	v_cvt_pk_bf16_f32 v49, v50, v51
	global_store_dwordx2 v[170:171], v[48:49], off
	s_waitcnt vmcnt(25)
	v_pk_fma_f32 v[40:41], v[40:41], v[140:141], v[200:201]
	v_pk_fma_f32 v[42:43], v[42:43], v[142:143], v[202:203]
	v_cvt_pk_bf16_f32 v40, v40, v41
	v_cvt_pk_bf16_f32 v41, v42, v43
	global_store_dwordx2 v[170:171], v[40:41], off offset:32
	s_waitcnt vmcnt(24)
	v_pk_fma_f32 v[36:37], v[36:37], v[132:133], v[204:205]
	v_pk_fma_f32 v[38:39], v[38:39], v[134:135], v[206:207]
	v_cvt_pk_bf16_f32 v36, v36, v37
	v_cvt_pk_bf16_f32 v37, v38, v39
	global_store_dwordx2 v[170:171], v[36:37], off offset:256
	s_waitcnt vmcnt(23)
	v_pk_fma_f32 v[28:29], v[28:29], v[128:129], v[208:209]
	v_pk_fma_f32 v[30:31], v[30:31], v[130:131], v[210:211]
	v_cvt_pk_bf16_f32 v28, v28, v29
	v_cvt_pk_bf16_f32 v29, v30, v31
	global_store_dwordx2 v[170:171], v[28:29], off offset:288
	s_mov_b32 s28, 0xa0000
	v_lshl_add_u64 v[170:171], v[176:177], 0, s[28:29]
	s_waitcnt vmcnt(22)
	v_pk_fma_f32 v[32:33], v[32:33], v[136:137], v[212:213]
	v_pk_fma_f32 v[34:35], v[34:35], v[138:139], v[214:215]
	v_cvt_pk_bf16_f32 v32, v32, v33
	v_cvt_pk_bf16_f32 v33, v34, v35
	global_store_dwordx2 v[170:171], v[32:33], off
	s_waitcnt vmcnt(21)
	v_pk_fma_f32 v[24:25], v[24:25], v[140:141], v[216:217]
	v_pk_fma_f32 v[26:27], v[26:27], v[142:143], v[218:219]
	v_cvt_pk_bf16_f32 v24, v24, v25
	v_cvt_pk_bf16_f32 v25, v26, v27
	global_store_dwordx2 v[170:171], v[24:25], off offset:32
	s_waitcnt vmcnt(20)
	v_pk_fma_f32 v[20:21], v[20:21], v[132:133], v[220:221]
	v_pk_fma_f32 v[22:23], v[22:23], v[134:135], v[222:223]
	v_cvt_pk_bf16_f32 v20, v20, v21
	v_cvt_pk_bf16_f32 v21, v22, v23
	global_store_dwordx2 v[170:171], v[20:21], off offset:256
	s_waitcnt vmcnt(19)
	v_pk_fma_f32 v[12:13], v[12:13], v[128:129], v[224:225]
	v_pk_fma_f32 v[14:15], v[14:15], v[130:131], v[226:227]
	v_cvt_pk_bf16_f32 v12, v12, v13
	v_cvt_pk_bf16_f32 v13, v14, v15
	global_store_dwordx2 v[170:171], v[12:13], off offset:288
	s_mov_b32 s28, 0xb0000
	v_lshl_add_u64 v[170:171], v[176:177], 0, s[28:29]
	s_waitcnt vmcnt(18)
	v_pk_fma_f32 v[16:17], v[16:17], v[136:137], v[228:229]
	v_pk_fma_f32 v[18:19], v[18:19], v[138:139], v[230:231]
	v_cvt_pk_bf16_f32 v16, v16, v17
	v_cvt_pk_bf16_f32 v17, v18, v19
	global_store_dwordx2 v[170:171], v[16:17], off
	s_waitcnt vmcnt(17)
	v_pk_fma_f32 v[8:9], v[8:9], v[140:141], v[232:233]
	v_pk_fma_f32 v[10:11], v[10:11], v[142:143], v[234:235]
	v_cvt_pk_bf16_f32 v8, v8, v9
	v_cvt_pk_bf16_f32 v9, v10, v11
	global_store_dwordx2 v[170:171], v[8:9], off offset:32
	s_waitcnt vmcnt(16)
	v_pk_fma_f32 v[4:5], v[4:5], v[132:133], v[236:237]
	v_pk_fma_f32 v[6:7], v[6:7], v[134:135], v[238:239]
	v_cvt_pk_bf16_f32 v4, v4, v5
	v_cvt_pk_bf16_f32 v5, v6, v7
	global_store_dwordx2 v[170:171], v[4:5], off offset:256
	s_waitcnt vmcnt(15)
	v_pk_fma_f32 v[0:1], v[0:1], v[128:129], v[240:241]
	v_pk_fma_f32 v[2:3], v[2:3], v[130:131], v[242:243]
	v_cvt_pk_bf16_f32 v0, v0, v1
	v_cvt_pk_bf16_f32 v1, v2, v3
	global_store_dwordx2 v[170:171], v[0:1], off offset:288
	s_and_b64 vcc, exec, s[34:35]
	s_cbranch_vccz .LBB0_1065
	s_branch .LBB0_1077

.LBB0_1202:
	s_ashr_i32 s13, s12, 31
	s_xor_b64 s[16:17], s[28:29], -1
	s_lshl_b64 s[14:15], s[12:13], 20
	s_add_u32 s14, s33, s14
	s_addc_u32 s15, s40, s15
	s_and_b64 s[18:19], s[28:29], exec
	s_cselect_b32 s13, s15, s35
	s_cselect_b32 s58, s14, s34
	s_ashr_i32 s11, s10, 31
	s_lshl_b64 s[18:19], s[10:11], 20
	s_add_u32 s18, s41, s18
	s_addc_u32 s19, s42, s19
	s_and_b64 s[28:29], s[28:29], exec
	s_cselect_b32 s11, s19, s37
	s_cselect_b32 s28, s18, s36
	s_add_u32 s34, s34, 0x80080
	s_addc_u32 s35, s35, 0
	s_add_u32 s29, s36, 0x100
	s_addc_u32 s59, s37, 0
	s_mov_b32 s60, -2
	ds_read_b128 v[150:153], v147
	ds_read_b128 v[154:157], v147 offset:1024
	ds_read_b128 v[158:161], v147 offset:2048
	ds_read_b128 v[162:165], v147 offset:3072
	s_add_u32 s36, s34, 0xfff80080
	s_addc_u32 s37, s35, -1
	s_cmp_eq_u32 s60, 28
	s_cselect_b32 s39, s13, s37
	s_cselect_b32 s38, s58, s36
	s_cselect_b32 s37, s11, s59
	s_cselect_b32 s36, s28, s29
	s_add_i32 m0, s31, 0xc000
	ds_read_b128 v[166:169], v148
	ds_read_b128 v[170:173], v148 offset:1024
	ds_read_b128 v[174:177], v148 offset:2048
	ds_read_b128 v[178:181], v148 offset:3072
	ds_read_b128 v[182:185], v148 offset:4096
	ds_read_b128 v[186:189], v148 offset:5120
	ds_read_b128 v[190:193], v148 offset:6144
	ds_read_b128 v[194:197], v148 offset:7168
	global_load_lds_dwordx4 v136, s[34:35]
	s_add_i32 m0, s31, 0xe000
	s_nop 0
	global_load_lds_dwordx4 v138, s[34:35]
	s_waitcnt lgkmcnt(8)
	s_barrier
	s_waitcnt lgkmcnt(0)
	v_mfma_f32_16x16x32_bf16 v[124:127], v[150:153], v[166:169], 0
	v_mfma_f32_16x16x32_bf16 v[120:123], v[158:161], v[166:169], 0
	v_mfma_f32_16x16x32_bf16 v[108:111], v[150:153], v[174:177], 0
	v_mfma_f32_16x16x32_bf16 v[104:107], v[158:161], v[174:177], 0
	v_mfma_f32_16x16x32_bf16 v[92:95], v[150:153], v[182:185], 0
	v_mfma_f32_16x16x32_bf16 v[88:91], v[158:161], v[182:185], 0
	v_mfma_f32_16x16x32_bf16 v[76:79], v[150:153], v[190:193], 0
	v_mfma_f32_16x16x32_bf16 v[72:75], v[158:161], v[190:193], 0
	v_mfma_f32_16x16x32_bf16 v[124:127], v[154:157], v[170:173], v[124:127]
	v_mfma_f32_16x16x32_bf16 v[120:123], v[162:165], v[170:173], v[120:123]
	v_mfma_f32_16x16x32_bf16 v[108:111], v[154:157], v[178:181], v[108:111]
	v_mfma_f32_16x16x32_bf16 v[104:107], v[162:165], v[178:181], v[104:107]
	v_mfma_f32_16x16x32_bf16 v[92:95], v[154:157], v[186:189], v[92:95]
	v_mfma_f32_16x16x32_bf16 v[88:91], v[162:165], v[186:189], v[88:91]
	v_mfma_f32_16x16x32_bf16 v[76:79], v[154:157], v[194:197], v[76:79]
	v_mfma_f32_16x16x32_bf16 v[72:75], v[162:165], v[194:197], v[72:75]
	s_barrier
	s_add_i32 s61, s54, s43
	s_add_u32 s98, s36, s8
	s_addc_u32 s99, s37, s9
	s_mov_b32 m0, s61
	ds_read_b128 v[198:201], v149
	ds_read_b128 v[202:205], v149 offset:1024
	ds_read_b128 v[206:209], v149 offset:2048
	ds_read_b128 v[210:213], v149 offset:3072
	global_load_lds_dwordx4 v132, s[36:37]
	s_add_i32 m0, s61, 0x2000
	s_nop 0
	global_load_lds_dwordx4 v128, s[36:37]
	s_barrier
	s_waitcnt lgkmcnt(0)
	v_mfma_f32_16x16x32_bf16 v[116:119], v[198:201], v[166:169], 0
	v_mfma_f32_16x16x32_bf16 v[112:115], v[206:209], v[166:169], 0
	v_mfma_f32_16x16x32_bf16 v[100:103], v[198:201], v[174:177], 0
	v_mfma_f32_16x16x32_bf16 v[96:99], v[206:209], v[174:177], 0
	v_mfma_f32_16x16x32_bf16 v[84:87], v[198:201], v[182:185], 0
	v_mfma_f32_16x16x32_bf16 v[80:83], v[206:209], v[182:185], 0
	v_mfma_f32_16x16x32_bf16 v[68:71], v[198:201], v[190:193], 0
	v_mfma_f32_16x16x32_bf16 v[64:67], v[206:209], v[190:193], 0
	v_mfma_f32_16x16x32_bf16 v[116:119], v[202:205], v[170:173], v[116:119]
	v_mfma_f32_16x16x32_bf16 v[112:115], v[210:213], v[170:173], v[112:115]
	v_mfma_f32_16x16x32_bf16 v[100:103], v[202:205], v[178:181], v[100:103]
	v_mfma_f32_16x16x32_bf16 v[96:99], v[210:213], v[178:181], v[96:99]
	v_mfma_f32_16x16x32_bf16 v[84:87], v[202:205], v[186:189], v[84:87]
	v_mfma_f32_16x16x32_bf16 v[80:83], v[210:213], v[186:189], v[80:83]
	v_mfma_f32_16x16x32_bf16 v[68:71], v[202:205], v[194:197], v[68:71]
	v_mfma_f32_16x16x32_bf16 v[64:67], v[210:213], v[194:197], v[64:67]
	s_mov_b32 m0, s31
	s_add_u32 s100, s38, s8
	s_addc_u32 s101, s39, s9
	s_barrier
	ds_read_b128 v[166:169], v148 offset:16384
	ds_read_b128 v[170:173], v148 offset:17408
	ds_read_b128 v[174:177], v148 offset:18432
	ds_read_b128 v[178:181], v148 offset:19456
	ds_read_b128 v[182:185], v148 offset:20480
	ds_read_b128 v[186:189], v148 offset:21504
	ds_read_b128 v[190:193], v148 offset:22528
	ds_read_b128 v[194:197], v148 offset:23552
	global_load_lds_dwordx4 v134, s[38:39]
	s_mov_b32 m0, s46
	s_nop 0
	global_load_lds_dwordx4 v130, s[38:39]
	s_barrier
	s_waitcnt lgkmcnt(0)
	v_mfma_f32_16x16x32_bf16 v[60:63], v[150:153], v[166:169], 0
	v_mfma_f32_16x16x32_bf16 v[56:59], v[158:161], v[166:169], 0
	v_mfma_f32_16x16x32_bf16 v[44:47], v[150:153], v[174:177], 0
	v_mfma_f32_16x16x32_bf16 v[40:43], v[158:161], v[174:177], 0
	v_mfma_f32_16x16x32_bf16 v[28:31], v[150:153], v[182:185], 0
	v_mfma_f32_16x16x32_bf16 v[24:27], v[158:161], v[182:185], 0
	v_mfma_f32_16x16x32_bf16 v[12:15], v[150:153], v[190:193], 0
	v_mfma_f32_16x16x32_bf16 v[8:11], v[158:161], v[190:193], 0
	v_mfma_f32_16x16x32_bf16 v[60:63], v[154:157], v[170:173], v[60:63]
	v_mfma_f32_16x16x32_bf16 v[56:59], v[162:165], v[170:173], v[56:59]
	v_mfma_f32_16x16x32_bf16 v[44:47], v[154:157], v[178:181], v[44:47]
	v_mfma_f32_16x16x32_bf16 v[40:43], v[162:165], v[178:181], v[40:43]
	v_mfma_f32_16x16x32_bf16 v[28:31], v[154:157], v[186:189], v[28:31]
	v_mfma_f32_16x16x32_bf16 v[24:27], v[162:165], v[186:189], v[24:27]
	v_mfma_f32_16x16x32_bf16 v[12:15], v[154:157], v[194:197], v[12:15]
	v_mfma_f32_16x16x32_bf16 v[8:11], v[162:165], v[194:197], v[8:11]
	s_barrier
	s_add_u32 s62, s36, 0x80000
	s_addc_u32 s63, s37, 0
	s_add_i32 s61, s55, s43
	s_mov_b32 m0, s61
	s_nop 0
	global_load_lds_dwordx4 v132, s[62:63]
	s_add_i32 m0, s61, 0x2000
	s_nop 0
	global_load_lds_dwordx4 v128, s[62:63]
	s_waitcnt vmcnt(6)
	s_barrier
	v_mfma_f32_16x16x32_bf16 v[52:55], v[198:201], v[166:169], 0
	v_mfma_f32_16x16x32_bf16 v[48:51], v[206:209], v[166:169], 0
	v_mfma_f32_16x16x32_bf16 v[36:39], v[198:201], v[174:177], 0
	v_mfma_f32_16x16x32_bf16 v[32:35], v[206:209], v[174:177], 0
	v_mfma_f32_16x16x32_bf16 v[20:23], v[198:201], v[182:185], 0
	v_mfma_f32_16x16x32_bf16 v[16:19], v[206:209], v[182:185], 0
	v_mfma_f32_16x16x32_bf16 v[4:7], v[198:201], v[190:193], 0
	v_mfma_f32_16x16x32_bf16 v[0:3], v[206:209], v[190:193], 0
	v_mfma_f32_16x16x32_bf16 v[52:55], v[202:205], v[170:173], v[52:55]
	v_mfma_f32_16x16x32_bf16 v[48:51], v[210:213], v[170:173], v[48:51]
	v_mfma_f32_16x16x32_bf16 v[36:39], v[202:205], v[178:181], v[36:39]
	v_mfma_f32_16x16x32_bf16 v[32:35], v[210:213], v[178:181], v[32:35]
	v_mfma_f32_16x16x32_bf16 v[20:23], v[202:205], v[186:189], v[20:23]
	v_mfma_f32_16x16x32_bf16 v[16:19], v[210:213], v[186:189], v[16:19]
	v_mfma_f32_16x16x32_bf16 v[4:7], v[202:205], v[194:197], v[4:7]
	v_mfma_f32_16x16x32_bf16 v[0:3], v[210:213], v[194:197], v[0:3]
	s_add_i32 s61, 0, 0x18000
	v_add_u32_e32 v162, s61, v143
	s_barrier
	ds_read_b128 v[150:153], v162
	ds_read_b128 v[154:157], v162 offset:1024
	ds_read_b128 v[158:161], v162 offset:2048
	ds_read_b128 v[162:165], v162 offset:3072
	s_add_u32 s38, s38, 0x80000
	s_addc_u32 s39, s39, 0
	s_mov_b32 m0, s47
	ds_read_b128 v[166:169], v148 offset:32768
	ds_read_b128 v[170:173], v148 offset:33792
	ds_read_b128 v[174:177], v148 offset:34816
	ds_read_b128 v[178:181], v148 offset:35840
	ds_read_b128 v[182:185], v148 offset:36864
	ds_read_b128 v[186:189], v148 offset:37888
	ds_read_b128 v[190:193], v148 offset:38912
	ds_read_b128 v[194:197], v148 offset:39936
	global_load_lds_dwordx4 v134, s[38:39]
	s_mov_b32 m0, s48
	s_nop 0
	global_load_lds_dwordx4 v130, s[38:39]
	s_waitcnt lgkmcnt(8)
	s_barrier
	s_waitcnt lgkmcnt(0)
	v_mfma_f32_16x16x32_bf16 v[124:127], v[150:153], v[166:169], v[124:127]
	v_mfma_f32_16x16x32_bf16 v[120:123], v[158:161], v[166:169], v[120:123]
	v_mfma_f32_16x16x32_bf16 v[108:111], v[150:153], v[174:177], v[108:111]
	v_mfma_f32_16x16x32_bf16 v[104:107], v[158:161], v[174:177], v[104:107]
	v_mfma_f32_16x16x32_bf16 v[92:95], v[150:153], v[182:185], v[92:95]
	v_mfma_f32_16x16x32_bf16 v[88:91], v[158:161], v[182:185], v[88:91]
	v_mfma_f32_16x16x32_bf16 v[76:79], v[150:153], v[190:193], v[76:79]
	v_mfma_f32_16x16x32_bf16 v[72:75], v[158:161], v[190:193], v[72:75]
	v_mfma_f32_16x16x32_bf16 v[124:127], v[154:157], v[170:173], v[124:127]
	v_mfma_f32_16x16x32_bf16 v[120:123], v[162:165], v[170:173], v[120:123]
	v_mfma_f32_16x16x32_bf16 v[108:111], v[154:157], v[178:181], v[108:111]
	v_mfma_f32_16x16x32_bf16 v[104:107], v[162:165], v[178:181], v[104:107]
	v_mfma_f32_16x16x32_bf16 v[92:95], v[154:157], v[186:189], v[92:95]
	v_mfma_f32_16x16x32_bf16 v[88:91], v[162:165], v[186:189], v[88:91]
	v_mfma_f32_16x16x32_bf16 v[76:79], v[154:157], v[194:197], v[76:79]
	v_mfma_f32_16x16x32_bf16 v[72:75], v[162:165], v[194:197], v[72:75]
	s_barrier
	s_add_i32 s38, 0, 0x1c000
	s_add_i32 s39, s61, s43
	v_add_u32_e32 v210, s38, v143
	s_mov_b32 m0, s39
	ds_read_b128 v[198:201], v210
	ds_read_b128 v[202:205], v210 offset:1024
	ds_read_b128 v[206:209], v210 offset:2048
	ds_read_b128 v[210:213], v210 offset:3072
	global_load_lds_dwordx4 v132, s[98:99]
	s_add_i32 m0, s39, 0x2000
	s_nop 0
	global_load_lds_dwordx4 v128, s[98:99]
	s_barrier
	s_waitcnt lgkmcnt(0)
	v_mfma_f32_16x16x32_bf16 v[116:119], v[198:201], v[166:169], v[116:119]
	v_mfma_f32_16x16x32_bf16 v[112:115], v[206:209], v[166:169], v[112:115]
	v_mfma_f32_16x16x32_bf16 v[100:103], v[198:201], v[174:177], v[100:103]
	v_mfma_f32_16x16x32_bf16 v[96:99], v[206:209], v[174:177], v[96:99]
	v_mfma_f32_16x16x32_bf16 v[84:87], v[198:201], v[182:185], v[84:87]
	v_mfma_f32_16x16x32_bf16 v[80:83], v[206:209], v[182:185], v[80:83]
	v_mfma_f32_16x16x32_bf16 v[68:71], v[198:201], v[190:193], v[68:71]
	v_mfma_f32_16x16x32_bf16 v[64:67], v[206:209], v[190:193], v[64:67]
	v_mfma_f32_16x16x32_bf16 v[116:119], v[202:205], v[170:173], v[116:119]
	v_mfma_f32_16x16x32_bf16 v[112:115], v[210:213], v[170:173], v[112:115]
	v_mfma_f32_16x16x32_bf16 v[100:103], v[202:205], v[178:181], v[100:103]
	v_mfma_f32_16x16x32_bf16 v[96:99], v[210:213], v[178:181], v[96:99]
	v_mfma_f32_16x16x32_bf16 v[84:87], v[202:205], v[186:189], v[84:87]
	v_mfma_f32_16x16x32_bf16 v[80:83], v[210:213], v[186:189], v[80:83]
	v_mfma_f32_16x16x32_bf16 v[68:71], v[202:205], v[194:197], v[68:71]
	v_mfma_f32_16x16x32_bf16 v[64:67], v[210:213], v[194:197], v[64:67]
	s_mov_b32 m0, s50
	s_barrier
	ds_read_b128 v[166:169], v148 offset:49152
	ds_read_b128 v[170:173], v148 offset:50176
	ds_read_b128 v[174:177], v148 offset:51200
	ds_read_b128 v[178:181], v148 offset:52224
	ds_read_b128 v[182:185], v148 offset:53248
	ds_read_b128 v[186:189], v148 offset:54272
	ds_read_b128 v[190:193], v148 offset:55296
	ds_read_b128 v[194:197], v148 offset:56320
	global_load_lds_dwordx4 v134, s[100:101]
	s_mov_b32 m0, s51
	s_nop 0
	global_load_lds_dwordx4 v130, s[100:101]
	s_barrier
	s_waitcnt lgkmcnt(0)
	v_mfma_f32_16x16x32_bf16 v[60:63], v[150:153], v[166:169], v[60:63]
	v_mfma_f32_16x16x32_bf16 v[56:59], v[158:161], v[166:169], v[56:59]
	v_mfma_f32_16x16x32_bf16 v[44:47], v[150:153], v[174:177], v[44:47]
	v_mfma_f32_16x16x32_bf16 v[40:43], v[158:161], v[174:177], v[40:43]
	v_mfma_f32_16x16x32_bf16 v[28:31], v[150:153], v[182:185], v[28:31]
	v_mfma_f32_16x16x32_bf16 v[24:27], v[158:161], v[182:185], v[24:27]
	v_mfma_f32_16x16x32_bf16 v[12:15], v[150:153], v[190:193], v[12:15]
	v_mfma_f32_16x16x32_bf16 v[8:11], v[158:161], v[190:193], v[8:11]
	v_mfma_f32_16x16x32_bf16 v[60:63], v[154:157], v[170:173], v[60:63]
	v_mfma_f32_16x16x32_bf16 v[56:59], v[162:165], v[170:173], v[56:59]
	v_mfma_f32_16x16x32_bf16 v[44:47], v[154:157], v[178:181], v[44:47]
	v_mfma_f32_16x16x32_bf16 v[40:43], v[162:165], v[178:181], v[40:43]
	v_mfma_f32_16x16x32_bf16 v[28:31], v[154:157], v[186:189], v[28:31]
	v_mfma_f32_16x16x32_bf16 v[24:27], v[162:165], v[186:189], v[24:27]
	v_mfma_f32_16x16x32_bf16 v[12:15], v[154:157], v[194:197], v[12:15]
	v_mfma_f32_16x16x32_bf16 v[8:11], v[162:165], v[194:197], v[8:11]
	s_barrier
	s_add_u32 s36, s36, 0x80080
	s_addc_u32 s37, s37, 0
	s_add_i32 s38, s38, s43
	s_mov_b32 m0, s38
	s_nop 0
	global_load_lds_dwordx4 v132, s[36:37]
	s_add_i32 m0, s38, 0x2000
	s_nop 0
	global_load_lds_dwordx4 v128, s[36:37]
	s_waitcnt vmcnt(6)
	s_barrier
	v_mfma_f32_16x16x32_bf16 v[52:55], v[198:201], v[166:169], v[52:55]
	v_mfma_f32_16x16x32_bf16 v[48:51], v[206:209], v[166:169], v[48:51]
	v_mfma_f32_16x16x32_bf16 v[36:39], v[198:201], v[174:177], v[36:39]
	v_mfma_f32_16x16x32_bf16 v[32:35], v[206:209], v[174:177], v[32:35]
	v_mfma_f32_16x16x32_bf16 v[20:23], v[198:201], v[182:185], v[20:23]
	v_mfma_f32_16x16x32_bf16 v[16:19], v[206:209], v[182:185], v[16:19]
	v_mfma_f32_16x16x32_bf16 v[4:7], v[198:201], v[190:193], v[4:7]
	v_mfma_f32_16x16x32_bf16 v[0:3], v[206:209], v[190:193], v[0:3]
	v_mfma_f32_16x16x32_bf16 v[52:55], v[202:205], v[170:173], v[52:55]
	v_mfma_f32_16x16x32_bf16 v[48:51], v[210:213], v[170:173], v[48:51]
	v_mfma_f32_16x16x32_bf16 v[36:39], v[202:205], v[178:181], v[36:39]
	v_mfma_f32_16x16x32_bf16 v[32:35], v[210:213], v[178:181], v[32:35]
	v_mfma_f32_16x16x32_bf16 v[20:23], v[202:205], v[186:189], v[20:23]
	v_mfma_f32_16x16x32_bf16 v[16:19], v[210:213], v[186:189], v[16:19]
	v_mfma_f32_16x16x32_bf16 v[4:7], v[202:205], v[194:197], v[4:7]
	v_mfma_f32_16x16x32_bf16 v[0:3], v[210:213], v[194:197], v[0:3]
	s_add_i32 s60, s60, 2
	s_add_u32 s34, s34, 0x100
	s_addc_u32 s35, s35, 0
	s_add_u32 s29, s29, 0x100
	s_addc_u32 s59, s59, 0
	s_cmp_gt_u32 s60, 29
	s_barrier
	s_cbranch_scc0 .LBB0_1203
.LBB0_1203:
	ds_read_b128 v[150:153], v147
	ds_read_b128 v[154:157], v147 offset:1024
	ds_read_b128 v[158:161], v147 offset:2048
	ds_read_b128 v[162:165], v147 offset:3072
	s_add_u32 s36, s34, 0xfff80080
	s_addc_u32 s37, s35, -1
	s_cmp_eq_u32 s60, 28
	s_cselect_b32 s39, s13, s37
	s_cselect_b32 s38, s58, s36
	s_cselect_b32 s37, s11, s59
	s_cselect_b32 s36, s28, s29
	s_add_i32 m0, s31, 0xc000
	ds_read_b128 v[166:169], v148
	ds_read_b128 v[170:173], v148 offset:1024
	ds_read_b128 v[174:177], v148 offset:2048
	ds_read_b128 v[178:181], v148 offset:3072
	ds_read_b128 v[182:185], v148 offset:4096
	ds_read_b128 v[186:189], v148 offset:5120
	ds_read_b128 v[190:193], v148 offset:6144
	ds_read_b128 v[194:197], v148 offset:7168
	global_load_lds_dwordx4 v136, s[34:35]
	s_add_i32 m0, s31, 0xe000
	s_nop 0
	global_load_lds_dwordx4 v138, s[34:35]
	s_waitcnt lgkmcnt(8)
	s_barrier
	s_waitcnt lgkmcnt(0)
	v_mfma_f32_16x16x32_bf16 v[124:127], v[150:153], v[166:169], v[124:127]
	v_mfma_f32_16x16x32_bf16 v[120:123], v[158:161], v[166:169], v[120:123]
	v_mfma_f32_16x16x32_bf16 v[108:111], v[150:153], v[174:177], v[108:111]
	v_mfma_f32_16x16x32_bf16 v[104:107], v[158:161], v[174:177], v[104:107]
	v_mfma_f32_16x16x32_bf16 v[92:95], v[150:153], v[182:185], v[92:95]
	v_mfma_f32_16x16x32_bf16 v[88:91], v[158:161], v[182:185], v[88:91]
	v_mfma_f32_16x16x32_bf16 v[76:79], v[150:153], v[190:193], v[76:79]
	v_mfma_f32_16x16x32_bf16 v[72:75], v[158:161], v[190:193], v[72:75]
	v_mfma_f32_16x16x32_bf16 v[124:127], v[154:157], v[170:173], v[124:127]
	v_mfma_f32_16x16x32_bf16 v[120:123], v[162:165], v[170:173], v[120:123]
	v_mfma_f32_16x16x32_bf16 v[108:111], v[154:157], v[178:181], v[108:111]
	v_mfma_f32_16x16x32_bf16 v[104:107], v[162:165], v[178:181], v[104:107]
	v_mfma_f32_16x16x32_bf16 v[92:95], v[154:157], v[186:189], v[92:95]
	v_mfma_f32_16x16x32_bf16 v[88:91], v[162:165], v[186:189], v[88:91]
	v_mfma_f32_16x16x32_bf16 v[76:79], v[154:157], v[194:197], v[76:79]
	v_mfma_f32_16x16x32_bf16 v[72:75], v[162:165], v[194:197], v[72:75]
	s_barrier
	s_add_i32 s61, s54, s43
	s_add_u32 s98, s36, s8
	s_addc_u32 s99, s37, s9
	s_mov_b32 m0, s61
	ds_read_b128 v[198:201], v149
	ds_read_b128 v[202:205], v149 offset:1024
	ds_read_b128 v[206:209], v149 offset:2048
	ds_read_b128 v[210:213], v149 offset:3072
	global_load_lds_dwordx4 v132, s[36:37]
	s_add_i32 m0, s61, 0x2000
	s_nop 0
	global_load_lds_dwordx4 v128, s[36:37]
	s_barrier
	s_waitcnt lgkmcnt(0)
	v_mfma_f32_16x16x32_bf16 v[116:119], v[198:201], v[166:169], v[116:119]
	v_mfma_f32_16x16x32_bf16 v[112:115], v[206:209], v[166:169], v[112:115]
	v_mfma_f32_16x16x32_bf16 v[100:103], v[198:201], v[174:177], v[100:103]
	v_mfma_f32_16x16x32_bf16 v[96:99], v[206:209], v[174:177], v[96:99]
	v_mfma_f32_16x16x32_bf16 v[84:87], v[198:201], v[182:185], v[84:87]
	v_mfma_f32_16x16x32_bf16 v[80:83], v[206:209], v[182:185], v[80:83]
	v_mfma_f32_16x16x32_bf16 v[68:71], v[198:201], v[190:193], v[68:71]
	v_mfma_f32_16x16x32_bf16 v[64:67], v[206:209], v[190:193], v[64:67]
	v_mfma_f32_16x16x32_bf16 v[116:119], v[202:205], v[170:173], v[116:119]
	v_mfma_f32_16x16x32_bf16 v[112:115], v[210:213], v[170:173], v[112:115]
	v_mfma_f32_16x16x32_bf16 v[100:103], v[202:205], v[178:181], v[100:103]
	v_mfma_f32_16x16x32_bf16 v[96:99], v[210:213], v[178:181], v[96:99]
	v_mfma_f32_16x16x32_bf16 v[84:87], v[202:205], v[186:189], v[84:87]
	v_mfma_f32_16x16x32_bf16 v[80:83], v[210:213], v[186:189], v[80:83]
	v_mfma_f32_16x16x32_bf16 v[68:71], v[202:205], v[194:197], v[68:71]
	v_mfma_f32_16x16x32_bf16 v[64:67], v[210:213], v[194:197], v[64:67]
	s_mov_b32 m0, s31
	s_add_u32 s100, s38, s8
	s_addc_u32 s101, s39, s9
	s_barrier
	ds_read_b128 v[166:169], v148 offset:16384
	ds_read_b128 v[170:173], v148 offset:17408
	ds_read_b128 v[174:177], v148 offset:18432
	ds_read_b128 v[178:181], v148 offset:19456
	ds_read_b128 v[182:185], v148 offset:20480
	ds_read_b128 v[186:189], v148 offset:21504
	ds_read_b128 v[190:193], v148 offset:22528
	ds_read_b128 v[194:197], v148 offset:23552
	global_load_lds_dwordx4 v134, s[38:39]
	s_mov_b32 m0, s46
	s_nop 0
	global_load_lds_dwordx4 v130, s[38:39]
	s_barrier
	s_waitcnt lgkmcnt(0)
	v_mfma_f32_16x16x32_bf16 v[60:63], v[150:153], v[166:169], v[60:63]
	v_mfma_f32_16x16x32_bf16 v[56:59], v[158:161], v[166:169], v[56:59]
	v_mfma_f32_16x16x32_bf16 v[44:47], v[150:153], v[174:177], v[44:47]
	v_mfma_f32_16x16x32_bf16 v[40:43], v[158:161], v[174:177], v[40:43]
	v_mfma_f32_16x16x32_bf16 v[28:31], v[150:153], v[182:185], v[28:31]
	v_mfma_f32_16x16x32_bf16 v[24:27], v[158:161], v[182:185], v[24:27]
	v_mfma_f32_16x16x32_bf16 v[12:15], v[150:153], v[190:193], v[12:15]
	v_mfma_f32_16x16x32_bf16 v[8:11], v[158:161], v[190:193], v[8:11]
	v_mfma_f32_16x16x32_bf16 v[60:63], v[154:157], v[170:173], v[60:63]
	v_mfma_f32_16x16x32_bf16 v[56:59], v[162:165], v[170:173], v[56:59]
	v_mfma_f32_16x16x32_bf16 v[44:47], v[154:157], v[178:181], v[44:47]
	v_mfma_f32_16x16x32_bf16 v[40:43], v[162:165], v[178:181], v[40:43]
	v_mfma_f32_16x16x32_bf16 v[28:31], v[154:157], v[186:189], v[28:31]
	v_mfma_f32_16x16x32_bf16 v[24:27], v[162:165], v[186:189], v[24:27]
	v_mfma_f32_16x16x32_bf16 v[12:15], v[154:157], v[194:197], v[12:15]
	v_mfma_f32_16x16x32_bf16 v[8:11], v[162:165], v[194:197], v[8:11]
	s_barrier
	s_add_u32 s62, s36, 0x80000
	s_addc_u32 s63, s37, 0
	s_add_i32 s61, s55, s43
	s_mov_b32 m0, s61
	s_nop 0
	global_load_lds_dwordx4 v132, s[62:63]
	s_add_i32 m0, s61, 0x2000
	s_nop 0
	global_load_lds_dwordx4 v128, s[62:63]
	s_waitcnt vmcnt(6)
	s_barrier
	v_mfma_f32_16x16x32_bf16 v[52:55], v[198:201], v[166:169], v[52:55]
	v_mfma_f32_16x16x32_bf16 v[48:51], v[206:209], v[166:169], v[48:51]
	v_mfma_f32_16x16x32_bf16 v[36:39], v[198:201], v[174:177], v[36:39]
	v_mfma_f32_16x16x32_bf16 v[32:35], v[206:209], v[174:177], v[32:35]
	v_mfma_f32_16x16x32_bf16 v[20:23], v[198:201], v[182:185], v[20:23]
	v_mfma_f32_16x16x32_bf16 v[16:19], v[206:209], v[182:185], v[16:19]
	v_mfma_f32_16x16x32_bf16 v[4:7], v[198:201], v[190:193], v[4:7]
	v_mfma_f32_16x16x32_bf16 v[0:3], v[206:209], v[190:193], v[0:3]
	v_mfma_f32_16x16x32_bf16 v[52:55], v[202:205], v[170:173], v[52:55]
	v_mfma_f32_16x16x32_bf16 v[48:51], v[210:213], v[170:173], v[48:51]
	v_mfma_f32_16x16x32_bf16 v[36:39], v[202:205], v[178:181], v[36:39]
	v_mfma_f32_16x16x32_bf16 v[32:35], v[210:213], v[178:181], v[32:35]
	v_mfma_f32_16x16x32_bf16 v[20:23], v[202:205], v[186:189], v[20:23]
	v_mfma_f32_16x16x32_bf16 v[16:19], v[210:213], v[186:189], v[16:19]
	v_mfma_f32_16x16x32_bf16 v[4:7], v[202:205], v[194:197], v[4:7]
	v_mfma_f32_16x16x32_bf16 v[0:3], v[210:213], v[194:197], v[0:3]
	s_add_i32 s61, 0, 0x18000
	v_add_u32_e32 v162, s61, v143
	s_barrier
	ds_read_b128 v[150:153], v162
	ds_read_b128 v[154:157], v162 offset:1024
	ds_read_b128 v[158:161], v162 offset:2048
	ds_read_b128 v[162:165], v162 offset:3072
	s_add_u32 s38, s38, 0x80000
	s_addc_u32 s39, s39, 0
	s_mov_b32 m0, s47
	ds_read_b128 v[166:169], v148 offset:32768
	ds_read_b128 v[170:173], v148 offset:33792
	ds_read_b128 v[174:177], v148 offset:34816
	ds_read_b128 v[178:181], v148 offset:35840
	ds_read_b128 v[182:185], v148 offset:36864
	ds_read_b128 v[186:189], v148 offset:37888
	ds_read_b128 v[190:193], v148 offset:38912
	ds_read_b128 v[194:197], v148 offset:39936
	global_load_lds_dwordx4 v134, s[38:39]
	s_mov_b32 m0, s48
	s_nop 0
	global_load_lds_dwordx4 v130, s[38:39]
	s_waitcnt lgkmcnt(8)
	s_barrier
	s_waitcnt lgkmcnt(0)
	v_mfma_f32_16x16x32_bf16 v[124:127], v[150:153], v[166:169], v[124:127]
	v_mfma_f32_16x16x32_bf16 v[120:123], v[158:161], v[166:169], v[120:123]
	v_mfma_f32_16x16x32_bf16 v[108:111], v[150:153], v[174:177], v[108:111]
	v_mfma_f32_16x16x32_bf16 v[104:107], v[158:161], v[174:177], v[104:107]
	v_mfma_f32_16x16x32_bf16 v[92:95], v[150:153], v[182:185], v[92:95]
	v_mfma_f32_16x16x32_bf16 v[88:91], v[158:161], v[182:185], v[88:91]
	v_mfma_f32_16x16x32_bf16 v[76:79], v[150:153], v[190:193], v[76:79]
	v_mfma_f32_16x16x32_bf16 v[72:75], v[158:161], v[190:193], v[72:75]
	v_mfma_f32_16x16x32_bf16 v[124:127], v[154:157], v[170:173], v[124:127]
	v_mfma_f32_16x16x32_bf16 v[120:123], v[162:165], v[170:173], v[120:123]
	v_mfma_f32_16x16x32_bf16 v[108:111], v[154:157], v[178:181], v[108:111]
	v_mfma_f32_16x16x32_bf16 v[104:107], v[162:165], v[178:181], v[104:107]
	v_mfma_f32_16x16x32_bf16 v[92:95], v[154:157], v[186:189], v[92:95]
	v_mfma_f32_16x16x32_bf16 v[88:91], v[162:165], v[186:189], v[88:91]
	v_mfma_f32_16x16x32_bf16 v[76:79], v[154:157], v[194:197], v[76:79]
	v_mfma_f32_16x16x32_bf16 v[72:75], v[162:165], v[194:197], v[72:75]
	s_barrier
	s_add_i32 s38, 0, 0x1c000
	s_add_i32 s39, s61, s43
	v_add_u32_e32 v210, s38, v143
	s_mov_b32 m0, s39
	ds_read_b128 v[198:201], v210
	ds_read_b128 v[202:205], v210 offset:1024
	ds_read_b128 v[206:209], v210 offset:2048
	ds_read_b128 v[210:213], v210 offset:3072
	global_load_lds_dwordx4 v132, s[98:99]
	s_add_i32 m0, s39, 0x2000
	s_nop 0
	global_load_lds_dwordx4 v128, s[98:99]
	s_barrier
	s_waitcnt lgkmcnt(0)
	v_mfma_f32_16x16x32_bf16 v[116:119], v[198:201], v[166:169], v[116:119]
	v_mfma_f32_16x16x32_bf16 v[112:115], v[206:209], v[166:169], v[112:115]
	v_mfma_f32_16x16x32_bf16 v[100:103], v[198:201], v[174:177], v[100:103]
	v_mfma_f32_16x16x32_bf16 v[96:99], v[206:209], v[174:177], v[96:99]
	v_mfma_f32_16x16x32_bf16 v[84:87], v[198:201], v[182:185], v[84:87]
	v_mfma_f32_16x16x32_bf16 v[80:83], v[206:209], v[182:185], v[80:83]
	v_mfma_f32_16x16x32_bf16 v[68:71], v[198:201], v[190:193], v[68:71]
	v_mfma_f32_16x16x32_bf16 v[64:67], v[206:209], v[190:193], v[64:67]
	v_mfma_f32_16x16x32_bf16 v[116:119], v[202:205], v[170:173], v[116:119]
	v_mfma_f32_16x16x32_bf16 v[112:115], v[210:213], v[170:173], v[112:115]
	v_mfma_f32_16x16x32_bf16 v[100:103], v[202:205], v[178:181], v[100:103]
	v_mfma_f32_16x16x32_bf16 v[96:99], v[210:213], v[178:181], v[96:99]
	v_mfma_f32_16x16x32_bf16 v[84:87], v[202:205], v[186:189], v[84:87]
	v_mfma_f32_16x16x32_bf16 v[80:83], v[210:213], v[186:189], v[80:83]
	v_mfma_f32_16x16x32_bf16 v[68:71], v[202:205], v[194:197], v[68:71]
	v_mfma_f32_16x16x32_bf16 v[64:67], v[210:213], v[194:197], v[64:67]
	s_mov_b32 m0, s50
	s_barrier
	ds_read_b128 v[166:169], v148 offset:49152
	ds_read_b128 v[170:173], v148 offset:50176
	ds_read_b128 v[174:177], v148 offset:51200
	ds_read_b128 v[178:181], v148 offset:52224
	ds_read_b128 v[182:185], v148 offset:53248
	ds_read_b128 v[186:189], v148 offset:54272
	ds_read_b128 v[190:193], v148 offset:55296
	ds_read_b128 v[194:197], v148 offset:56320
	global_load_lds_dwordx4 v134, s[100:101]
	s_mov_b32 m0, s51
	s_nop 0
	global_load_lds_dwordx4 v130, s[100:101]
	s_barrier
	s_waitcnt lgkmcnt(0)
	v_mfma_f32_16x16x32_bf16 v[60:63], v[150:153], v[166:169], v[60:63]
	v_mfma_f32_16x16x32_bf16 v[56:59], v[158:161], v[166:169], v[56:59]
	v_mfma_f32_16x16x32_bf16 v[44:47], v[150:153], v[174:177], v[44:47]
	v_mfma_f32_16x16x32_bf16 v[40:43], v[158:161], v[174:177], v[40:43]
	v_mfma_f32_16x16x32_bf16 v[28:31], v[150:153], v[182:185], v[28:31]
	v_mfma_f32_16x16x32_bf16 v[24:27], v[158:161], v[182:185], v[24:27]
	v_mfma_f32_16x16x32_bf16 v[12:15], v[150:153], v[190:193], v[12:15]
	v_mfma_f32_16x16x32_bf16 v[8:11], v[158:161], v[190:193], v[8:11]
	v_mfma_f32_16x16x32_bf16 v[60:63], v[154:157], v[170:173], v[60:63]
	v_mfma_f32_16x16x32_bf16 v[56:59], v[162:165], v[170:173], v[56:59]
	v_mfma_f32_16x16x32_bf16 v[44:47], v[154:157], v[178:181], v[44:47]
	v_mfma_f32_16x16x32_bf16 v[40:43], v[162:165], v[178:181], v[40:43]
	v_mfma_f32_16x16x32_bf16 v[28:31], v[154:157], v[186:189], v[28:31]
	v_mfma_f32_16x16x32_bf16 v[24:27], v[162:165], v[186:189], v[24:27]
	v_mfma_f32_16x16x32_bf16 v[12:15], v[154:157], v[194:197], v[12:15]
	v_mfma_f32_16x16x32_bf16 v[8:11], v[162:165], v[194:197], v[8:11]
	s_barrier
	s_add_u32 s36, s36, 0x80080
	s_addc_u32 s37, s37, 0
	s_add_i32 s38, s38, s43
	s_mov_b32 m0, s38
	s_nop 0
	global_load_lds_dwordx4 v132, s[36:37]
	s_add_i32 m0, s38, 0x2000
	s_nop 0
	global_load_lds_dwordx4 v128, s[36:37]
	s_waitcnt vmcnt(6)
	s_barrier
	v_mfma_f32_16x16x32_bf16 v[52:55], v[198:201], v[166:169], v[52:55]
	v_mfma_f32_16x16x32_bf16 v[48:51], v[206:209], v[166:169], v[48:51]
	v_mfma_f32_16x16x32_bf16 v[36:39], v[198:201], v[174:177], v[36:39]
	v_mfma_f32_16x16x32_bf16 v[32:35], v[206:209], v[174:177], v[32:35]
	v_mfma_f32_16x16x32_bf16 v[20:23], v[198:201], v[182:185], v[20:23]
	v_mfma_f32_16x16x32_bf16 v[16:19], v[206:209], v[182:185], v[16:19]
	v_mfma_f32_16x16x32_bf16 v[4:7], v[198:201], v[190:193], v[4:7]
	v_mfma_f32_16x16x32_bf16 v[0:3], v[206:209], v[190:193], v[0:3]
	v_mfma_f32_16x16x32_bf16 v[52:55], v[202:205], v[170:173], v[52:55]
	v_mfma_f32_16x16x32_bf16 v[48:51], v[210:213], v[170:173], v[48:51]
	v_mfma_f32_16x16x32_bf16 v[36:39], v[202:205], v[178:181], v[36:39]
	v_mfma_f32_16x16x32_bf16 v[32:35], v[210:213], v[178:181], v[32:35]
	v_mfma_f32_16x16x32_bf16 v[20:23], v[202:205], v[186:189], v[20:23]
	v_mfma_f32_16x16x32_bf16 v[16:19], v[210:213], v[186:189], v[16:19]
	v_mfma_f32_16x16x32_bf16 v[4:7], v[202:205], v[194:197], v[4:7]
	v_mfma_f32_16x16x32_bf16 v[0:3], v[210:213], v[194:197], v[0:3]
	s_add_i32 s60, s60, 2
	s_add_u32 s34, s34, 0x100
	s_addc_u32 s35, s35, 0
	s_add_u32 s29, s29, 0x100
	s_addc_u32 s59, s59, 0
	s_cmp_gt_u32 s60, 29
	s_barrier
	s_cbranch_scc0 .LBB0_1203
	v_pk_add_f32 v[124:125], v[124:125], 0 op_sel_hi:[1,0]
	v_pk_add_f32 v[126:127], v[126:127], 0 op_sel_hi:[1,0]
	v_mul_f32_e32 v151, 0xbfb8aa3b, v124
	v_exp_f32_e32 v151, v151
	v_mul_f32_e32 v154, 0xbfb8aa3b, v125
	v_exp_f32_e32 v155, v154
	v_pk_add_f32 v[116:117], v[116:117], 0 op_sel_hi:[1,0]
	v_add_f32_e32 v151, 1.0, v151
	v_rcp_f32_e32 v154, v151
	v_add_f32_e32 v151, 1.0, v155
	v_mul_f32_e32 v155, 0xbfb8aa3b, v126
	v_exp_f32_e32 v156, v155
	v_mul_f32_e32 v155, 0xbfb8aa3b, v127
	v_exp_f32_e32 v157, v155
	v_rcp_f32_e32 v155, v151
	v_add_f32_e32 v151, 1.0, v156
	v_rcp_f32_e32 v156, v151
	v_add_f32_e32 v151, 1.0, v157
	v_rcp_f32_e32 v157, v151
	v_pk_mul_f32 v[124:125], v[124:125], v[154:155]
	v_pk_add_f32 v[120:121], v[120:121], 0 op_sel_hi:[1,0]
	v_pk_mul_f32 v[116:117], v[124:125], v[116:117]
	v_pk_mul_f32 v[124:125], v[126:127], v[156:157]
	v_mul_f32_e32 v126, 0xbfb8aa3b, v120
	v_exp_f32_e32 v126, v126
	v_pk_add_f32 v[118:119], v[118:119], 0 op_sel_hi:[1,0]
	v_pk_add_f32 v[122:123], v[122:123], 0 op_sel_hi:[1,0]
	v_pk_mul_f32 v[118:119], v[124:125], v[118:119]
	v_mul_f32_e32 v124, 0xbfb8aa3b, v121
	v_exp_f32_e32 v125, v124
	v_add_f32_e32 v124, 1.0, v126
	v_mul_f32_e32 v126, 0xbfb8aa3b, v122
	v_mul_f32_e32 v127, 0xbfb8aa3b, v123
	v_exp_f32_e32 v126, v126
	v_exp_f32_e32 v127, v127
	v_add_f32_e32 v125, 1.0, v125
	v_rcp_f32_e32 v124, v124
	v_rcp_f32_e32 v125, v125
	v_add_f32_e32 v126, 1.0, v126
	v_add_f32_e32 v127, 1.0, v127
	v_rcp_f32_e32 v126, v126
	v_rcp_f32_e32 v127, v127
	v_pk_add_f32 v[112:113], v[112:113], 0 op_sel_hi:[1,0]
	v_pk_mul_f32 v[120:121], v[120:121], v[124:125]
	v_lshl_or_b32 v152, s57, 7, v146
	v_pk_mul_f32 v[112:113], v[120:121], v[112:113]
	v_pk_add_f32 v[114:115], v[114:115], 0 op_sel_hi:[1,0]
	v_pk_mul_f32 v[120:121], v[122:123], v[126:127]
	v_lshl_add_u32 v150, s30, 8, v142
	v_ashrrev_i32_e32 v153, 31, v152
	v_pk_mul_f32 v[114:115], v[120:121], v[114:115]
	v_cvt_pk_bf16_f32 v116, v116, v117
	v_cvt_pk_bf16_f32 v117, v118, v119
	v_cvt_pk_bf16_f32 v118, v112, v113
	v_mov_b64_e32 v[112:113], s[6:7]
	v_cvt_pk_bf16_f32 v119, v114, v115
	v_mad_i64_i32 v[120:121], s[28:29], v150, s56, v[112:113]
	v_lshlrev_b64 v[114:115], 1, v[152:153]
	v_lshl_add_u64 v[120:121], v[120:121], 0, v[114:115]
	v_pk_add_f32 v[108:109], v[108:109], 0 op_sel_hi:[1,0]
	global_store_dwordx4 v[120:121], v[116:119], off sc0 sc1
	v_mul_f32_e32 v122, 0xbfb8aa3b, v108
	v_pk_add_f32 v[110:111], v[110:111], 0 op_sel_hi:[1,0]
	v_mul_f32_e32 v116, 0xbfb8aa3b, v109
	v_exp_f32_e32 v122, v122
	v_exp_f32_e32 v117, v116
	v_mul_f32_e32 v118, 0xbfb8aa3b, v110
	v_mul_f32_e32 v119, 0xbfb8aa3b, v111
	v_exp_f32_e32 v118, v118
	v_exp_f32_e32 v119, v119
	v_add_f32_e32 v116, 1.0, v122
	v_add_f32_e32 v117, 1.0, v117
	v_rcp_f32_e32 v116, v116
	v_rcp_f32_e32 v117, v117
	v_add_f32_e32 v118, 1.0, v118
	v_add_f32_e32 v119, 1.0, v119
	v_rcp_f32_e32 v118, v118
	v_rcp_f32_e32 v119, v119
	v_pk_add_f32 v[100:101], v[100:101], 0 op_sel_hi:[1,0]
	v_pk_mul_f32 v[108:109], v[108:109], v[116:117]
	v_pk_add_f32 v[104:105], v[104:105], 0 op_sel_hi:[1,0]
	v_pk_mul_f32 v[100:101], v[108:109], v[100:101]
	v_pk_mul_f32 v[108:109], v[110:111], v[118:119]
	v_mul_f32_e32 v110, 0xbfb8aa3b, v104
	v_exp_f32_e32 v110, v110
	v_pk_add_f32 v[102:103], v[102:103], 0 op_sel_hi:[1,0]
	v_pk_add_f32 v[106:107], v[106:107], 0 op_sel_hi:[1,0]
	v_pk_mul_f32 v[102:103], v[108:109], v[102:103]
	v_mul_f32_e32 v108, 0xbfb8aa3b, v105
	v_exp_f32_e32 v109, v108
	v_add_f32_e32 v108, 1.0, v110
	v_mul_f32_e32 v110, 0xbfb8aa3b, v106
	v_mul_f32_e32 v111, 0xbfb8aa3b, v107
	v_exp_f32_e32 v110, v110
	v_exp_f32_e32 v111, v111
	v_add_f32_e32 v109, 1.0, v109
	v_rcp_f32_e32 v108, v108
	v_rcp_f32_e32 v109, v109
	v_add_f32_e32 v110, 1.0, v110
	v_add_f32_e32 v111, 1.0, v111
	v_rcp_f32_e32 v110, v110
	v_rcp_f32_e32 v111, v111
	v_pk_add_f32 v[96:97], v[96:97], 0 op_sel_hi:[1,0]
	v_pk_mul_f32 v[104:105], v[104:105], v[108:109]
	v_or_b32_e32 v108, 16, v150
	v_pk_mul_f32 v[104:105], v[104:105], v[96:97]
	v_pk_add_f32 v[96:97], v[98:99], 0 op_sel_hi:[1,0]
	v_pk_mul_f32 v[98:99], v[106:107], v[110:111]
	v_pk_add_f32 v[92:93], v[92:93], 0 op_sel_hi:[1,0]
	v_pk_mul_f32 v[106:107], v[98:99], v[96:97]
	v_cvt_pk_bf16_f32 v96, v100, v101
	v_mad_i64_i32 v[100:101], s[28:29], v108, s56, v[112:113]
	v_cvt_pk_bf16_f32 v97, v102, v103
	v_cvt_pk_bf16_f32 v98, v104, v105
	v_cvt_pk_bf16_f32 v99, v106, v107
	v_lshl_add_u64 v[100:101], v[100:101], 0, v[114:115]
	v_mul_f32_e32 v102, 0xbfb8aa3b, v92
	global_store_dwordx4 v[100:101], v[96:99], off sc0 sc1
	v_pk_add_f32 v[94:95], v[94:95], 0 op_sel_hi:[1,0]
	v_exp_f32_e32 v102, v102
	v_mul_f32_e32 v96, 0xbfb8aa3b, v93
	v_exp_f32_e32 v97, v96
	v_mul_f32_e32 v98, 0xbfb8aa3b, v94
	v_mul_f32_e32 v99, 0xbfb8aa3b, v95
	v_exp_f32_e32 v98, v98
	v_exp_f32_e32 v99, v99
	v_add_f32_e32 v96, 1.0, v102
	v_add_f32_e32 v97, 1.0, v97
	v_rcp_f32_e32 v96, v96
	v_rcp_f32_e32 v97, v97
	v_add_f32_e32 v98, 1.0, v98
	v_add_f32_e32 v99, 1.0, v99
	v_rcp_f32_e32 v98, v98
	v_rcp_f32_e32 v99, v99
	v_pk_add_f32 v[84:85], v[84:85], 0 op_sel_hi:[1,0]
	v_pk_mul_f32 v[92:93], v[92:93], v[96:97]
	v_pk_add_f32 v[88:89], v[88:89], 0 op_sel_hi:[1,0]
	v_pk_mul_f32 v[84:85], v[92:93], v[84:85]
	v_pk_mul_f32 v[92:93], v[94:95], v[98:99]
	v_mul_f32_e32 v94, 0xbfb8aa3b, v88
	v_exp_f32_e32 v94, v94
	v_pk_add_f32 v[86:87], v[86:87], 0 op_sel_hi:[1,0]
	v_pk_add_f32 v[90:91], v[90:91], 0 op_sel_hi:[1,0]
	v_pk_mul_f32 v[86:87], v[92:93], v[86:87]
	v_mul_f32_e32 v92, 0xbfb8aa3b, v89
	v_exp_f32_e32 v93, v92
	v_add_f32_e32 v92, 1.0, v94
	v_mul_f32_e32 v94, 0xbfb8aa3b, v90
	v_mul_f32_e32 v95, 0xbfb8aa3b, v91
	v_exp_f32_e32 v94, v94
	v_exp_f32_e32 v95, v95
	v_add_f32_e32 v93, 1.0, v93
	v_rcp_f32_e32 v92, v92
	v_rcp_f32_e32 v93, v93
	v_add_f32_e32 v94, 1.0, v94
	v_add_f32_e32 v95, 1.0, v95
	v_rcp_f32_e32 v94, v94
	v_rcp_f32_e32 v95, v95
	v_pk_add_f32 v[80:81], v[80:81], 0 op_sel_hi:[1,0]
	v_pk_mul_f32 v[88:89], v[88:89], v[92:93]
	v_or_b32_e32 v92, 32, v150
	v_pk_mul_f32 v[88:89], v[88:89], v[80:81]
	v_pk_add_f32 v[80:81], v[82:83], 0 op_sel_hi:[1,0]
	v_pk_mul_f32 v[82:83], v[90:91], v[94:95]
	v_pk_add_f32 v[76:77], v[76:77], 0 op_sel_hi:[1,0]
	v_pk_mul_f32 v[90:91], v[82:83], v[80:81]
	v_cvt_pk_bf16_f32 v80, v84, v85
	v_mad_i64_i32 v[84:85], s[28:29], v92, s56, v[112:113]
	v_cvt_pk_bf16_f32 v81, v86, v87
	v_cvt_pk_bf16_f32 v82, v88, v89
	v_cvt_pk_bf16_f32 v83, v90, v91
	v_lshl_add_u64 v[84:85], v[84:85], 0, v[114:115]
	v_mul_f32_e32 v86, 0xbfb8aa3b, v76
	global_store_dwordx4 v[84:85], v[80:83], off sc0 sc1
	v_pk_add_f32 v[78:79], v[78:79], 0 op_sel_hi:[1,0]
	v_exp_f32_e32 v86, v86
	v_mul_f32_e32 v80, 0xbfb8aa3b, v77
	v_exp_f32_e32 v81, v80
	v_mul_f32_e32 v82, 0xbfb8aa3b, v78
	v_mul_f32_e32 v83, 0xbfb8aa3b, v79
	v_exp_f32_e32 v82, v82
	v_exp_f32_e32 v83, v83
	v_add_f32_e32 v80, 1.0, v86
	v_add_f32_e32 v81, 1.0, v81
	v_rcp_f32_e32 v80, v80
	v_rcp_f32_e32 v81, v81
	v_add_f32_e32 v82, 1.0, v82
	v_add_f32_e32 v83, 1.0, v83
	v_rcp_f32_e32 v82, v82
	v_rcp_f32_e32 v83, v83
	v_pk_add_f32 v[68:69], v[68:69], 0 op_sel_hi:[1,0]
	v_pk_mul_f32 v[76:77], v[76:77], v[80:81]
	v_pk_add_f32 v[72:73], v[72:73], 0 op_sel_hi:[1,0]
	v_pk_mul_f32 v[68:69], v[76:77], v[68:69]
	v_pk_mul_f32 v[76:77], v[78:79], v[82:83]
	v_mul_f32_e32 v78, 0xbfb8aa3b, v72
	v_exp_f32_e32 v78, v78
	v_pk_add_f32 v[70:71], v[70:71], 0 op_sel_hi:[1,0]
	v_pk_add_f32 v[74:75], v[74:75], 0 op_sel_hi:[1,0]
	v_pk_mul_f32 v[70:71], v[76:77], v[70:71]
	v_mul_f32_e32 v76, 0xbfb8aa3b, v73
	v_exp_f32_e32 v77, v76
	v_add_f32_e32 v76, 1.0, v78
	v_mul_f32_e32 v78, 0xbfb8aa3b, v74
	v_mul_f32_e32 v79, 0xbfb8aa3b, v75
	v_exp_f32_e32 v78, v78
	v_exp_f32_e32 v79, v79
	v_add_f32_e32 v77, 1.0, v77
	v_rcp_f32_e32 v76, v76
	v_rcp_f32_e32 v77, v77
	v_add_f32_e32 v78, 1.0, v78
	v_add_f32_e32 v79, 1.0, v79
	v_rcp_f32_e32 v78, v78
	v_rcp_f32_e32 v79, v79
	v_pk_add_f32 v[64:65], v[64:65], 0 op_sel_hi:[1,0]
	v_pk_mul_f32 v[72:73], v[72:73], v[76:77]
	v_or_b32_e32 v76, 48, v150
	v_pk_mul_f32 v[72:73], v[72:73], v[64:65]
	v_pk_add_f32 v[64:65], v[66:67], 0 op_sel_hi:[1,0]
	v_pk_mul_f32 v[66:67], v[74:75], v[78:79]
	v_pk_add_f32 v[60:61], v[60:61], 0 op_sel_hi:[1,0]
	v_pk_mul_f32 v[74:75], v[66:67], v[64:65]
	v_cvt_pk_bf16_f32 v64, v68, v69
	v_mad_i64_i32 v[68:69], s[28:29], v76, s56, v[112:113]
	v_cvt_pk_bf16_f32 v65, v70, v71
	v_cvt_pk_bf16_f32 v66, v72, v73
	v_cvt_pk_bf16_f32 v67, v74, v75
	v_lshl_add_u64 v[68:69], v[68:69], 0, v[114:115]
	global_store_dwordx4 v[68:69], v[64:67], off sc0 sc1
	v_pk_add_f32 v[62:63], v[62:63], 0 op_sel_hi:[1,0]
	v_pk_add_f32 v[52:53], v[52:53], 0 op_sel_hi:[1,0]
	v_mul_f32_e32 v64, 0xbfb8aa3b, v60
	v_mul_f32_e32 v65, 0xbfb8aa3b, v61
	v_exp_f32_e32 v64, v64
	v_exp_f32_e32 v65, v65
	v_mul_f32_e32 v66, 0xbfb8aa3b, v62
	v_mul_f32_e32 v67, 0xbfb8aa3b, v63
	v_exp_f32_e32 v66, v66
	v_exp_f32_e32 v67, v67
	v_add_f32_e32 v64, 1.0, v64
	v_add_f32_e32 v65, 1.0, v65
	v_rcp_f32_e32 v64, v64
	v_rcp_f32_e32 v65, v65
	v_add_f32_e32 v66, 1.0, v66
	v_add_f32_e32 v67, 1.0, v67
	v_rcp_f32_e32 v66, v66
	v_rcp_f32_e32 v67, v67
	v_pk_mul_f32 v[60:61], v[60:61], v[64:65]
	v_pk_add_f32 v[56:57], v[56:57], 0 op_sel_hi:[1,0]
	v_pk_mul_f32 v[52:53], v[60:61], v[52:53]
	v_pk_mul_f32 v[60:61], v[62:63], v[66:67]
	v_mul_f32_e32 v62, 0xbfb8aa3b, v56
	v_exp_f32_e32 v62, v62
	v_pk_add_f32 v[54:55], v[54:55], 0 op_sel_hi:[1,0]
	v_pk_add_f32 v[58:59], v[58:59], 0 op_sel_hi:[1,0]
	v_pk_mul_f32 v[54:55], v[60:61], v[54:55]
	v_mul_f32_e32 v60, 0xbfb8aa3b, v57
	v_exp_f32_e32 v61, v60
	v_add_f32_e32 v60, 1.0, v62
	v_mul_f32_e32 v62, 0xbfb8aa3b, v58
	v_mul_f32_e32 v63, 0xbfb8aa3b, v59
	v_exp_f32_e32 v62, v62
	v_exp_f32_e32 v63, v63
	v_add_f32_e32 v61, 1.0, v61
	v_rcp_f32_e32 v60, v60
	v_rcp_f32_e32 v61, v61
	v_add_f32_e32 v62, 1.0, v62
	v_add_f32_e32 v63, 1.0, v63
	v_rcp_f32_e32 v62, v62
	v_rcp_f32_e32 v63, v63
	v_pk_add_f32 v[48:49], v[48:49], 0 op_sel_hi:[1,0]
	v_pk_mul_f32 v[56:57], v[56:57], v[60:61]
	v_add_u32_e32 v68, 0x80, v150
	v_pk_mul_f32 v[56:57], v[56:57], v[48:49]
	v_pk_add_f32 v[48:49], v[50:51], 0 op_sel_hi:[1,0]
	v_pk_mul_f32 v[50:51], v[58:59], v[62:63]
	v_pk_add_f32 v[44:45], v[44:45], 0 op_sel_hi:[1,0]
	v_pk_mul_f32 v[58:59], v[50:51], v[48:49]
	v_cvt_pk_bf16_f32 v48, v52, v53
	v_mad_i64_i32 v[52:53], s[28:29], v68, s56, v[112:113]
	v_cvt_pk_bf16_f32 v49, v54, v55
	v_cvt_pk_bf16_f32 v50, v56, v57
	v_cvt_pk_bf16_f32 v51, v58, v59
	v_lshl_add_u64 v[52:53], v[52:53], 0, v[114:115]
	v_mul_f32_e32 v54, 0xbfb8aa3b, v44
	global_store_dwordx4 v[52:53], v[48:51], off sc0 sc1
	v_pk_add_f32 v[46:47], v[46:47], 0 op_sel_hi:[1,0]
	v_exp_f32_e32 v54, v54
	v_mul_f32_e32 v48, 0xbfb8aa3b, v45
	v_exp_f32_e32 v49, v48
	v_mul_f32_e32 v50, 0xbfb8aa3b, v46
	v_mul_f32_e32 v51, 0xbfb8aa3b, v47
	v_exp_f32_e32 v50, v50
	v_exp_f32_e32 v51, v51
	v_add_f32_e32 v48, 1.0, v54
	v_add_f32_e32 v49, 1.0, v49
	v_rcp_f32_e32 v48, v48
	v_rcp_f32_e32 v49, v49
	v_add_f32_e32 v50, 1.0, v50
	v_add_f32_e32 v51, 1.0, v51
	v_rcp_f32_e32 v50, v50
	v_rcp_f32_e32 v51, v51
	v_pk_add_f32 v[36:37], v[36:37], 0 op_sel_hi:[1,0]
	v_pk_mul_f32 v[44:45], v[44:45], v[48:49]
	v_pk_add_f32 v[40:41], v[40:41], 0 op_sel_hi:[1,0]
	v_pk_mul_f32 v[36:37], v[44:45], v[36:37]
	v_pk_mul_f32 v[44:45], v[46:47], v[50:51]
	v_mul_f32_e32 v46, 0xbfb8aa3b, v40
	v_exp_f32_e32 v46, v46
	v_pk_add_f32 v[38:39], v[38:39], 0 op_sel_hi:[1,0]
	v_pk_add_f32 v[42:43], v[42:43], 0 op_sel_hi:[1,0]
	v_pk_mul_f32 v[38:39], v[44:45], v[38:39]
	v_mul_f32_e32 v44, 0xbfb8aa3b, v41
	v_exp_f32_e32 v45, v44
	v_add_f32_e32 v44, 1.0, v46
	v_mul_f32_e32 v46, 0xbfb8aa3b, v42
	v_mul_f32_e32 v47, 0xbfb8aa3b, v43
	v_exp_f32_e32 v46, v46
	v_exp_f32_e32 v47, v47
	v_add_f32_e32 v45, 1.0, v45
	v_rcp_f32_e32 v44, v44
	v_rcp_f32_e32 v45, v45
	v_add_f32_e32 v46, 1.0, v46
	v_add_f32_e32 v47, 1.0, v47
	v_rcp_f32_e32 v46, v46
	v_rcp_f32_e32 v47, v47
	v_pk_add_f32 v[32:33], v[32:33], 0 op_sel_hi:[1,0]
	v_pk_mul_f32 v[40:41], v[40:41], v[44:45]
	v_add_u32_e32 v44, 0x90, v150
	v_pk_mul_f32 v[40:41], v[40:41], v[32:33]
	v_pk_add_f32 v[32:33], v[34:35], 0 op_sel_hi:[1,0]
	v_pk_mul_f32 v[34:35], v[42:43], v[46:47]
	v_pk_add_f32 v[28:29], v[28:29], 0 op_sel_hi:[1,0]
	v_pk_mul_f32 v[42:43], v[34:35], v[32:33]
	v_cvt_pk_bf16_f32 v32, v36, v37
	v_mad_i64_i32 v[36:37], s[28:29], v44, s56, v[112:113]
	v_cvt_pk_bf16_f32 v33, v38, v39
	v_cvt_pk_bf16_f32 v34, v40, v41
	v_cvt_pk_bf16_f32 v35, v42, v43
	v_lshl_add_u64 v[36:37], v[36:37], 0, v[114:115]
	v_mul_f32_e32 v38, 0xbfb8aa3b, v28
	global_store_dwordx4 v[36:37], v[32:35], off sc0 sc1
	v_pk_add_f32 v[30:31], v[30:31], 0 op_sel_hi:[1,0]
	v_exp_f32_e32 v38, v38
	v_mul_f32_e32 v32, 0xbfb8aa3b, v29
	v_exp_f32_e32 v33, v32
	v_mul_f32_e32 v34, 0xbfb8aa3b, v30
	v_mul_f32_e32 v35, 0xbfb8aa3b, v31
	v_exp_f32_e32 v34, v34
	v_exp_f32_e32 v35, v35
	v_add_f32_e32 v32, 1.0, v38
	v_add_f32_e32 v33, 1.0, v33
	v_rcp_f32_e32 v32, v32
	v_rcp_f32_e32 v33, v33
	v_add_f32_e32 v34, 1.0, v34
	v_add_f32_e32 v35, 1.0, v35
	v_rcp_f32_e32 v34, v34
	v_rcp_f32_e32 v35, v35
	v_pk_add_f32 v[20:21], v[20:21], 0 op_sel_hi:[1,0]
	v_pk_mul_f32 v[28:29], v[28:29], v[32:33]
	v_pk_add_f32 v[24:25], v[24:25], 0 op_sel_hi:[1,0]
	v_pk_mul_f32 v[20:21], v[28:29], v[20:21]
	v_pk_mul_f32 v[28:29], v[30:31], v[34:35]
	v_mul_f32_e32 v30, 0xbfb8aa3b, v24
	v_exp_f32_e32 v30, v30
	v_pk_add_f32 v[22:23], v[22:23], 0 op_sel_hi:[1,0]
	v_pk_add_f32 v[26:27], v[26:27], 0 op_sel_hi:[1,0]
	v_pk_mul_f32 v[22:23], v[28:29], v[22:23]
	v_mul_f32_e32 v28, 0xbfb8aa3b, v25
	v_exp_f32_e32 v29, v28
	v_add_f32_e32 v28, 1.0, v30
	v_mul_f32_e32 v30, 0xbfb8aa3b, v26
	v_mul_f32_e32 v31, 0xbfb8aa3b, v27
	v_exp_f32_e32 v30, v30
	v_exp_f32_e32 v31, v31
	v_add_f32_e32 v29, 1.0, v29
	v_rcp_f32_e32 v28, v28
	v_rcp_f32_e32 v29, v29
	v_add_f32_e32 v30, 1.0, v30
	v_add_f32_e32 v31, 1.0, v31
	v_rcp_f32_e32 v30, v30
	v_rcp_f32_e32 v31, v31
	v_pk_add_f32 v[16:17], v[16:17], 0 op_sel_hi:[1,0]
	v_pk_mul_f32 v[24:25], v[24:25], v[28:29]
	v_add_u32_e32 v28, 0xa0, v150
	v_pk_mul_f32 v[24:25], v[24:25], v[16:17]
	v_pk_add_f32 v[16:17], v[18:19], 0 op_sel_hi:[1,0]
	v_pk_mul_f32 v[18:19], v[26:27], v[30:31]
	v_pk_add_f32 v[12:13], v[12:13], 0 op_sel_hi:[1,0]
	v_pk_mul_f32 v[26:27], v[18:19], v[16:17]
	v_cvt_pk_bf16_f32 v16, v20, v21
	v_mad_i64_i32 v[20:21], s[28:29], v28, s56, v[112:113]
	v_cvt_pk_bf16_f32 v17, v22, v23
	v_cvt_pk_bf16_f32 v18, v24, v25
	v_cvt_pk_bf16_f32 v19, v26, v27
	v_lshl_add_u64 v[20:21], v[20:21], 0, v[114:115]
	v_mul_f32_e32 v22, 0xbfb8aa3b, v12
	global_store_dwordx4 v[20:21], v[16:19], off sc0 sc1
	v_pk_add_f32 v[14:15], v[14:15], 0 op_sel_hi:[1,0]
	v_exp_f32_e32 v22, v22
	v_mul_f32_e32 v16, 0xbfb8aa3b, v13
	v_exp_f32_e32 v17, v16
	v_mul_f32_e32 v18, 0xbfb8aa3b, v14
	v_mul_f32_e32 v19, 0xbfb8aa3b, v15
	v_exp_f32_e32 v18, v18
	v_exp_f32_e32 v19, v19
	v_add_f32_e32 v16, 1.0, v22
	v_add_f32_e32 v17, 1.0, v17
	v_rcp_f32_e32 v16, v16
	v_rcp_f32_e32 v17, v17
	v_add_f32_e32 v18, 1.0, v18
	v_add_f32_e32 v19, 1.0, v19
	v_rcp_f32_e32 v18, v18
	v_rcp_f32_e32 v19, v19
	v_pk_add_f32 v[4:5], v[4:5], 0 op_sel_hi:[1,0]
	v_pk_mul_f32 v[12:13], v[12:13], v[16:17]
	v_pk_add_f32 v[8:9], v[8:9], 0 op_sel_hi:[1,0]
	v_pk_mul_f32 v[4:5], v[12:13], v[4:5]
	v_pk_mul_f32 v[12:13], v[14:15], v[18:19]
	v_mul_f32_e32 v14, 0xbfb8aa3b, v8
	v_exp_f32_e32 v14, v14
	v_pk_add_f32 v[6:7], v[6:7], 0 op_sel_hi:[1,0]
	v_pk_add_f32 v[10:11], v[10:11], 0 op_sel_hi:[1,0]
	v_pk_mul_f32 v[6:7], v[12:13], v[6:7]
	v_mul_f32_e32 v12, 0xbfb8aa3b, v9
	v_exp_f32_e32 v13, v12
	v_add_f32_e32 v12, 1.0, v14
	v_mul_f32_e32 v14, 0xbfb8aa3b, v10
	v_mul_f32_e32 v15, 0xbfb8aa3b, v11
	v_exp_f32_e32 v14, v14
	v_exp_f32_e32 v15, v15
	v_add_f32_e32 v13, 1.0, v13
	v_rcp_f32_e32 v12, v12
	v_rcp_f32_e32 v13, v13
	v_add_f32_e32 v14, 1.0, v14
	v_add_f32_e32 v15, 1.0, v15
	v_rcp_f32_e32 v14, v14
	v_rcp_f32_e32 v15, v15
	v_pk_add_f32 v[0:1], v[0:1], 0 op_sel_hi:[1,0]
	v_pk_mul_f32 v[8:9], v[8:9], v[12:13]
	v_add_u32_e32 v12, 0xb0, v150
	v_pk_mul_f32 v[8:9], v[8:9], v[0:1]
	v_pk_add_f32 v[0:1], v[2:3], 0 op_sel_hi:[1,0]
	v_pk_mul_f32 v[2:3], v[10:11], v[14:15]
	s_and_b64 vcc, exec, s[16:17]
	v_pk_mul_f32 v[10:11], v[2:3], v[0:1]
	v_cvt_pk_bf16_f32 v0, v4, v5
	v_mad_i64_i32 v[4:5], s[28:29], v12, s56, v[112:113]
	v_cvt_pk_bf16_f32 v1, v6, v7
	v_cvt_pk_bf16_f32 v2, v8, v9
	v_cvt_pk_bf16_f32 v3, v10, v11
	v_lshl_add_u64 v[4:5], v[4:5], 0, v[114:115]
	s_mov_b32 s57, s10
	s_mov_b32 s30, s12
	s_mov_b64 s[36:37], s[18:19]
	s_mov_b64 s[34:35], s[14:15]
	global_store_dwordx4 v[4:5], v[0:3], off sc0 sc1
	s_cbranch_vccz .LBB0_1198
	s_branch .LBB0_1206

.LBB0_1284:
	s_add_u32 s36, s36, 0x160080
	s_addc_u32 s37, s37, 0
	s_add_u32 s28, s38, 0x100
	s_addc_u32 s29, s39, 0
	s_mov_b32 s68, -2
	ds_read_b128 v[128:131], v169
	ds_read_b128 v[132:135], v169 offset:1024
	ds_read_b128 v[136:139], v169 offset:2048
	ds_read_b128 v[140:143], v169 offset:3072
	s_add_u32 s38, s36, 0xffea0080
	s_addc_u32 s39, s37, -1
	s_cmpk_eq_i32 s68, 0x54
	s_cselect_b32 s41, s35, s39
	s_cselect_b32 s40, s34, s38
	s_cselect_b32 s39, s1, s29
	s_cselect_b32 s38, s0, s28
	s_add_i32 m0, s47, 0xc000
	ds_read_b128 v[156:159], v170
	ds_read_b128 v[160:163], v170 offset:1024
	ds_read_b128 v[172:175], v170 offset:2048
	ds_read_b128 v[176:179], v170 offset:3072
	ds_read_b128 v[180:183], v170 offset:4096
	ds_read_b128 v[184:187], v170 offset:5120
	ds_read_b128 v[188:191], v170 offset:6144
	ds_read_b128 v[192:195], v170 offset:7168
	global_load_lds_dwordx4 v150, s[36:37]
	s_add_i32 m0, s47, 0xe000
	s_nop 0
	global_load_lds_dwordx4 v152, s[36:37]
	s_waitcnt lgkmcnt(8)
	s_barrier
	s_waitcnt lgkmcnt(0)
	v_mfma_f32_16x16x32_bf16 v[124:127], v[128:131], v[156:159], 0
	v_mfma_f32_16x16x32_bf16 v[120:123], v[136:139], v[156:159], 0
	v_mfma_f32_16x16x32_bf16 v[116:119], v[128:131], v[172:175], 0
	v_mfma_f32_16x16x32_bf16 v[104:107], v[136:139], v[172:175], 0
	v_mfma_f32_16x16x32_bf16 v[92:95], v[128:131], v[180:183], 0
	v_mfma_f32_16x16x32_bf16 v[88:91], v[136:139], v[180:183], 0
	v_mfma_f32_16x16x32_bf16 v[76:79], v[128:131], v[188:191], 0
	v_mfma_f32_16x16x32_bf16 v[72:75], v[136:139], v[188:191], 0
	v_mfma_f32_16x16x32_bf16 v[124:127], v[132:135], v[160:163], v[124:127]
	v_mfma_f32_16x16x32_bf16 v[120:123], v[140:143], v[160:163], v[120:123]
	v_mfma_f32_16x16x32_bf16 v[116:119], v[132:135], v[176:179], v[116:119]
	v_mfma_f32_16x16x32_bf16 v[104:107], v[140:143], v[176:179], v[104:107]
	v_mfma_f32_16x16x32_bf16 v[92:95], v[132:135], v[184:187], v[92:95]
	v_mfma_f32_16x16x32_bf16 v[88:91], v[140:143], v[184:187], v[88:91]
	v_mfma_f32_16x16x32_bf16 v[76:79], v[132:135], v[192:195], v[76:79]
	v_mfma_f32_16x16x32_bf16 v[72:75], v[140:143], v[192:195], v[72:75]
	s_barrier
	s_add_i32 s69, s58, s46
	s_add_u32 s98, s38, s10
	s_addc_u32 s99, s39, s11
	s_mov_b32 m0, s69
	ds_read_b128 v[196:199], v171
	ds_read_b128 v[200:203], v171 offset:1024
	ds_read_b128 v[204:207], v171 offset:2048
	ds_read_b128 v[208:211], v171 offset:3072
	global_load_lds_dwordx4 v146, s[38:39]
	s_add_i32 m0, s69, 0x2000
	s_nop 0
	global_load_lds_dwordx4 v148, s[38:39]
	s_barrier
	s_waitcnt lgkmcnt(0)
	v_mfma_f32_16x16x32_bf16 v[112:115], v[196:199], v[156:159], 0
	v_mfma_f32_16x16x32_bf16 v[108:111], v[204:207], v[156:159], 0
	v_mfma_f32_16x16x32_bf16 v[100:103], v[196:199], v[172:175], 0
	v_mfma_f32_16x16x32_bf16 v[96:99], v[204:207], v[172:175], 0
	v_mfma_f32_16x16x32_bf16 v[84:87], v[196:199], v[180:183], 0
	v_mfma_f32_16x16x32_bf16 v[80:83], v[204:207], v[180:183], 0
	v_mfma_f32_16x16x32_bf16 v[68:71], v[196:199], v[188:191], 0
	v_mfma_f32_16x16x32_bf16 v[64:67], v[204:207], v[188:191], 0
	v_mfma_f32_16x16x32_bf16 v[112:115], v[200:203], v[160:163], v[112:115]
	v_mfma_f32_16x16x32_bf16 v[108:111], v[208:211], v[160:163], v[108:111]
	v_mfma_f32_16x16x32_bf16 v[100:103], v[200:203], v[176:179], v[100:103]
	v_mfma_f32_16x16x32_bf16 v[96:99], v[208:211], v[176:179], v[96:99]
	v_mfma_f32_16x16x32_bf16 v[84:87], v[200:203], v[184:187], v[84:87]
	v_mfma_f32_16x16x32_bf16 v[80:83], v[208:211], v[184:187], v[80:83]
	v_mfma_f32_16x16x32_bf16 v[68:71], v[200:203], v[192:195], v[68:71]
	v_mfma_f32_16x16x32_bf16 v[64:67], v[208:211], v[192:195], v[64:67]
	s_mov_b32 m0, s47
	s_add_u32 s100, s40, s10
	s_addc_u32 s101, s41, s11
	s_barrier
	ds_read_b128 v[156:159], v170 offset:16384
	ds_read_b128 v[160:163], v170 offset:17408
	ds_read_b128 v[172:175], v170 offset:18432
	ds_read_b128 v[176:179], v170 offset:19456
	ds_read_b128 v[180:183], v170 offset:20480
	ds_read_b128 v[184:187], v170 offset:21504
	ds_read_b128 v[188:191], v170 offset:22528
	ds_read_b128 v[192:195], v170 offset:23552
	global_load_lds_dwordx4 v146, s[40:41]
	s_mov_b32 m0, s48
	s_nop 0
	global_load_lds_dwordx4 v148, s[40:41]
	s_barrier
	s_waitcnt lgkmcnt(0)
	v_mfma_f32_16x16x32_bf16 v[60:63], v[128:131], v[156:159], 0
	v_mfma_f32_16x16x32_bf16 v[56:59], v[136:139], v[156:159], 0
	v_mfma_f32_16x16x32_bf16 v[44:47], v[128:131], v[172:175], 0
	v_mfma_f32_16x16x32_bf16 v[40:43], v[136:139], v[172:175], 0
	v_mfma_f32_16x16x32_bf16 v[36:39], v[128:131], v[180:183], 0
	v_mfma_f32_16x16x32_bf16 v[28:31], v[136:139], v[180:183], 0
	v_mfma_f32_16x16x32_bf16 v[20:23], v[128:131], v[188:191], 0
	v_mfma_f32_16x16x32_bf16 v[12:15], v[136:139], v[188:191], 0
	v_mfma_f32_16x16x32_bf16 v[60:63], v[132:135], v[160:163], v[60:63]
	v_mfma_f32_16x16x32_bf16 v[56:59], v[140:143], v[160:163], v[56:59]
	v_mfma_f32_16x16x32_bf16 v[44:47], v[132:135], v[176:179], v[44:47]
	v_mfma_f32_16x16x32_bf16 v[40:43], v[140:143], v[176:179], v[40:43]
	v_mfma_f32_16x16x32_bf16 v[36:39], v[132:135], v[184:187], v[36:39]
	v_mfma_f32_16x16x32_bf16 v[28:31], v[140:143], v[184:187], v[28:31]
	v_mfma_f32_16x16x32_bf16 v[20:23], v[132:135], v[192:195], v[20:23]
	v_mfma_f32_16x16x32_bf16 v[12:15], v[140:143], v[192:195], v[12:15]
	s_barrier
	s_add_u32 s70, s38, 0x160000
	s_addc_u32 s71, s39, 0
	s_add_i32 s69, s59, s46
	s_mov_b32 m0, s69
	s_nop 0
	global_load_lds_dwordx4 v146, s[70:71]
	s_add_i32 m0, s69, 0x2000
	s_nop 0
	global_load_lds_dwordx4 v148, s[70:71]
	s_waitcnt vmcnt(6)
	s_barrier
	v_mfma_f32_16x16x32_bf16 v[52:55], v[196:199], v[156:159], 0
	v_mfma_f32_16x16x32_bf16 v[48:51], v[204:207], v[156:159], 0
	v_mfma_f32_16x16x32_bf16 v[32:35], v[196:199], v[172:175], 0
	v_mfma_f32_16x16x32_bf16 v[24:27], v[204:207], v[172:175], 0
	v_mfma_f32_16x16x32_bf16 v[16:19], v[196:199], v[180:183], 0
	v_mfma_f32_16x16x32_bf16 v[8:11], v[204:207], v[180:183], 0
	v_mfma_f32_16x16x32_bf16 v[4:7], v[196:199], v[188:191], 0
	v_mfma_f32_16x16x32_bf16 v[0:3], v[204:207], v[188:191], 0
	v_mfma_f32_16x16x32_bf16 v[52:55], v[200:203], v[160:163], v[52:55]
	v_mfma_f32_16x16x32_bf16 v[48:51], v[208:211], v[160:163], v[48:51]
	v_mfma_f32_16x16x32_bf16 v[32:35], v[200:203], v[176:179], v[32:35]
	v_mfma_f32_16x16x32_bf16 v[24:27], v[208:211], v[176:179], v[24:27]
	v_mfma_f32_16x16x32_bf16 v[16:19], v[200:203], v[184:187], v[16:19]
	v_mfma_f32_16x16x32_bf16 v[8:11], v[208:211], v[184:187], v[8:11]
	v_mfma_f32_16x16x32_bf16 v[4:7], v[200:203], v[192:195], v[4:7]
	v_mfma_f32_16x16x32_bf16 v[0:3], v[208:211], v[192:195], v[0:3]
	s_add_i32 s69, 0, 0x18000
	v_add_u32_e32 v140, s69, v167
	s_barrier
	ds_read_b128 v[128:131], v140
	ds_read_b128 v[132:135], v140 offset:1024
	ds_read_b128 v[136:139], v140 offset:2048
	ds_read_b128 v[140:143], v140 offset:3072
	s_add_u32 s40, s40, 0x160000
	s_addc_u32 s41, s41, 0
	s_mov_b32 m0, s49
	ds_read_b128 v[156:159], v170 offset:32768
	ds_read_b128 v[160:163], v170 offset:33792
	ds_read_b128 v[172:175], v170 offset:34816
	ds_read_b128 v[176:179], v170 offset:35840
	ds_read_b128 v[180:183], v170 offset:36864
	ds_read_b128 v[184:187], v170 offset:37888
	ds_read_b128 v[188:191], v170 offset:38912
	ds_read_b128 v[192:195], v170 offset:39936
	global_load_lds_dwordx4 v146, s[40:41]
	s_mov_b32 m0, s50
	s_nop 0
	global_load_lds_dwordx4 v148, s[40:41]
	s_waitcnt lgkmcnt(8)
	s_barrier
	s_waitcnt lgkmcnt(0)
	v_mfma_f32_16x16x32_bf16 v[124:127], v[128:131], v[156:159], v[124:127]
	v_mfma_f32_16x16x32_bf16 v[120:123], v[136:139], v[156:159], v[120:123]
	v_mfma_f32_16x16x32_bf16 v[116:119], v[128:131], v[172:175], v[116:119]
	v_mfma_f32_16x16x32_bf16 v[104:107], v[136:139], v[172:175], v[104:107]
	v_mfma_f32_16x16x32_bf16 v[92:95], v[128:131], v[180:183], v[92:95]
	v_mfma_f32_16x16x32_bf16 v[88:91], v[136:139], v[180:183], v[88:91]
	v_mfma_f32_16x16x32_bf16 v[76:79], v[128:131], v[188:191], v[76:79]
	v_mfma_f32_16x16x32_bf16 v[72:75], v[136:139], v[188:191], v[72:75]
	v_mfma_f32_16x16x32_bf16 v[124:127], v[132:135], v[160:163], v[124:127]
	v_mfma_f32_16x16x32_bf16 v[120:123], v[140:143], v[160:163], v[120:123]
	v_mfma_f32_16x16x32_bf16 v[116:119], v[132:135], v[176:179], v[116:119]
	v_mfma_f32_16x16x32_bf16 v[104:107], v[140:143], v[176:179], v[104:107]
	v_mfma_f32_16x16x32_bf16 v[92:95], v[132:135], v[184:187], v[92:95]
	v_mfma_f32_16x16x32_bf16 v[88:91], v[140:143], v[184:187], v[88:91]
	v_mfma_f32_16x16x32_bf16 v[76:79], v[132:135], v[192:195], v[76:79]
	v_mfma_f32_16x16x32_bf16 v[72:75], v[140:143], v[192:195], v[72:75]
	s_barrier
	s_add_i32 s40, 0, 0x1c000
	s_add_i32 s41, s69, s46
	v_add_u32_e32 v208, s40, v167
	s_mov_b32 m0, s41
	ds_read_b128 v[196:199], v208
	ds_read_b128 v[200:203], v208 offset:1024
	ds_read_b128 v[204:207], v208 offset:2048
	ds_read_b128 v[208:211], v208 offset:3072
	global_load_lds_dwordx4 v146, s[98:99]
	s_add_i32 m0, s41, 0x2000
	s_nop 0
	global_load_lds_dwordx4 v148, s[98:99]
	s_barrier
	s_waitcnt lgkmcnt(0)
	v_mfma_f32_16x16x32_bf16 v[112:115], v[196:199], v[156:159], v[112:115]
	v_mfma_f32_16x16x32_bf16 v[108:111], v[204:207], v[156:159], v[108:111]
	v_mfma_f32_16x16x32_bf16 v[100:103], v[196:199], v[172:175], v[100:103]
	v_mfma_f32_16x16x32_bf16 v[96:99], v[204:207], v[172:175], v[96:99]
	v_mfma_f32_16x16x32_bf16 v[84:87], v[196:199], v[180:183], v[84:87]
	v_mfma_f32_16x16x32_bf16 v[80:83], v[204:207], v[180:183], v[80:83]
	v_mfma_f32_16x16x32_bf16 v[68:71], v[196:199], v[188:191], v[68:71]
	v_mfma_f32_16x16x32_bf16 v[64:67], v[204:207], v[188:191], v[64:67]
	v_mfma_f32_16x16x32_bf16 v[112:115], v[200:203], v[160:163], v[112:115]
	v_mfma_f32_16x16x32_bf16 v[108:111], v[208:211], v[160:163], v[108:111]
	v_mfma_f32_16x16x32_bf16 v[100:103], v[200:203], v[176:179], v[100:103]
	v_mfma_f32_16x16x32_bf16 v[96:99], v[208:211], v[176:179], v[96:99]
	v_mfma_f32_16x16x32_bf16 v[84:87], v[200:203], v[184:187], v[84:87]
	v_mfma_f32_16x16x32_bf16 v[80:83], v[208:211], v[184:187], v[80:83]
	v_mfma_f32_16x16x32_bf16 v[68:71], v[200:203], v[192:195], v[68:71]
	v_mfma_f32_16x16x32_bf16 v[64:67], v[208:211], v[192:195], v[64:67]
	s_mov_b32 m0, s54
	s_barrier
	ds_read_b128 v[156:159], v170 offset:49152
	ds_read_b128 v[160:163], v170 offset:50176
	ds_read_b128 v[172:175], v170 offset:51200
	ds_read_b128 v[176:179], v170 offset:52224
	ds_read_b128 v[180:183], v170 offset:53248
	ds_read_b128 v[184:187], v170 offset:54272
	ds_read_b128 v[188:191], v170 offset:55296
	ds_read_b128 v[192:195], v170 offset:56320
	global_load_lds_dwordx4 v146, s[100:101]
	s_mov_b32 m0, s55
	s_nop 0
	global_load_lds_dwordx4 v148, s[100:101]
	s_barrier
	s_waitcnt lgkmcnt(0)
	v_mfma_f32_16x16x32_bf16 v[60:63], v[128:131], v[156:159], v[60:63]
	v_mfma_f32_16x16x32_bf16 v[56:59], v[136:139], v[156:159], v[56:59]
	v_mfma_f32_16x16x32_bf16 v[44:47], v[128:131], v[172:175], v[44:47]
	v_mfma_f32_16x16x32_bf16 v[40:43], v[136:139], v[172:175], v[40:43]
	v_mfma_f32_16x16x32_bf16 v[36:39], v[128:131], v[180:183], v[36:39]
	v_mfma_f32_16x16x32_bf16 v[28:31], v[136:139], v[180:183], v[28:31]
	v_mfma_f32_16x16x32_bf16 v[20:23], v[128:131], v[188:191], v[20:23]
	v_mfma_f32_16x16x32_bf16 v[12:15], v[136:139], v[188:191], v[12:15]
	v_mfma_f32_16x16x32_bf16 v[60:63], v[132:135], v[160:163], v[60:63]
	v_mfma_f32_16x16x32_bf16 v[56:59], v[140:143], v[160:163], v[56:59]
	v_mfma_f32_16x16x32_bf16 v[44:47], v[132:135], v[176:179], v[44:47]
	v_mfma_f32_16x16x32_bf16 v[40:43], v[140:143], v[176:179], v[40:43]
	v_mfma_f32_16x16x32_bf16 v[36:39], v[132:135], v[184:187], v[36:39]
	v_mfma_f32_16x16x32_bf16 v[28:31], v[140:143], v[184:187], v[28:31]
	v_mfma_f32_16x16x32_bf16 v[20:23], v[132:135], v[192:195], v[20:23]
	v_mfma_f32_16x16x32_bf16 v[12:15], v[140:143], v[192:195], v[12:15]
	s_barrier
	s_add_u32 s38, s38, 0x160080
	s_addc_u32 s39, s39, 0
	s_add_i32 s40, s40, s46
	s_mov_b32 m0, s40
	s_nop 0
	global_load_lds_dwordx4 v146, s[38:39]
	s_add_i32 m0, s40, 0x2000
	s_nop 0
	global_load_lds_dwordx4 v148, s[38:39]
	s_waitcnt vmcnt(6)
	s_barrier
	v_mfma_f32_16x16x32_bf16 v[52:55], v[196:199], v[156:159], v[52:55]
	v_mfma_f32_16x16x32_bf16 v[48:51], v[204:207], v[156:159], v[48:51]
	v_mfma_f32_16x16x32_bf16 v[32:35], v[196:199], v[172:175], v[32:35]
	v_mfma_f32_16x16x32_bf16 v[24:27], v[204:207], v[172:175], v[24:27]
	v_mfma_f32_16x16x32_bf16 v[16:19], v[196:199], v[180:183], v[16:19]
	v_mfma_f32_16x16x32_bf16 v[8:11], v[204:207], v[180:183], v[8:11]
	v_mfma_f32_16x16x32_bf16 v[4:7], v[196:199], v[188:191], v[4:7]
	v_mfma_f32_16x16x32_bf16 v[0:3], v[204:207], v[188:191], v[0:3]
	v_mfma_f32_16x16x32_bf16 v[52:55], v[200:203], v[160:163], v[52:55]
	v_mfma_f32_16x16x32_bf16 v[48:51], v[208:211], v[160:163], v[48:51]
	v_mfma_f32_16x16x32_bf16 v[32:35], v[200:203], v[176:179], v[32:35]
	v_mfma_f32_16x16x32_bf16 v[24:27], v[208:211], v[176:179], v[24:27]
	v_mfma_f32_16x16x32_bf16 v[16:19], v[200:203], v[184:187], v[16:19]
	v_mfma_f32_16x16x32_bf16 v[8:11], v[208:211], v[184:187], v[8:11]
	v_mfma_f32_16x16x32_bf16 v[4:7], v[200:203], v[192:195], v[4:7]
	v_mfma_f32_16x16x32_bf16 v[0:3], v[208:211], v[192:195], v[0:3]
	s_add_i32 s68, s68, 2
	s_add_u32 s36, s36, 0x100
	s_addc_u32 s37, s37, 0
	s_add_u32 s28, s28, 0x100
	s_addc_u32 s29, s29, 0
	s_cmpk_gt_u32 s68, 0x55
	s_barrier
	s_cbranch_scc0 .LBB0_1285
.LBB0_1285:
	ds_read_b128 v[128:131], v169
	ds_read_b128 v[132:135], v169 offset:1024
	ds_read_b128 v[136:139], v169 offset:2048
	ds_read_b128 v[140:143], v169 offset:3072
	s_add_u32 s38, s36, 0xffea0080
	s_addc_u32 s39, s37, -1
	s_cmpk_eq_i32 s68, 0x54
	s_cselect_b32 s41, s35, s39
	s_cselect_b32 s40, s34, s38
	s_cselect_b32 s39, s1, s29
	s_cselect_b32 s38, s0, s28
	s_add_i32 m0, s47, 0xc000
	ds_read_b128 v[156:159], v170
	ds_read_b128 v[160:163], v170 offset:1024
	ds_read_b128 v[172:175], v170 offset:2048
	ds_read_b128 v[176:179], v170 offset:3072
	ds_read_b128 v[180:183], v170 offset:4096
	ds_read_b128 v[184:187], v170 offset:5120
	ds_read_b128 v[188:191], v170 offset:6144
	ds_read_b128 v[192:195], v170 offset:7168
	global_load_lds_dwordx4 v150, s[36:37]
	s_add_i32 m0, s47, 0xe000
	s_nop 0
	global_load_lds_dwordx4 v152, s[36:37]
	s_waitcnt lgkmcnt(8)
	s_barrier
	s_waitcnt lgkmcnt(0)
	v_mfma_f32_16x16x32_bf16 v[124:127], v[128:131], v[156:159], v[124:127]
	v_mfma_f32_16x16x32_bf16 v[120:123], v[136:139], v[156:159], v[120:123]
	v_mfma_f32_16x16x32_bf16 v[116:119], v[128:131], v[172:175], v[116:119]
	v_mfma_f32_16x16x32_bf16 v[104:107], v[136:139], v[172:175], v[104:107]
	v_mfma_f32_16x16x32_bf16 v[92:95], v[128:131], v[180:183], v[92:95]
	v_mfma_f32_16x16x32_bf16 v[88:91], v[136:139], v[180:183], v[88:91]
	v_mfma_f32_16x16x32_bf16 v[76:79], v[128:131], v[188:191], v[76:79]
	v_mfma_f32_16x16x32_bf16 v[72:75], v[136:139], v[188:191], v[72:75]
	v_mfma_f32_16x16x32_bf16 v[124:127], v[132:135], v[160:163], v[124:127]
	v_mfma_f32_16x16x32_bf16 v[120:123], v[140:143], v[160:163], v[120:123]
	v_mfma_f32_16x16x32_bf16 v[116:119], v[132:135], v[176:179], v[116:119]
	v_mfma_f32_16x16x32_bf16 v[104:107], v[140:143], v[176:179], v[104:107]
	v_mfma_f32_16x16x32_bf16 v[92:95], v[132:135], v[184:187], v[92:95]
	v_mfma_f32_16x16x32_bf16 v[88:91], v[140:143], v[184:187], v[88:91]
	v_mfma_f32_16x16x32_bf16 v[76:79], v[132:135], v[192:195], v[76:79]
	v_mfma_f32_16x16x32_bf16 v[72:75], v[140:143], v[192:195], v[72:75]
	s_barrier
	s_add_i32 s69, s58, s46
	s_add_u32 s98, s38, s10
	s_addc_u32 s99, s39, s11
	s_mov_b32 m0, s69
	ds_read_b128 v[196:199], v171
	ds_read_b128 v[200:203], v171 offset:1024
	ds_read_b128 v[204:207], v171 offset:2048
	ds_read_b128 v[208:211], v171 offset:3072
	global_load_lds_dwordx4 v146, s[38:39]
	s_add_i32 m0, s69, 0x2000
	s_nop 0
	global_load_lds_dwordx4 v148, s[38:39]
	s_barrier
	s_waitcnt lgkmcnt(0)
	v_mfma_f32_16x16x32_bf16 v[112:115], v[196:199], v[156:159], v[112:115]
	v_mfma_f32_16x16x32_bf16 v[108:111], v[204:207], v[156:159], v[108:111]
	v_mfma_f32_16x16x32_bf16 v[100:103], v[196:199], v[172:175], v[100:103]
	v_mfma_f32_16x16x32_bf16 v[96:99], v[204:207], v[172:175], v[96:99]
	v_mfma_f32_16x16x32_bf16 v[84:87], v[196:199], v[180:183], v[84:87]
	v_mfma_f32_16x16x32_bf16 v[80:83], v[204:207], v[180:183], v[80:83]
	v_mfma_f32_16x16x32_bf16 v[68:71], v[196:199], v[188:191], v[68:71]
	v_mfma_f32_16x16x32_bf16 v[64:67], v[204:207], v[188:191], v[64:67]
	v_mfma_f32_16x16x32_bf16 v[112:115], v[200:203], v[160:163], v[112:115]
	v_mfma_f32_16x16x32_bf16 v[108:111], v[208:211], v[160:163], v[108:111]
	v_mfma_f32_16x16x32_bf16 v[100:103], v[200:203], v[176:179], v[100:103]
	v_mfma_f32_16x16x32_bf16 v[96:99], v[208:211], v[176:179], v[96:99]
	v_mfma_f32_16x16x32_bf16 v[84:87], v[200:203], v[184:187], v[84:87]
	v_mfma_f32_16x16x32_bf16 v[80:83], v[208:211], v[184:187], v[80:83]
	v_mfma_f32_16x16x32_bf16 v[68:71], v[200:203], v[192:195], v[68:71]
	v_mfma_f32_16x16x32_bf16 v[64:67], v[208:211], v[192:195], v[64:67]
	s_mov_b32 m0, s47
	s_add_u32 s100, s40, s10
	s_addc_u32 s101, s41, s11
	s_barrier
	ds_read_b128 v[156:159], v170 offset:16384
	ds_read_b128 v[160:163], v170 offset:17408
	ds_read_b128 v[172:175], v170 offset:18432
	ds_read_b128 v[176:179], v170 offset:19456
	ds_read_b128 v[180:183], v170 offset:20480
	ds_read_b128 v[184:187], v170 offset:21504
	ds_read_b128 v[188:191], v170 offset:22528
	ds_read_b128 v[192:195], v170 offset:23552
	global_load_lds_dwordx4 v146, s[40:41]
	s_mov_b32 m0, s48
	s_nop 0
	global_load_lds_dwordx4 v148, s[40:41]
	s_barrier
	s_waitcnt lgkmcnt(0)
	v_mfma_f32_16x16x32_bf16 v[60:63], v[128:131], v[156:159], v[60:63]
	v_mfma_f32_16x16x32_bf16 v[56:59], v[136:139], v[156:159], v[56:59]
	v_mfma_f32_16x16x32_bf16 v[44:47], v[128:131], v[172:175], v[44:47]
	v_mfma_f32_16x16x32_bf16 v[40:43], v[136:139], v[172:175], v[40:43]
	v_mfma_f32_16x16x32_bf16 v[36:39], v[128:131], v[180:183], v[36:39]
	v_mfma_f32_16x16x32_bf16 v[28:31], v[136:139], v[180:183], v[28:31]
	v_mfma_f32_16x16x32_bf16 v[20:23], v[128:131], v[188:191], v[20:23]
	v_mfma_f32_16x16x32_bf16 v[12:15], v[136:139], v[188:191], v[12:15]
	v_mfma_f32_16x16x32_bf16 v[60:63], v[132:135], v[160:163], v[60:63]
	v_mfma_f32_16x16x32_bf16 v[56:59], v[140:143], v[160:163], v[56:59]
	v_mfma_f32_16x16x32_bf16 v[44:47], v[132:135], v[176:179], v[44:47]
	v_mfma_f32_16x16x32_bf16 v[40:43], v[140:143], v[176:179], v[40:43]
	v_mfma_f32_16x16x32_bf16 v[36:39], v[132:135], v[184:187], v[36:39]
	v_mfma_f32_16x16x32_bf16 v[28:31], v[140:143], v[184:187], v[28:31]
	v_mfma_f32_16x16x32_bf16 v[20:23], v[132:135], v[192:195], v[20:23]
	v_mfma_f32_16x16x32_bf16 v[12:15], v[140:143], v[192:195], v[12:15]
	s_barrier
	s_add_u32 s70, s38, 0x160000
	s_addc_u32 s71, s39, 0
	s_add_i32 s69, s59, s46
	s_mov_b32 m0, s69
	s_nop 0
	global_load_lds_dwordx4 v146, s[70:71]
	s_add_i32 m0, s69, 0x2000
	s_nop 0
	global_load_lds_dwordx4 v148, s[70:71]
	s_waitcnt vmcnt(6)
	s_barrier
	v_mfma_f32_16x16x32_bf16 v[52:55], v[196:199], v[156:159], v[52:55]
	v_mfma_f32_16x16x32_bf16 v[48:51], v[204:207], v[156:159], v[48:51]
	v_mfma_f32_16x16x32_bf16 v[32:35], v[196:199], v[172:175], v[32:35]
	v_mfma_f32_16x16x32_bf16 v[24:27], v[204:207], v[172:175], v[24:27]
	v_mfma_f32_16x16x32_bf16 v[16:19], v[196:199], v[180:183], v[16:19]
	v_mfma_f32_16x16x32_bf16 v[8:11], v[204:207], v[180:183], v[8:11]
	v_mfma_f32_16x16x32_bf16 v[4:7], v[196:199], v[188:191], v[4:7]
	v_mfma_f32_16x16x32_bf16 v[0:3], v[204:207], v[188:191], v[0:3]
	v_mfma_f32_16x16x32_bf16 v[52:55], v[200:203], v[160:163], v[52:55]
	v_mfma_f32_16x16x32_bf16 v[48:51], v[208:211], v[160:163], v[48:51]
	v_mfma_f32_16x16x32_bf16 v[32:35], v[200:203], v[176:179], v[32:35]
	v_mfma_f32_16x16x32_bf16 v[24:27], v[208:211], v[176:179], v[24:27]
	v_mfma_f32_16x16x32_bf16 v[16:19], v[200:203], v[184:187], v[16:19]
	v_mfma_f32_16x16x32_bf16 v[8:11], v[208:211], v[184:187], v[8:11]
	v_mfma_f32_16x16x32_bf16 v[4:7], v[200:203], v[192:195], v[4:7]
	v_mfma_f32_16x16x32_bf16 v[0:3], v[208:211], v[192:195], v[0:3]
	s_add_i32 s69, 0, 0x18000
	v_add_u32_e32 v140, s69, v167
	s_barrier
	ds_read_b128 v[128:131], v140
	ds_read_b128 v[132:135], v140 offset:1024
	ds_read_b128 v[136:139], v140 offset:2048
	ds_read_b128 v[140:143], v140 offset:3072
	s_add_u32 s40, s40, 0x160000
	s_addc_u32 s41, s41, 0
	s_mov_b32 m0, s49
	ds_read_b128 v[156:159], v170 offset:32768
	ds_read_b128 v[160:163], v170 offset:33792
	ds_read_b128 v[172:175], v170 offset:34816
	ds_read_b128 v[176:179], v170 offset:35840
	ds_read_b128 v[180:183], v170 offset:36864
	ds_read_b128 v[184:187], v170 offset:37888
	ds_read_b128 v[188:191], v170 offset:38912
	ds_read_b128 v[192:195], v170 offset:39936
	global_load_lds_dwordx4 v146, s[40:41]
	s_mov_b32 m0, s50
	s_nop 0
	global_load_lds_dwordx4 v148, s[40:41]
	s_waitcnt lgkmcnt(8)
	s_barrier
	s_waitcnt lgkmcnt(0)
	v_mfma_f32_16x16x32_bf16 v[124:127], v[128:131], v[156:159], v[124:127]
	v_mfma_f32_16x16x32_bf16 v[120:123], v[136:139], v[156:159], v[120:123]
	v_mfma_f32_16x16x32_bf16 v[116:119], v[128:131], v[172:175], v[116:119]
	v_mfma_f32_16x16x32_bf16 v[104:107], v[136:139], v[172:175], v[104:107]
	v_mfma_f32_16x16x32_bf16 v[92:95], v[128:131], v[180:183], v[92:95]
	v_mfma_f32_16x16x32_bf16 v[88:91], v[136:139], v[180:183], v[88:91]
	v_mfma_f32_16x16x32_bf16 v[76:79], v[128:131], v[188:191], v[76:79]
	v_mfma_f32_16x16x32_bf16 v[72:75], v[136:139], v[188:191], v[72:75]
	v_mfma_f32_16x16x32_bf16 v[124:127], v[132:135], v[160:163], v[124:127]
	v_mfma_f32_16x16x32_bf16 v[120:123], v[140:143], v[160:163], v[120:123]
	v_mfma_f32_16x16x32_bf16 v[116:119], v[132:135], v[176:179], v[116:119]
	v_mfma_f32_16x16x32_bf16 v[104:107], v[140:143], v[176:179], v[104:107]
	v_mfma_f32_16x16x32_bf16 v[92:95], v[132:135], v[184:187], v[92:95]
	v_mfma_f32_16x16x32_bf16 v[88:91], v[140:143], v[184:187], v[88:91]
	v_mfma_f32_16x16x32_bf16 v[76:79], v[132:135], v[192:195], v[76:79]
	v_mfma_f32_16x16x32_bf16 v[72:75], v[140:143], v[192:195], v[72:75]
	s_barrier
	s_add_i32 s40, 0, 0x1c000
	s_add_i32 s41, s69, s46
	v_add_u32_e32 v208, s40, v167
	s_mov_b32 m0, s41
	ds_read_b128 v[196:199], v208
	ds_read_b128 v[200:203], v208 offset:1024
	ds_read_b128 v[204:207], v208 offset:2048
	ds_read_b128 v[208:211], v208 offset:3072
	global_load_lds_dwordx4 v146, s[98:99]
	s_add_i32 m0, s41, 0x2000
	s_nop 0
	global_load_lds_dwordx4 v148, s[98:99]
	s_barrier
	s_waitcnt lgkmcnt(0)
	v_mfma_f32_16x16x32_bf16 v[112:115], v[196:199], v[156:159], v[112:115]
	v_mfma_f32_16x16x32_bf16 v[108:111], v[204:207], v[156:159], v[108:111]
	v_mfma_f32_16x16x32_bf16 v[100:103], v[196:199], v[172:175], v[100:103]
	v_mfma_f32_16x16x32_bf16 v[96:99], v[204:207], v[172:175], v[96:99]
	v_mfma_f32_16x16x32_bf16 v[84:87], v[196:199], v[180:183], v[84:87]
	v_mfma_f32_16x16x32_bf16 v[80:83], v[204:207], v[180:183], v[80:83]
	v_mfma_f32_16x16x32_bf16 v[68:71], v[196:199], v[188:191], v[68:71]
	v_mfma_f32_16x16x32_bf16 v[64:67], v[204:207], v[188:191], v[64:67]
	v_mfma_f32_16x16x32_bf16 v[112:115], v[200:203], v[160:163], v[112:115]
	v_mfma_f32_16x16x32_bf16 v[108:111], v[208:211], v[160:163], v[108:111]
	v_mfma_f32_16x16x32_bf16 v[100:103], v[200:203], v[176:179], v[100:103]
	v_mfma_f32_16x16x32_bf16 v[96:99], v[208:211], v[176:179], v[96:99]
	v_mfma_f32_16x16x32_bf16 v[84:87], v[200:203], v[184:187], v[84:87]
	v_mfma_f32_16x16x32_bf16 v[80:83], v[208:211], v[184:187], v[80:83]
	v_mfma_f32_16x16x32_bf16 v[68:71], v[200:203], v[192:195], v[68:71]
	v_mfma_f32_16x16x32_bf16 v[64:67], v[208:211], v[192:195], v[64:67]
	s_mov_b32 m0, s54
	s_barrier
	ds_read_b128 v[156:159], v170 offset:49152
	ds_read_b128 v[160:163], v170 offset:50176
	ds_read_b128 v[172:175], v170 offset:51200
	ds_read_b128 v[176:179], v170 offset:52224
	ds_read_b128 v[180:183], v170 offset:53248
	ds_read_b128 v[184:187], v170 offset:54272
	ds_read_b128 v[188:191], v170 offset:55296
	ds_read_b128 v[192:195], v170 offset:56320
	global_load_lds_dwordx4 v146, s[100:101]
	s_mov_b32 m0, s55
	s_nop 0
	global_load_lds_dwordx4 v148, s[100:101]
	s_barrier
	s_waitcnt lgkmcnt(0)
	v_mfma_f32_16x16x32_bf16 v[60:63], v[128:131], v[156:159], v[60:63]
	v_mfma_f32_16x16x32_bf16 v[56:59], v[136:139], v[156:159], v[56:59]
	v_mfma_f32_16x16x32_bf16 v[44:47], v[128:131], v[172:175], v[44:47]
	v_mfma_f32_16x16x32_bf16 v[40:43], v[136:139], v[172:175], v[40:43]
	v_mfma_f32_16x16x32_bf16 v[36:39], v[128:131], v[180:183], v[36:39]
	v_mfma_f32_16x16x32_bf16 v[28:31], v[136:139], v[180:183], v[28:31]
	v_mfma_f32_16x16x32_bf16 v[20:23], v[128:131], v[188:191], v[20:23]
	v_mfma_f32_16x16x32_bf16 v[12:15], v[136:139], v[188:191], v[12:15]
	v_mfma_f32_16x16x32_bf16 v[60:63], v[132:135], v[160:163], v[60:63]
	v_mfma_f32_16x16x32_bf16 v[56:59], v[140:143], v[160:163], v[56:59]
	v_mfma_f32_16x16x32_bf16 v[44:47], v[132:135], v[176:179], v[44:47]
	v_mfma_f32_16x16x32_bf16 v[40:43], v[140:143], v[176:179], v[40:43]
	v_mfma_f32_16x16x32_bf16 v[36:39], v[132:135], v[184:187], v[36:39]
	v_mfma_f32_16x16x32_bf16 v[28:31], v[140:143], v[184:187], v[28:31]
	v_mfma_f32_16x16x32_bf16 v[20:23], v[132:135], v[192:195], v[20:23]
	v_mfma_f32_16x16x32_bf16 v[12:15], v[140:143], v[192:195], v[12:15]
	s_barrier
	s_add_u32 s38, s38, 0x160080
	s_addc_u32 s39, s39, 0
	s_add_i32 s40, s40, s46
	s_mov_b32 m0, s40
	s_nop 0
	global_load_lds_dwordx4 v146, s[38:39]
	s_add_i32 m0, s40, 0x2000
	s_nop 0
	global_load_lds_dwordx4 v148, s[38:39]
	s_waitcnt vmcnt(6)
	s_barrier
	v_mfma_f32_16x16x32_bf16 v[52:55], v[196:199], v[156:159], v[52:55]
	v_mfma_f32_16x16x32_bf16 v[48:51], v[204:207], v[156:159], v[48:51]
	v_mfma_f32_16x16x32_bf16 v[32:35], v[196:199], v[172:175], v[32:35]
	v_mfma_f32_16x16x32_bf16 v[24:27], v[204:207], v[172:175], v[24:27]
	v_mfma_f32_16x16x32_bf16 v[16:19], v[196:199], v[180:183], v[16:19]
	v_mfma_f32_16x16x32_bf16 v[8:11], v[204:207], v[180:183], v[8:11]
	v_mfma_f32_16x16x32_bf16 v[4:7], v[196:199], v[188:191], v[4:7]
	v_mfma_f32_16x16x32_bf16 v[0:3], v[204:207], v[188:191], v[0:3]
	v_mfma_f32_16x16x32_bf16 v[52:55], v[200:203], v[160:163], v[52:55]
	v_mfma_f32_16x16x32_bf16 v[48:51], v[208:211], v[160:163], v[48:51]
	v_mfma_f32_16x16x32_bf16 v[32:35], v[200:203], v[176:179], v[32:35]
	v_mfma_f32_16x16x32_bf16 v[24:27], v[208:211], v[176:179], v[24:27]
	v_mfma_f32_16x16x32_bf16 v[16:19], v[200:203], v[184:187], v[16:19]
	v_mfma_f32_16x16x32_bf16 v[8:11], v[208:211], v[184:187], v[8:11]
	v_mfma_f32_16x16x32_bf16 v[4:7], v[200:203], v[192:195], v[4:7]
	v_mfma_f32_16x16x32_bf16 v[0:3], v[208:211], v[192:195], v[0:3]
	s_add_i32 s68, s68, 2
	s_add_u32 s36, s36, 0x100
	s_addc_u32 s37, s37, 0
	s_add_u32 s28, s28, 0x100
	s_addc_u32 s29, s29, 0
	s_cmpk_gt_u32 s68, 0x55
	s_barrier
	s_cbranch_scc0 .LBB0_1285
	v_lshl_add_u32 v164, s66, 8, v166
	v_lshl_or_b32 v128, s67, 8, v168
	v_ashrrev_i32_e32 v165, 31, v164
	s_ashr_i32 s28, s66, 3
	v_ashrrev_i32_e32 v129, 31, v128
	v_lshlrev_b64 v[130:131], 12, v[164:165]
	s_mul_hi_i32 s29, s28, 0xc000
	s_mul_i32 s28, s28, 0xc000
	v_lshl_add_u64 v[130:131], s[8:9], 0, v[130:131]
	v_lshlrev_b64 v[158:159], 1, v[128:129]
	s_add_u32 s28, s52, s28
	v_lshl_add_u64 v[156:157], v[130:131], 0, v[158:159]
	v_or_b32_e32 v130, 16, v164
	s_addc_u32 s29, s53, s29
	v_lshl_add_u64 v[128:129], v[128:129], 2, s[28:29]
	v_ashrrev_i32_e32 v131, 31, v130
	global_load_dwordx2 v[162:163], v[156:157], off
	global_load_dwordx2 v[172:173], v[156:157], off offset:32
	global_load_dwordx2 v[174:175], v[156:157], off offset:256
	global_load_dwordx4 v[132:135], v[128:129], off offset:512
	global_load_dwordx2 v[176:177], v[156:157], off offset:288
	global_load_dwordx4 v[140:143], v[128:129], off
	global_load_dwordx4 v[136:139], v[128:129], off offset:64
	v_lshlrev_b64 v[130:131], 12, v[130:131]
	v_lshl_add_u64 v[160:161], s[8:9], 0, v[130:131]
	global_load_dwordx4 v[128:131], v[128:129], off offset:576
	v_lshl_add_u64 v[160:161], v[160:161], 0, v[158:159]
	global_load_dwordx2 v[178:179], v[160:161], off
	global_load_dwordx2 v[180:181], v[160:161], off offset:32
	global_load_dwordx2 v[182:183], v[160:161], off offset:256
	global_load_dwordx2 v[186:187], v[160:161], off offset:288
	v_or_b32_e32 v184, 32, v164
	v_or_b32_e32 v164, 48, v164
	v_ashrrev_i32_e32 v185, 31, v184
	v_ashrrev_i32_e32 v165, 31, v164
	v_lshlrev_b64 v[184:185], 12, v[184:185]
	v_lshlrev_b64 v[164:165], 12, v[164:165]
	v_lshl_add_u64 v[184:185], s[8:9], 0, v[184:185]
	v_lshl_add_u64 v[164:165], s[8:9], 0, v[164:165]
	v_lshl_add_u64 v[184:185], v[184:185], 0, v[158:159]
	v_lshl_add_u64 v[158:159], v[164:165], 0, v[158:159]
	global_load_dwordx2 v[164:165], v[184:185], off
	global_load_dwordx2 v[188:189], v[184:185], off offset:32
	global_load_dwordx2 v[190:191], v[184:185], off offset:256
	global_load_dwordx2 v[192:193], v[184:185], off offset:288
	global_load_dwordx2 v[194:195], v[158:159], off
	s_mov_b32 s67, s64
	s_mov_b32 s66, s65
	s_mov_b64 s[38:39], s[0:1]
	s_mov_b64 s[36:37], s[34:35]
	s_waitcnt vmcnt(0)
	v_lshlrev_b32_e32 v196, 16, v162
	v_and_b32_e32 v197, 0xffff0000, v162
	v_lshlrev_b32_e32 v162, 16, v163
	v_and_b32_e32 v163, 0xffff0000, v163
	v_lshlrev_b32_e32 v198, 16, v172
	v_and_b32_e32 v199, 0xffff0000, v172
	v_lshlrev_b32_e32 v172, 16, v173
	v_and_b32_e32 v173, 0xffff0000, v173
	v_lshlrev_b32_e32 v200, 16, v174
	v_and_b32_e32 v201, 0xffff0000, v174
	v_lshlrev_b32_e32 v174, 16, v175
	v_and_b32_e32 v175, 0xffff0000, v175
	v_lshlrev_b32_e32 v202, 16, v176
	v_and_b32_e32 v203, 0xffff0000, v176
	v_lshlrev_b32_e32 v176, 16, v177
	v_and_b32_e32 v177, 0xffff0000, v177
	v_pk_fma_f32 v[126:127], v[126:127], v[142:143], v[162:163]
	v_pk_fma_f32 v[124:125], v[124:125], v[140:141], v[196:197]
	v_pk_fma_f32 v[122:123], v[122:123], v[138:139], v[172:173]
	v_pk_fma_f32 v[120:121], v[120:121], v[136:137], v[198:199]
	v_pk_fma_f32 v[114:115], v[114:115], v[134:135], v[174:175]
	v_pk_fma_f32 v[112:113], v[112:113], v[132:133], v[200:201]
	v_pk_fma_f32 v[110:111], v[110:111], v[130:131], v[176:177]
	v_pk_fma_f32 v[108:109], v[108:109], v[128:129], v[202:203]
	v_cvt_pk_bf16_f32 v124, v124, v125
	v_cvt_pk_bf16_f32 v125, v126, v127
	v_cvt_pk_bf16_f32 v120, v120, v121
	v_cvt_pk_bf16_f32 v121, v122, v123
	v_cvt_pk_bf16_f32 v112, v112, v113
	v_cvt_pk_bf16_f32 v113, v114, v115
	v_cvt_pk_bf16_f32 v108, v108, v109
	v_cvt_pk_bf16_f32 v109, v110, v111
	global_store_dwordx2 v[156:157], v[124:125], off
	global_store_dwordx2 v[156:157], v[120:121], off offset:32
	global_store_dwordx2 v[156:157], v[112:113], off offset:256
	global_store_dwordx2 v[156:157], v[108:109], off offset:288
	global_load_dwordx2 v[112:113], v[158:159], off offset:32
	v_lshlrev_b32_e32 v162, 16, v178
	v_and_b32_e32 v163, 0xffff0000, v178
	v_lshlrev_b32_e32 v172, 16, v179
	v_and_b32_e32 v173, 0xffff0000, v179
	v_pk_fma_f32 v[110:111], v[118:119], v[142:143], v[172:173]
	v_pk_fma_f32 v[114:115], v[116:117], v[140:141], v[162:163]
	v_cvt_pk_bf16_f32 v109, v110, v111
	v_cvt_pk_bf16_f32 v108, v114, v115
	global_store_dwordx2 v[160:161], v[108:109], off
	v_lshlrev_b32_e32 v108, 16, v180
	v_and_b32_e32 v109, 0xffff0000, v180
	v_lshlrev_b32_e32 v110, 16, v181
	v_and_b32_e32 v111, 0xffff0000, v181
	v_pk_fma_f32 v[106:107], v[106:107], v[138:139], v[110:111]
	v_pk_fma_f32 v[104:105], v[104:105], v[136:137], v[108:109]
	s_nop 0
	v_cvt_pk_bf16_f32 v104, v104, v105
	v_cvt_pk_bf16_f32 v105, v106, v107
	global_store_dwordx2 v[160:161], v[104:105], off offset:32
	v_lshlrev_b32_e32 v104, 16, v182
	v_and_b32_e32 v105, 0xffff0000, v182
	v_lshlrev_b32_e32 v106, 16, v183
	v_and_b32_e32 v107, 0xffff0000, v183
	v_pk_fma_f32 v[102:103], v[102:103], v[134:135], v[106:107]
	v_pk_fma_f32 v[100:101], v[100:101], v[132:133], v[104:105]
	v_lshlrev_b32_e32 v104, 16, v187
	v_cvt_pk_bf16_f32 v100, v100, v101
	v_cvt_pk_bf16_f32 v101, v102, v103
	global_load_dwordx2 v[102:103], v[158:159], off offset:256
	v_and_b32_e32 v105, 0xffff0000, v187
	global_store_dwordx2 v[160:161], v[100:101], off offset:256
	v_lshlrev_b32_e32 v100, 16, v186
	v_and_b32_e32 v101, 0xffff0000, v186
	v_pk_fma_f32 v[98:99], v[98:99], v[130:131], v[104:105]
	v_pk_fma_f32 v[96:97], v[96:97], v[128:129], v[100:101]
	v_lshlrev_b32_e32 v100, 16, v165
	v_cvt_pk_bf16_f32 v96, v96, v97
	v_cvt_pk_bf16_f32 v97, v98, v99
	global_store_dwordx2 v[160:161], v[96:97], off offset:288
	global_load_dwordx2 v[96:97], v[158:159], off offset:288
	v_and_b32_e32 v101, 0xffff0000, v165
	v_pk_fma_f32 v[94:95], v[94:95], v[142:143], v[100:101]
	v_add_co_u32_e32 v100, vcc, s60, v156
	v_lshlrev_b32_e32 v98, 16, v164
	v_and_b32_e32 v99, 0xffff0000, v164
	v_addc_co_u32_e32 v101, vcc, 0, v157, vcc
	global_load_dwordx2 v[104:105], v[100:101], off
	v_pk_fma_f32 v[92:93], v[92:93], v[140:141], v[98:99]
	s_nop 0
	v_cvt_pk_bf16_f32 v92, v92, v93
	v_cvt_pk_bf16_f32 v93, v94, v95
	global_store_dwordx2 v[184:185], v[92:93], off
	v_lshlrev_b32_e32 v92, 16, v188
	v_and_b32_e32 v93, 0xffff0000, v188
	v_lshlrev_b32_e32 v94, 16, v189
	v_and_b32_e32 v95, 0xffff0000, v189
	v_pk_fma_f32 v[90:91], v[90:91], v[138:139], v[94:95]
	v_pk_fma_f32 v[88:89], v[88:89], v[136:137], v[92:93]
	v_lshlrev_b32_e32 v92, 16, v190
	v_cvt_pk_bf16_f32 v88, v88, v89
	v_cvt_pk_bf16_f32 v89, v90, v91
	global_store_dwordx2 v[184:185], v[88:89], off offset:32
	v_lshl_add_u64 v[88:89], v[156:157], 0, s[12:13]
	global_load_dwordx2 v[90:91], v[88:89], off offset:32
	v_and_b32_e32 v93, 0xffff0000, v190
	v_lshlrev_b32_e32 v94, 16, v191
	v_and_b32_e32 v95, 0xffff0000, v191
	v_pk_fma_f32 v[86:87], v[86:87], v[134:135], v[94:95]
	v_pk_fma_f32 v[84:85], v[84:85], v[132:133], v[92:93]
	v_lshlrev_b32_e32 v92, 16, v193
	v_cvt_pk_bf16_f32 v84, v84, v85
	v_cvt_pk_bf16_f32 v85, v86, v87
	global_load_dwordx2 v[86:87], v[88:89], off offset:256
	v_and_b32_e32 v93, 0xffff0000, v193
	global_store_dwordx2 v[184:185], v[84:85], off offset:256
	v_lshlrev_b32_e32 v84, 16, v192
	v_and_b32_e32 v85, 0xffff0000, v192
	v_pk_fma_f32 v[82:83], v[82:83], v[130:131], v[92:93]
	v_pk_fma_f32 v[80:81], v[80:81], v[128:129], v[84:85]
	v_lshlrev_b32_e32 v84, 16, v195
	v_cvt_pk_bf16_f32 v80, v80, v81
	v_cvt_pk_bf16_f32 v81, v82, v83
	global_load_dwordx2 v[82:83], v[88:89], off offset:288
	v_and_b32_e32 v85, 0xffff0000, v195
	global_store_dwordx2 v[184:185], v[80:81], off offset:288
	v_lshlrev_b32_e32 v80, 16, v194
	v_and_b32_e32 v81, 0xffff0000, v194
	v_pk_fma_f32 v[78:79], v[78:79], v[142:143], v[84:85]
	v_pk_fma_f32 v[76:77], v[76:77], v[140:141], v[80:81]
	s_waitcnt vmcnt(0)
	v_lshlrev_b32_e32 v84, 16, v113
	v_cvt_pk_bf16_f32 v76, v76, v77
	v_cvt_pk_bf16_f32 v77, v78, v79
	v_add_co_u32_e32 v78, vcc, s61, v156
	global_store_dwordx2 v[158:159], v[76:77], off
	v_lshlrev_b32_e32 v76, 16, v112
	v_and_b32_e32 v77, 0xffff0000, v112
	v_addc_co_u32_e32 v79, vcc, 0, v157, vcc
	v_and_b32_e32 v85, 0xffff0000, v113
	global_load_dwordx2 v[80:81], v[78:79], off
	v_pk_fma_f32 v[74:75], v[74:75], v[138:139], v[84:85]
	v_pk_fma_f32 v[72:73], v[72:73], v[136:137], v[76:77]
	v_lshlrev_b32_e32 v84, 16, v103
	v_cvt_pk_bf16_f32 v72, v72, v73
	v_cvt_pk_bf16_f32 v73, v74, v75
	global_store_dwordx2 v[158:159], v[72:73], off offset:32
	v_lshl_add_u64 v[72:73], v[156:157], 0, s[14:15]
	global_load_dwordx2 v[76:77], v[72:73], off offset:32
	v_lshlrev_b32_e32 v74, 16, v102
	v_and_b32_e32 v75, 0xffff0000, v102
	v_and_b32_e32 v85, 0xffff0000, v103
	v_pk_fma_f32 v[70:71], v[70:71], v[134:135], v[84:85]
	v_pk_fma_f32 v[68:69], v[68:69], v[132:133], v[74:75]
	v_lshlrev_b32_e32 v74, 16, v97
	v_cvt_pk_bf16_f32 v68, v68, v69
	v_cvt_pk_bf16_f32 v69, v70, v71
	global_store_dwordx2 v[158:159], v[68:69], off offset:256
	v_lshlrev_b32_e32 v68, 16, v96
	v_and_b32_e32 v69, 0xffff0000, v96
	global_load_dwordx2 v[70:71], v[72:73], off offset:256
	v_and_b32_e32 v75, 0xffff0000, v97
	v_pk_fma_f32 v[66:67], v[66:67], v[130:131], v[74:75]
	v_pk_fma_f32 v[64:65], v[64:65], v[128:129], v[68:69]
	v_lshlrev_b32_e32 v68, 16, v105
	v_cvt_pk_bf16_f32 v64, v64, v65
	v_cvt_pk_bf16_f32 v65, v66, v67
	global_store_dwordx2 v[158:159], v[64:65], off offset:288
	v_lshlrev_b32_e32 v64, 16, v104
	v_and_b32_e32 v65, 0xffff0000, v104
	global_load_dwordx2 v[66:67], v[72:73], off offset:288
	v_pk_fma_f32 v[60:61], v[60:61], v[140:141], v[64:65]
	v_add_co_u32_e32 v64, vcc, s62, v156
	v_and_b32_e32 v69, 0xffff0000, v105
	s_nop 0
	v_addc_co_u32_e32 v65, vcc, 0, v157, vcc
	v_pk_fma_f32 v[62:63], v[62:63], v[142:143], v[68:69]
	global_load_dwordx2 v[68:69], v[64:65], off
	v_cvt_pk_bf16_f32 v60, v60, v61
	v_cvt_pk_bf16_f32 v61, v62, v63
	v_lshl_add_u64 v[74:75], v[156:157], 0, s[16:17]
	global_store_dwordx2 v[100:101], v[60:61], off
	v_lshlrev_b32_e32 v60, 16, v90
	v_and_b32_e32 v61, 0xffff0000, v90
	v_lshlrev_b32_e32 v62, 16, v91
	v_and_b32_e32 v63, 0xffff0000, v91
	global_load_dwordx2 v[84:85], v[74:75], off offset:32
	v_pk_fma_f32 v[58:59], v[58:59], v[138:139], v[62:63]
	v_pk_fma_f32 v[56:57], v[56:57], v[136:137], v[60:61]
	global_load_dwordx2 v[60:61], v[74:75], off offset:256
	v_cvt_pk_bf16_f32 v56, v56, v57
	v_cvt_pk_bf16_f32 v57, v58, v59
	global_store_dwordx2 v[88:89], v[56:57], off offset:32
	v_lshlrev_b32_e32 v56, 16, v86
	v_and_b32_e32 v57, 0xffff0000, v86
	v_lshlrev_b32_e32 v58, 16, v87
	v_and_b32_e32 v59, 0xffff0000, v87
	v_pk_fma_f32 v[54:55], v[54:55], v[134:135], v[58:59]
	v_pk_fma_f32 v[52:53], v[52:53], v[132:133], v[56:57]
	v_lshlrev_b32_e32 v56, 16, v83
	v_cvt_pk_bf16_f32 v52, v52, v53
	v_cvt_pk_bf16_f32 v53, v54, v55
	global_store_dwordx2 v[88:89], v[52:53], off offset:256
	v_lshlrev_b32_e32 v52, 16, v82
	v_and_b32_e32 v53, 0xffff0000, v82
	global_load_dwordx2 v[54:55], v[74:75], off offset:288
	v_pk_fma_f32 v[48:49], v[48:49], v[128:129], v[52:53]
	v_add_co_u32_e32 v52, vcc, s63, v156
	v_and_b32_e32 v57, 0xffff0000, v83
	s_nop 0
	v_addc_co_u32_e32 v53, vcc, 0, v157, vcc
	v_pk_fma_f32 v[50:51], v[50:51], v[130:131], v[56:57]
	global_load_dwordx2 v[56:57], v[52:53], off
	v_lshl_add_u64 v[58:59], v[156:157], 0, s[18:19]
	v_cvt_pk_bf16_f32 v48, v48, v49
	v_cvt_pk_bf16_f32 v49, v50, v51
	global_load_dwordx2 v[62:63], v[58:59], off offset:32
	s_waitcnt vmcnt(0)
	v_lshlrev_b32_e32 v50, 16, v81
	global_store_dwordx2 v[88:89], v[48:49], off offset:288
	v_lshlrev_b32_e32 v48, 16, v80
	v_and_b32_e32 v49, 0xffff0000, v80
	v_and_b32_e32 v51, 0xffff0000, v81
	v_pk_fma_f32 v[46:47], v[46:47], v[142:143], v[50:51]
	v_pk_fma_f32 v[44:45], v[44:45], v[140:141], v[48:49]
	global_load_dwordx2 v[48:49], v[58:59], off offset:256
	v_cvt_pk_bf16_f32 v44, v44, v45
	v_cvt_pk_bf16_f32 v45, v46, v47
	global_store_dwordx2 v[78:79], v[44:45], off
	v_lshlrev_b32_e32 v44, 16, v76
	v_and_b32_e32 v45, 0xffff0000, v76
	v_lshlrev_b32_e32 v46, 16, v77
	v_and_b32_e32 v47, 0xffff0000, v77
	v_pk_fma_f32 v[42:43], v[42:43], v[138:139], v[46:47]
	v_pk_fma_f32 v[40:41], v[40:41], v[136:137], v[44:45]
	s_and_b64 vcc, exec, s[30:31]
	v_cvt_pk_bf16_f32 v40, v40, v41
	v_cvt_pk_bf16_f32 v41, v42, v43
	global_load_dwordx2 v[42:43], v[58:59], off offset:288
	v_lshlrev_b32_e32 v44, 16, v71
	global_store_dwordx2 v[72:73], v[40:41], off offset:32
	v_lshlrev_b32_e32 v40, 16, v70
	v_and_b32_e32 v41, 0xffff0000, v70
	v_and_b32_e32 v45, 0xffff0000, v71
	v_pk_fma_f32 v[34:35], v[34:35], v[134:135], v[44:45]
	v_pk_fma_f32 v[32:33], v[32:33], v[132:133], v[40:41]
	s_nop 0
	v_cvt_pk_bf16_f32 v32, v32, v33
	v_cvt_pk_bf16_f32 v33, v34, v35
	global_store_dwordx2 v[72:73], v[32:33], off offset:256
	v_lshlrev_b32_e32 v32, 16, v66
	v_and_b32_e32 v33, 0xffff0000, v66
	v_lshlrev_b32_e32 v34, 16, v67
	v_and_b32_e32 v35, 0xffff0000, v67
	v_pk_fma_f32 v[26:27], v[26:27], v[130:131], v[34:35]
	v_pk_fma_f32 v[24:25], v[24:25], v[128:129], v[32:33]
	s_nop 0
	v_cvt_pk_bf16_f32 v24, v24, v25
	v_cvt_pk_bf16_f32 v25, v26, v27
	global_store_dwordx2 v[72:73], v[24:25], off offset:288
	v_lshlrev_b32_e32 v24, 16, v68
	v_and_b32_e32 v25, 0xffff0000, v68
	v_lshlrev_b32_e32 v26, 16, v69
	v_and_b32_e32 v27, 0xffff0000, v69
	v_pk_fma_f32 v[26:27], v[38:39], v[142:143], v[26:27]
	v_pk_fma_f32 v[24:25], v[36:37], v[140:141], v[24:25]
	s_nop 0
	v_cvt_pk_bf16_f32 v24, v24, v25
	v_cvt_pk_bf16_f32 v25, v26, v27
	global_store_dwordx2 v[64:65], v[24:25], off
	v_lshlrev_b32_e32 v24, 16, v84
	v_and_b32_e32 v25, 0xffff0000, v84
	v_lshlrev_b32_e32 v26, 16, v85
	v_and_b32_e32 v27, 0xffff0000, v85
	v_pk_fma_f32 v[26:27], v[30:31], v[138:139], v[26:27]
	v_pk_fma_f32 v[24:25], v[28:29], v[136:137], v[24:25]
	s_nop 0
	v_cvt_pk_bf16_f32 v24, v24, v25
	v_cvt_pk_bf16_f32 v25, v26, v27
	global_store_dwordx2 v[74:75], v[24:25], off offset:32
	v_lshlrev_b32_e32 v24, 16, v60
	v_and_b32_e32 v25, 0xffff0000, v60
	v_lshlrev_b32_e32 v26, 16, v61
	v_and_b32_e32 v27, 0xffff0000, v61
	v_pk_fma_f32 v[18:19], v[18:19], v[134:135], v[26:27]
	v_pk_fma_f32 v[16:17], v[16:17], v[132:133], v[24:25]
	s_nop 0
	v_cvt_pk_bf16_f32 v16, v16, v17
	v_cvt_pk_bf16_f32 v17, v18, v19
	global_store_dwordx2 v[74:75], v[16:17], off offset:256
	v_lshlrev_b32_e32 v16, 16, v54
	v_and_b32_e32 v17, 0xffff0000, v54
	v_lshlrev_b32_e32 v18, 16, v55
	v_and_b32_e32 v19, 0xffff0000, v55
	v_pk_fma_f32 v[10:11], v[10:11], v[130:131], v[18:19]
	v_pk_fma_f32 v[8:9], v[8:9], v[128:129], v[16:17]
	s_nop 0
	v_cvt_pk_bf16_f32 v8, v8, v9
	v_cvt_pk_bf16_f32 v9, v10, v11
	global_store_dwordx2 v[74:75], v[8:9], off offset:288
	v_lshlrev_b32_e32 v8, 16, v56
	v_and_b32_e32 v9, 0xffff0000, v56
	v_lshlrev_b32_e32 v10, 16, v57
	v_and_b32_e32 v11, 0xffff0000, v57
	v_pk_fma_f32 v[10:11], v[22:23], v[142:143], v[10:11]
	v_pk_fma_f32 v[8:9], v[20:21], v[140:141], v[8:9]
	s_nop 0
	v_cvt_pk_bf16_f32 v8, v8, v9
	v_cvt_pk_bf16_f32 v9, v10, v11
	global_store_dwordx2 v[52:53], v[8:9], off
	v_lshlrev_b32_e32 v8, 16, v62
	v_and_b32_e32 v9, 0xffff0000, v62
	v_lshlrev_b32_e32 v10, 16, v63
	v_and_b32_e32 v11, 0xffff0000, v63
	v_pk_fma_f32 v[10:11], v[14:15], v[138:139], v[10:11]
	v_pk_fma_f32 v[8:9], v[12:13], v[136:137], v[8:9]
	s_nop 0
	v_cvt_pk_bf16_f32 v8, v8, v9
	v_cvt_pk_bf16_f32 v9, v10, v11
	global_store_dwordx2 v[58:59], v[8:9], off offset:32
	s_waitcnt vmcnt(0)
	v_lshlrev_b32_e32 v8, 16, v48
	v_and_b32_e32 v9, 0xffff0000, v48
	v_lshlrev_b32_e32 v10, 16, v49
	v_and_b32_e32 v11, 0xffff0000, v49
	v_pk_fma_f32 v[6:7], v[6:7], v[134:135], v[10:11]
	v_pk_fma_f32 v[4:5], v[4:5], v[132:133], v[8:9]
	s_nop 0
	v_cvt_pk_bf16_f32 v4, v4, v5
	v_cvt_pk_bf16_f32 v5, v6, v7
	global_store_dwordx2 v[58:59], v[4:5], off offset:256
	v_lshlrev_b32_e32 v4, 16, v42
	v_and_b32_e32 v5, 0xffff0000, v42
	v_lshlrev_b32_e32 v6, 16, v43
	v_and_b32_e32 v7, 0xffff0000, v43
	v_pk_fma_f32 v[2:3], v[2:3], v[130:131], v[6:7]
	v_pk_fma_f32 v[0:1], v[0:1], v[128:129], v[4:5]
	s_nop 0
	v_cvt_pk_bf16_f32 v0, v0, v1
	v_cvt_pk_bf16_f32 v1, v2, v3
	global_store_dwordx2 v[58:59], v[0:1], off offset:288
	s_cbranch_vccz .LBB0_1272
	s_branch .LBB0_1288

	.amdhsa_kernel _Z4mega6Params
		.amdhsa_group_segment_fixed_size 0
		.amdhsa_private_segment_fixed_size 0
		.amdhsa_kernarg_size 568
		.amdhsa_user_sgpr_count 2
		.amdhsa_user_sgpr_dispatch_ptr 0
		.amdhsa_user_sgpr_queue_ptr 0
		.amdhsa_user_sgpr_kernarg_segment_ptr 1
		.amdhsa_user_sgpr_dispatch_id 0
		.amdhsa_user_sgpr_kernarg_preload_length 0
		.amdhsa_user_sgpr_kernarg_preload_offset 0
		.amdhsa_user_sgpr_private_segment_size 0
		.amdhsa_uses_dynamic_stack 0
		.amdhsa_enable_private_segment 0
		.amdhsa_system_sgpr_workgroup_id_x 1
		.amdhsa_system_sgpr_workgroup_id_y 0
		.amdhsa_system_sgpr_workgroup_id_z 0
		.amdhsa_system_sgpr_workgroup_info 0
		.amdhsa_system_vgpr_workitem_id 2
		.amdhsa_next_free_vgpr 249
		.amdhsa_next_free_sgpr 102
		.amdhsa_accum_offset 252
		.amdhsa_reserve_vcc 1
		.amdhsa_float_round_mode_32 0
		.amdhsa_float_round_mode_16_64 0
		.amdhsa_float_denorm_mode_32 3
		.amdhsa_float_denorm_mode_16_64 3
		.amdhsa_dx10_clamp 1
		.amdhsa_ieee_mode 1
		.amdhsa_fp16_overflow 0
		.amdhsa_tg_split 0
		.amdhsa_exception_fp_ieee_invalid_op 0
		.amdhsa_exception_fp_denorm_src 0
		.amdhsa_exception_fp_ieee_div_zero 0
		.amdhsa_exception_fp_ieee_overflow 0
		.amdhsa_exception_fp_ieee_underflow 0
		.amdhsa_exception_fp_ieee_inexact 0
		.amdhsa_exception_int_div_zero 0
	.end_amdhsa_kernel

amdhsa.kernels:
  - .agpr_count:     0
    .args:
      - .offset:         0
        .size:           312
        .value_kind:     by_value
      - .offset:         312
        .size:           4
        .value_kind:     hidden_block_count_x
      - .offset:         316
        .size:           4
        .value_kind:     hidden_block_count_y
      - .offset:         320
        .size:           4
        .value_kind:     hidden_block_count_z
      - .offset:         324
        .size:           2
        .value_kind:     hidden_group_size_x
      - .offset:         326
        .size:           2
        .value_kind:     hidden_group_size_y
      - .offset:         328
        .size:           2
        .value_kind:     hidden_group_size_z
      - .offset:         330
        .size:           2
        .value_kind:     hidden_remainder_x
      - .offset:         332
        .size:           2
        .value_kind:     hidden_remainder_y
      - .offset:         334
        .size:           2
        .value_kind:     hidden_remainder_z
      - .offset:         352
        .size:           8
        .value_kind:     hidden_global_offset_x
      - .offset:         360
        .size:           8
        .value_kind:     hidden_global_offset_y
      - .offset:         368
        .size:           8
        .value_kind:     hidden_global_offset_z
      - .offset:         376
        .size:           2
        .value_kind:     hidden_grid_dims
      - .offset:         400
        .size:           8
        .value_kind:     hidden_multigrid_sync_arg
      - .offset:         432
        .size:           4
        .value_kind:     hidden_dynamic_lds_size
    .group_segment_fixed_size: 0
    .kernarg_segment_align: 8
    .kernarg_segment_size: 568
    .language:       OpenCL C
    .language_version:
      - 2
      - 0
    .max_flat_workgroup_size: 512
    .name:           _Z4mega6Params
    .private_segment_fixed_size: 0
    .sgpr_count:     108
    .sgpr_spill_count: 50
    .symbol:         _Z4mega6Params.kd
    .uniform_work_group_size: 1
    .uses_dynamic_stack: false
    .vgpr_count:     249
    .vgpr_spill_count: 0
    .wavefront_size: 64
